# back-edge rotation (7.11), rotated SALU woven behind the last matrix segment's MFMAs instead of after them (four peeled GEMM K-loops)
# speedup vs baseline: 1.0119x; 1.0119x over previous
; #define PG8_STAGE(bufoff, gbase, voff) do { _Pragma("unroll") for (int _i = 0; _i < 2; ++_i) \
;         __builtin_amdgcn_global_load_lds((const unsigned*)((const char*)(gbase) + (voff)[_i]), (PG8_LAS unsigned*)(lds + (bufoff) + ldsw + _i * 8192), 16, 0, 0); } while (0)
; #define PG8_LDA(dst, b, h) do { _Pragma("unroll") for (int m = 0; m < 4; ++m) _Pragma("unroll") for (int k = 0; k < 2; ++k) dst[m][k] = *(const PG8_LAS bf16x8*)(lds + PG8_SA(b, h) + aoff + m * 2048 + k * 1024); } while (0)
; #define PG8_LDB(dst, b, h) do { _Pragma("unroll") for (int n = 0; n < 2; ++n) _Pragma("unroll") for (int k = 0; k < 2; ++k) dst[n][k] = *(const PG8_LAS bf16x8*)(lds + PG8_SB(b, h) + boff + n * 2048 + k * 1024); } while (0)
; #define PG8_WAIT_V(n) asm volatile("s_waitcnt vmcnt(" #n ")" ::: "memory")
; #define PG8_WAIT_L(n) asm volatile("s_waitcnt lgkmcnt(" #n ")" ::: "memory")
; #define PG8_BAR __builtin_amdgcn_s_barrier()
; #define PG8_SCHED __builtin_amdgcn_sched_barrier(0)
; template <class Epi, class Sched, bool ALIGN_EPI = false, bool SP2 = false>
; __device__ __forceinline__ void gemm_phase(PG8_LAS unsigned char* lds, const Gemm g, const Sched& S, const Epi& E) {
;     ...
;     for (;;) {
;         const bool has_next = S.next(ui + 1, nxt);
;         const char* nA = has_next ? (const char*)g.A + (size_t)nxt.pm * tstepA + (size_t)nxt.pn * pnoffA : cA; const char* nB = has_next ? (const char*)g.Bt + (size_t)nxt.pn * tstepB : cB;
;         for (int t = 0; t < nt; t += 2) {
;             const bool last = (t == nt - 2);
;             const char* a1 = cA + (size_t)(t + 1) * kstepA;
;             const char* a2 = last ? nA : cA + (size_t)(t + 2) * kstepA; const char* b2 = last ? nB : cB + (size_t)(t + 2) * kstep;
;             const char* a3 = a2 + kstepA; const char* b3 = b2 + kstep;
;             if (last && has_next) S.a_ready(nxt);
;             if constexpr (SP2) {
;             PG8_LDB(B0, 0, 0); PG8_LDB(B1, 0, 1); PG8_SCHED; PG8_LDA(At, 0, 0); PG8_STAGE(PG8_SA(1, 1), a1 + hstepA, voffA);
;             PG8_WAIT_V(8); PG8_WAIT_L(0); PG8_BAR; PG8_MMA(0, 0, At, B0); PG8_MMA(0, 1, At, B1); PG8_BAR; PG8_SCHED;
;             PG8_LDA(At, 0, 1); PG8_STAGE(PG8_SB(0, 0), b2, voffB); PG8_STAGE(PG8_SB(0, 1), b2 + hstepB, voffB); PG8_STAGE(PG8_SA(0, 0), a2, voffA);
;             PG8_WAIT_V(8); PG8_WAIT_L(0); PG8_BAR; PG8_MMA(1, 0, At, B0); PG8_MMA(1, 1, At, B1); PG8_BAR; PG8_SCHED;
.LBB0_34:
	s_ashr_i32 s11, s10, 31
	s_lshl_b64 s[14:15], s[10:11], 15
	s_add_u32 s14, s70, s14
	s_addc_u32 s15, s71, s15
	s_and_b64 s[0:1], s[0:1], exec
	s_cselect_b32 s11, s15, s19
	s_cselect_b32 s36, s14, s18
	s_add_u32 s0, s18, 0x404000
	s_addc_u32 s1, s19, 0
	s_add_u32 s37, s16, 0x100
	s_addc_u32 s38, s17, 0
	s_mov_b32 s39, -2
	s_add_u32 s16, s0, 0x3fc000
	s_addc_u32 s17, s1, 0
	s_cmp_eq_u32 s39, 40
	s_cselect_b32 s20, s36, s16
	s_cselect_b32 s21, s11, s17
	s_cselect_b32 s18, s12, s37
	s_cselect_b32 s19, s13, s38
	s_add_u32 s16, s20, 0x400000
	s_addc_u32 s17, s21, 0
	s_add_i32 s40, 0, 0x10000
	s_add_i32 s42, 0, 0x14000
	v_add_u32_e32 v156, s40, v153
	v_add_u32_e32 v172, s42, v153
	ds_read_b128 v[140:143], v156
	ds_read_b128 v[144:147], v156 offset:1024
	ds_read_b128 v[148:151], v156 offset:2048
	ds_read_b128 v[156:159], v156 offset:3072
	ds_read_b128 v[160:163], v172
	ds_read_b128 v[164:167], v172 offset:1024
	ds_read_b128 v[168:171], v172 offset:2048
	ds_read_b128 v[172:175], v172 offset:3072
	v_lshl_add_u64 v[192:193], s[0:1], 0, v[136:137]
	s_add_i32 m0, s23, 0xc000
	ds_read_b128 v[176:179], v155
	ds_read_b128 v[180:183], v155 offset:1024
	ds_read_b128 v[184:187], v155 offset:2048
	ds_read_b128 v[188:191], v155 offset:3072
	ds_read_b128 v[206:209], v155 offset:4096
	ds_read_b128 v[210:213], v155 offset:5120
	ds_read_b128 v[214:217], v155 offset:6144
	ds_read_b128 v[218:221], v155 offset:7168
	global_load_lds_dwordx4 v[192:193], off
	v_lshl_add_u64 v[192:193], s[0:1], 0, v[138:139]
	s_add_i32 m0, s23, 0xe000
	s_nop 0
	global_load_lds_dwordx4 v[192:193], off
	s_waitcnt vmcnt(8)
	s_waitcnt lgkmcnt(0)
	s_barrier
	s_setprio 1
	s_waitcnt lgkmcnt(0)
	v_mfma_f32_16x16x32_bf16 v[126:129], v[140:143], v[176:179], 0
	v_mfma_f32_16x16x32_bf16 v[122:125], v[148:151], v[176:179], 0
	v_mfma_f32_16x16x32_bf16 v[118:121], v[140:143], v[184:187], 0
	v_mfma_f32_16x16x32_bf16 v[114:117], v[148:151], v[184:187], 0
	v_mfma_f32_16x16x32_bf16 v[106:109], v[140:143], v[206:209], 0
	v_mfma_f32_16x16x32_bf16 v[98:101], v[148:151], v[206:209], 0
	v_mfma_f32_16x16x32_bf16 v[90:93], v[140:143], v[214:217], 0
	v_mfma_f32_16x16x32_bf16 v[82:85], v[148:151], v[214:217], 0
	v_mfma_f32_16x16x32_bf16 v[126:129], v[144:147], v[180:183], v[126:129]
	v_mfma_f32_16x16x32_bf16 v[122:125], v[156:159], v[180:183], v[122:125]
	v_mfma_f32_16x16x32_bf16 v[118:121], v[144:147], v[188:191], v[118:121]
	v_mfma_f32_16x16x32_bf16 v[114:117], v[156:159], v[188:191], v[114:117]
	v_mfma_f32_16x16x32_bf16 v[106:109], v[144:147], v[210:213], v[106:109]
	v_mfma_f32_16x16x32_bf16 v[98:101], v[156:159], v[210:213], v[98:101]
	v_mfma_f32_16x16x32_bf16 v[90:93], v[144:147], v[218:221], v[90:93]
	v_mfma_f32_16x16x32_bf16 v[82:85], v[156:159], v[218:221], v[82:85]
	s_setprio 0
	s_setprio 1
	v_mfma_f32_16x16x32_bf16 v[110:113], v[160:163], v[176:179], 0
	v_mfma_f32_16x16x32_bf16 v[102:105], v[168:171], v[176:179], 0
	v_mfma_f32_16x16x32_bf16 v[94:97], v[160:163], v[184:187], 0
	v_mfma_f32_16x16x32_bf16 v[86:89], v[168:171], v[184:187], 0
	v_mfma_f32_16x16x32_bf16 v[78:81], v[160:163], v[206:209], 0
	v_mfma_f32_16x16x32_bf16 v[74:77], v[168:171], v[206:209], 0
	v_mfma_f32_16x16x32_bf16 v[70:73], v[160:163], v[214:217], 0
	v_mfma_f32_16x16x32_bf16 v[66:69], v[168:171], v[214:217], 0
	v_mfma_f32_16x16x32_bf16 v[110:113], v[164:167], v[180:183], v[110:113]
	v_mfma_f32_16x16x32_bf16 v[102:105], v[172:175], v[180:183], v[102:105]
	v_mfma_f32_16x16x32_bf16 v[94:97], v[164:167], v[188:191], v[94:97]
	v_mfma_f32_16x16x32_bf16 v[86:89], v[172:175], v[188:191], v[86:89]
	v_mfma_f32_16x16x32_bf16 v[78:81], v[164:167], v[210:213], v[78:81]
	v_mfma_f32_16x16x32_bf16 v[74:77], v[172:175], v[210:213], v[74:77]
	v_mfma_f32_16x16x32_bf16 v[70:73], v[164:167], v[218:221], v[70:73]
	v_mfma_f32_16x16x32_bf16 v[66:69], v[172:175], v[218:221], v[66:69]
	s_setprio 0
	s_barrier
	s_add_i32 s40, s40, s22
	v_lshl_add_u64 v[192:193], s[18:19], 0, v[0:1]
	s_mov_b32 m0, s40
	ds_read_b128 v[176:179], v155 offset:16384
	ds_read_b128 v[180:183], v155 offset:17408
	ds_read_b128 v[184:187], v155 offset:18432
	ds_read_b128 v[188:191], v155 offset:19456
	ds_read_b128 v[206:209], v155 offset:20480
	ds_read_b128 v[210:213], v155 offset:21504
	ds_read_b128 v[214:217], v155 offset:22528
	ds_read_b128 v[218:221], v155 offset:23552
	global_load_lds_dwordx4 v[192:193], off
	s_add_i32 m0, s40, 0x2000
	s_add_u32 s40, s18, 0xb0000
	v_lshl_add_u64 v[222:223], s[18:19], 0, v[130:131]
	s_addc_u32 s41, s19, 0
	s_add_i32 s42, s42, s22
	global_load_lds_dwordx4 v[222:223], off
	v_lshl_add_u64 v[224:225], s[40:41], 0, v[0:1]
	s_mov_b32 m0, s42
	s_nop 0
	global_load_lds_dwordx4 v[224:225], off
	v_lshl_add_u64 v[224:225], s[40:41], 0, v[130:131]
	s_add_i32 m0, s42, 0x2000
	s_nop 0
	global_load_lds_dwordx4 v[224:225], off
	v_lshl_add_u64 v[224:225], s[20:21], 0, v[134:135]
	s_mov_b32 m0, s23
	s_nop 0
	global_load_lds_dwordx4 v[224:225], off
	v_lshl_add_u64 v[224:225], s[20:21], 0, v[132:133]
	s_mov_b32 m0, s25
	s_nop 0
	global_load_lds_dwordx4 v[224:225], off
	s_waitcnt vmcnt(8)
	s_waitcnt lgkmcnt(0)
	s_barrier
; #define PG8_STAGE(bufoff, gbase, voff) do { _Pragma("unroll") for (int _i = 0; _i < 2; ++_i) \
;         __builtin_amdgcn_global_load_lds((const unsigned*)((const char*)(gbase) + (voff)[_i]), (PG8_LAS unsigned*)(lds + (bufoff) + ldsw + _i * 8192), 16, 0, 0); } while (0)
; #define PG8_LDA(dst, b, h) do { _Pragma("unroll") for (int m = 0; m < 4; ++m) _Pragma("unroll") for (int k = 0; k < 2; ++k) dst[m][k] = *(const PG8_LAS bf16x8*)(lds + PG8_SA(b, h) + aoff + m * 2048 + k * 1024); } while (0)
; #define PG8_LDB(dst, b, h) do { _Pragma("unroll") for (int n = 0; n < 2; ++n) _Pragma("unroll") for (int k = 0; k < 2; ++k) dst[n][k] = *(const PG8_LAS bf16x8*)(lds + PG8_SB(b, h) + boff + n * 2048 + k * 1024); } while (0)
; #define PG8_MMA(ai, bj, At, Bt) do { __builtin_amdgcn_s_setprio(1); _Pragma("unroll") for (int m = 0; m < 4; ++m) _Pragma("unroll") for (int n = 0; n < 2; ++n) _Pragma("unroll") for (int k = 0; k < 2; ++k) \
;         acc[ai][bj][m][n] = __builtin_amdgcn_mfma_f32_16x16x32_bf16(Bt[n][k], At[m][k], acc[ai][bj][m][n], 0, 0, 0); __builtin_amdgcn_s_setprio(0); } while (0)
; #define PG8_WAIT_V(n) asm volatile("s_waitcnt vmcnt(" #n ")" ::: "memory")
; #define PG8_WAIT_L(n) asm volatile("s_waitcnt lgkmcnt(" #n ")" ::: "memory")
; #define PG8_BAR __builtin_amdgcn_s_barrier()
; #define PG8_SCHED __builtin_amdgcn_sched_barrier(0)
; template <class Epi, class Sched, bool ALIGN_EPI = false, bool SP2 = false>
; __device__ __forceinline__ void gemm_phase(PG8_LAS unsigned char* lds, const Gemm g, const Sched& S, const Epi& E) {
;     ...
;             PG8_WAIT_V(8); PG8_WAIT_L(0); PG8_BAR; PG8_MMA(1, 0, At, B0); PG8_MMA(1, 1, At, B1); PG8_BAR; PG8_SCHED;
;             PG8_LDB(B0, 1, 0); PG8_LDB(B1, 1, 1); PG8_SCHED; PG8_LDA(At, 1, 0); PG8_STAGE(PG8_SA(0, 1), a2 + hstepA, voffA);
;             PG8_WAIT_V(8); PG8_WAIT_L(0); PG8_BAR; PG8_MMA(0, 0, At, B0); PG8_MMA(0, 1, At, B1); PG8_BAR; PG8_SCHED;
	s_setprio 1
	s_waitcnt lgkmcnt(0)
	v_mfma_f32_16x16x32_bf16 v[62:65], v[140:143], v[176:179], 0
	v_mfma_f32_16x16x32_bf16 v[58:61], v[148:151], v[176:179], 0
	v_mfma_f32_16x16x32_bf16 v[54:57], v[140:143], v[184:187], 0
	v_mfma_f32_16x16x32_bf16 v[46:49], v[148:151], v[184:187], 0
	v_mfma_f32_16x16x32_bf16 v[38:41], v[140:143], v[206:209], 0
	v_mfma_f32_16x16x32_bf16 v[30:33], v[148:151], v[206:209], 0
	v_mfma_f32_16x16x32_bf16 v[22:25], v[140:143], v[214:217], 0
	v_mfma_f32_16x16x32_bf16 v[14:17], v[148:151], v[214:217], 0
	v_mfma_f32_16x16x32_bf16 v[62:65], v[144:147], v[180:183], v[62:65]
	v_mfma_f32_16x16x32_bf16 v[58:61], v[156:159], v[180:183], v[58:61]
	v_mfma_f32_16x16x32_bf16 v[54:57], v[144:147], v[188:191], v[54:57]
	v_mfma_f32_16x16x32_bf16 v[46:49], v[156:159], v[188:191], v[46:49]
	v_mfma_f32_16x16x32_bf16 v[38:41], v[144:147], v[210:213], v[38:41]
	v_mfma_f32_16x16x32_bf16 v[30:33], v[156:159], v[210:213], v[30:33]
	v_mfma_f32_16x16x32_bf16 v[22:25], v[144:147], v[218:221], v[22:25]
	v_mfma_f32_16x16x32_bf16 v[14:17], v[156:159], v[218:221], v[14:17]
	s_setprio 0
	s_setprio 1
	v_mfma_f32_16x16x32_bf16 v[50:53], v[160:163], v[176:179], 0
	v_mfma_f32_16x16x32_bf16 v[42:45], v[168:171], v[176:179], 0
	v_mfma_f32_16x16x32_bf16 v[34:37], v[160:163], v[184:187], 0
	v_mfma_f32_16x16x32_bf16 v[26:29], v[168:171], v[184:187], 0
	v_mfma_f32_16x16x32_bf16 v[18:21], v[160:163], v[206:209], 0
	v_mfma_f32_16x16x32_bf16 v[10:13], v[168:171], v[206:209], 0
	v_mfma_f32_16x16x32_bf16 v[6:9], v[160:163], v[214:217], 0
	v_mfma_f32_16x16x32_bf16 v[2:5], v[168:171], v[214:217], 0
	v_mfma_f32_16x16x32_bf16 v[50:53], v[164:167], v[180:183], v[50:53]
	v_mfma_f32_16x16x32_bf16 v[42:45], v[172:175], v[180:183], v[42:45]
	v_mfma_f32_16x16x32_bf16 v[34:37], v[164:167], v[188:191], v[34:37]
	v_mfma_f32_16x16x32_bf16 v[26:29], v[172:175], v[188:191], v[26:29]
	v_mfma_f32_16x16x32_bf16 v[18:21], v[164:167], v[210:213], v[18:21]
	v_mfma_f32_16x16x32_bf16 v[10:13], v[172:175], v[210:213], v[10:13]
	v_mfma_f32_16x16x32_bf16 v[6:9], v[164:167], v[218:221], v[6:9]
	v_mfma_f32_16x16x32_bf16 v[2:5], v[172:175], v[218:221], v[2:5]
	s_setprio 0
	s_barrier
	s_add_i32 s40, 0, 0x18000
	s_add_i32 s41, 0, 0x1c000
	v_add_u32_e32 v156, s40, v153
	v_add_u32_e32 v172, s41, v153
	ds_read_b128 v[140:143], v156
	ds_read_b128 v[144:147], v156 offset:1024
	ds_read_b128 v[148:151], v156 offset:2048
	ds_read_b128 v[156:159], v156 offset:3072
	ds_read_b128 v[160:163], v172
	ds_read_b128 v[164:167], v172 offset:1024
	ds_read_b128 v[168:171], v172 offset:2048
	ds_read_b128 v[172:175], v172 offset:3072
	s_add_u32 s20, s20, 0x4000
	s_addc_u32 s21, s21, 0
	s_mov_b32 m0, s26
	v_lshl_add_u64 v[224:225], s[20:21], 0, v[134:135]
	ds_read_b128 v[176:179], v155 offset:32768
	ds_read_b128 v[180:183], v155 offset:33792
	ds_read_b128 v[184:187], v155 offset:34816
	ds_read_b128 v[188:191], v155 offset:35840
	ds_read_b128 v[206:209], v155 offset:36864
	ds_read_b128 v[210:213], v155 offset:37888
	ds_read_b128 v[214:217], v155 offset:38912
	ds_read_b128 v[218:221], v155 offset:39936
	global_load_lds_dwordx4 v[224:225], off
	v_lshl_add_u64 v[224:225], s[20:21], 0, v[132:133]
	s_mov_b32 m0, s27
	s_nop 0
	global_load_lds_dwordx4 v[224:225], off
	s_waitcnt vmcnt(8)
	s_waitcnt lgkmcnt(0)
	s_barrier
	s_setprio 1
	s_waitcnt lgkmcnt(0)
	v_mfma_f32_16x16x32_bf16 v[126:129], v[140:143], v[176:179], v[126:129]
	v_mfma_f32_16x16x32_bf16 v[122:125], v[148:151], v[176:179], v[122:125]
	v_mfma_f32_16x16x32_bf16 v[118:121], v[140:143], v[184:187], v[118:121]
	v_mfma_f32_16x16x32_bf16 v[114:117], v[148:151], v[184:187], v[114:117]
	v_mfma_f32_16x16x32_bf16 v[106:109], v[140:143], v[206:209], v[106:109]
	v_mfma_f32_16x16x32_bf16 v[98:101], v[148:151], v[206:209], v[98:101]
	v_mfma_f32_16x16x32_bf16 v[90:93], v[140:143], v[214:217], v[90:93]
	v_mfma_f32_16x16x32_bf16 v[82:85], v[148:151], v[214:217], v[82:85]
	v_mfma_f32_16x16x32_bf16 v[126:129], v[144:147], v[180:183], v[126:129]
	v_mfma_f32_16x16x32_bf16 v[122:125], v[156:159], v[180:183], v[122:125]
	v_mfma_f32_16x16x32_bf16 v[118:121], v[144:147], v[188:191], v[118:121]
	v_mfma_f32_16x16x32_bf16 v[114:117], v[156:159], v[188:191], v[114:117]
	v_mfma_f32_16x16x32_bf16 v[106:109], v[144:147], v[210:213], v[106:109]
	v_mfma_f32_16x16x32_bf16 v[98:101], v[156:159], v[210:213], v[98:101]
	v_mfma_f32_16x16x32_bf16 v[90:93], v[144:147], v[218:221], v[90:93]
	v_mfma_f32_16x16x32_bf16 v[82:85], v[156:159], v[218:221], v[82:85]
	s_setprio 0
	s_setprio 1
	v_mfma_f32_16x16x32_bf16 v[110:113], v[160:163], v[176:179], v[110:113]
	v_mfma_f32_16x16x32_bf16 v[102:105], v[168:171], v[176:179], v[102:105]
	v_mfma_f32_16x16x32_bf16 v[94:97], v[160:163], v[184:187], v[94:97]
	v_mfma_f32_16x16x32_bf16 v[86:89], v[168:171], v[184:187], v[86:89]
	v_mfma_f32_16x16x32_bf16 v[78:81], v[160:163], v[206:209], v[78:81]
	v_mfma_f32_16x16x32_bf16 v[74:77], v[168:171], v[206:209], v[74:77]
	v_mfma_f32_16x16x32_bf16 v[70:73], v[160:163], v[214:217], v[70:73]
	v_mfma_f32_16x16x32_bf16 v[66:69], v[168:171], v[214:217], v[66:69]
	v_mfma_f32_16x16x32_bf16 v[110:113], v[164:167], v[180:183], v[110:113]
	v_mfma_f32_16x16x32_bf16 v[102:105], v[172:175], v[180:183], v[102:105]
	v_mfma_f32_16x16x32_bf16 v[94:97], v[164:167], v[188:191], v[94:97]
	v_mfma_f32_16x16x32_bf16 v[86:89], v[172:175], v[188:191], v[86:89]
	v_mfma_f32_16x16x32_bf16 v[78:81], v[164:167], v[210:213], v[78:81]
	v_mfma_f32_16x16x32_bf16 v[74:77], v[172:175], v[210:213], v[74:77]
	v_mfma_f32_16x16x32_bf16 v[70:73], v[164:167], v[218:221], v[70:73]
	v_mfma_f32_16x16x32_bf16 v[66:69], v[172:175], v[218:221], v[66:69]
	s_setprio 0
	s_barrier
; #define PG8_STAGE(bufoff, gbase, voff) do { _Pragma("unroll") for (int _i = 0; _i < 2; ++_i) \
;         __builtin_amdgcn_global_load_lds((const unsigned*)((const char*)(gbase) + (voff)[_i]), (PG8_LAS unsigned*)(lds + (bufoff) + ldsw + _i * 8192), 16, 0, 0); } while (0)
; #define PG8_LDA(dst, b, h) do { _Pragma("unroll") for (int m = 0; m < 4; ++m) _Pragma("unroll") for (int k = 0; k < 2; ++k) dst[m][k] = *(const PG8_LAS bf16x8*)(lds + PG8_SA(b, h) + aoff + m * 2048 + k * 1024); } while (0)
; #define PG8_LDB(dst, b, h) do { _Pragma("unroll") for (int n = 0; n < 2; ++n) _Pragma("unroll") for (int k = 0; k < 2; ++k) dst[n][k] = *(const PG8_LAS bf16x8*)(lds + PG8_SB(b, h) + boff + n * 2048 + k * 1024); } while (0)
; template <class Epi, class Sched, bool ALIGN_EPI = false, bool SP2 = false>
; __device__ __forceinline__ void gemm_phase(PG8_LAS unsigned char* lds, const Gemm g, const Sched& S, const Epi& E) {
;     ...
;         for (int t = 0; t < nt; t += 2) {
;             const bool last = (t == nt - 2);
;             const char* a1 = cA + (size_t)(t + 1) * kstepA;
;             const char* a2 = last ? nA : cA + (size_t)(t + 2) * kstepA; const char* b2 = last ? nB : cB + (size_t)(t + 2) * kstep;
;             const char* a3 = a2 + kstepA; const char* b3 = b2 + kstep;
;             if (last && has_next) S.a_ready(nxt);
;             if constexpr (SP2) {
;             PG8_LDB(B0, 0, 0); PG8_LDB(B1, 0, 1); PG8_SCHED; PG8_LDA(At, 0, 0); PG8_STAGE(PG8_SA(1, 1), a1 + hstepA, voffA);
;             PG8_WAIT_V(8); PG8_WAIT_L(0); PG8_BAR; PG8_MMA(0, 0, At, B0); PG8_MMA(0, 1, At, B1); PG8_BAR; PG8_SCHED;
;             PG8_LDA(At, 0, 1); PG8_STAGE(PG8_SB(0, 0), b2, voffB); PG8_STAGE(PG8_SB(0, 1), b2 + hstepB, voffB); PG8_STAGE(PG8_SA(0, 0), a2, voffA);
;             PG8_WAIT_V(8); PG8_WAIT_L(0); PG8_BAR; PG8_MMA(1, 0, At, B0); PG8_MMA(1, 1, At, B1); PG8_BAR; PG8_SCHED;
;             PG8_LDB(B0, 1, 0); PG8_LDB(B1, 1, 1); PG8_SCHED; PG8_LDA(At, 1, 0); PG8_STAGE(PG8_SA(0, 1), a2 + hstepA, voffA);
;             PG8_WAIT_V(8); PG8_WAIT_L(0); PG8_BAR; PG8_MMA(0, 0, At, B0); PG8_MMA(0, 1, At, B1); PG8_BAR; PG8_SCHED;
;             PG8_LDA(At, 1, 1); PG8_STAGE(PG8_SB(1, 0), b3, voffB); PG8_STAGE(PG8_SB(1, 1), b3 + hstepB, voffB); PG8_STAGE(PG8_SA(1, 0), a3, voffA);
;             PG8_WAIT_V(8); PG8_WAIT_L(0); PG8_BAR; PG8_MMA(1, 0, At, B0); PG8_MMA(1, 1, At, B1); PG8_BAR; PG8_SCHED;
	s_add_i32 s20, s40, s22
	v_lshl_add_u64 v[192:193], v[192:193], 0, s[78:79]
	s_mov_b32 m0, s20
	ds_read_b128 v[176:179], v155 offset:49152
	ds_read_b128 v[180:183], v155 offset:50176
	ds_read_b128 v[184:187], v155 offset:51200
	ds_read_b128 v[188:191], v155 offset:52224
	ds_read_b128 v[206:209], v155 offset:53248
	ds_read_b128 v[210:213], v155 offset:54272
	ds_read_b128 v[214:217], v155 offset:55296
	ds_read_b128 v[218:221], v155 offset:56320
	global_load_lds_dwordx4 v[192:193], off
	s_add_i32 m0, s20, 0x2000
	s_add_u32 s18, s18, 0xb0080
	v_lshl_add_u64 v[192:193], v[222:223], 0, s[78:79]
	s_addc_u32 s19, s19, 0
	s_add_i32 s20, s41, s22
	global_load_lds_dwordx4 v[192:193], off
	v_lshl_add_u64 v[192:193], s[18:19], 0, v[0:1]
	s_mov_b32 m0, s20
	s_nop 0
	global_load_lds_dwordx4 v[192:193], off
	v_lshl_add_u64 v[192:193], s[18:19], 0, v[130:131]
	s_add_i32 m0, s20, 0x2000
	s_nop 0
	global_load_lds_dwordx4 v[192:193], off
	v_lshl_add_u64 v[192:193], s[16:17], 0, v[134:135]
	s_mov_b32 m0, s28
	s_nop 0
	global_load_lds_dwordx4 v[192:193], off
	v_lshl_add_u64 v[192:193], s[16:17], 0, v[132:133]
	s_mov_b32 m0, s29
	s_nop 0
	global_load_lds_dwordx4 v[192:193], off
	s_waitcnt vmcnt(8)
	s_waitcnt lgkmcnt(0)
	s_barrier
	s_setprio 1
	s_waitcnt lgkmcnt(0)
	v_mfma_f32_16x16x32_bf16 v[62:65], v[140:143], v[176:179], v[62:65]
	v_mfma_f32_16x16x32_bf16 v[58:61], v[148:151], v[176:179], v[58:61]
	v_mfma_f32_16x16x32_bf16 v[54:57], v[140:143], v[184:187], v[54:57]
	v_mfma_f32_16x16x32_bf16 v[46:49], v[148:151], v[184:187], v[46:49]
	v_mfma_f32_16x16x32_bf16 v[38:41], v[140:143], v[206:209], v[38:41]
	v_mfma_f32_16x16x32_bf16 v[30:33], v[148:151], v[206:209], v[30:33]
	v_mfma_f32_16x16x32_bf16 v[22:25], v[140:143], v[214:217], v[22:25]
	v_mfma_f32_16x16x32_bf16 v[14:17], v[148:151], v[214:217], v[14:17]
	v_mfma_f32_16x16x32_bf16 v[62:65], v[144:147], v[180:183], v[62:65]
	v_mfma_f32_16x16x32_bf16 v[58:61], v[156:159], v[180:183], v[58:61]
	v_mfma_f32_16x16x32_bf16 v[54:57], v[144:147], v[188:191], v[54:57]
	v_mfma_f32_16x16x32_bf16 v[46:49], v[156:159], v[188:191], v[46:49]
	v_mfma_f32_16x16x32_bf16 v[38:41], v[144:147], v[210:213], v[38:41]
	v_mfma_f32_16x16x32_bf16 v[30:33], v[156:159], v[210:213], v[30:33]
	v_mfma_f32_16x16x32_bf16 v[22:25], v[144:147], v[218:221], v[22:25]
	v_mfma_f32_16x16x32_bf16 v[14:17], v[156:159], v[218:221], v[14:17]
	s_add_i32 s39, s39, 2
	s_setprio 0
	s_setprio 1
	v_mfma_f32_16x16x32_bf16 v[50:53], v[160:163], v[176:179], v[50:53]
	s_add_u32 s0, s0, 0x800000
	v_mfma_f32_16x16x32_bf16 v[42:45], v[168:171], v[176:179], v[42:45]
	s_addc_u32 s1, s1, 0
	v_mfma_f32_16x16x32_bf16 v[34:37], v[160:163], v[184:187], v[34:37]
	s_add_u32 s37, s37, 0x100
	v_mfma_f32_16x16x32_bf16 v[26:29], v[168:171], v[184:187], v[26:29]
	s_addc_u32 s38, s38, 0
	v_mfma_f32_16x16x32_bf16 v[18:21], v[160:163], v[206:209], v[18:21]
	s_add_u32 s16, s0, 0x3fc000
	v_mfma_f32_16x16x32_bf16 v[10:13], v[168:171], v[206:209], v[10:13]
	s_addc_u32 s17, s1, 0
	v_mfma_f32_16x16x32_bf16 v[6:9], v[160:163], v[214:217], v[6:9]
	s_cmp_eq_u32 s39, 40
	v_mfma_f32_16x16x32_bf16 v[2:5], v[168:171], v[214:217], v[2:5]
	s_cselect_b32 s20, s36, s16
	v_mfma_f32_16x16x32_bf16 v[50:53], v[164:167], v[180:183], v[50:53]
	s_cselect_b32 s21, s11, s17
	v_mfma_f32_16x16x32_bf16 v[42:45], v[172:175], v[180:183], v[42:45]
	s_cselect_b32 s18, s12, s37
	v_mfma_f32_16x16x32_bf16 v[34:37], v[164:167], v[188:191], v[34:37]
	s_cselect_b32 s19, s13, s38
	v_mfma_f32_16x16x32_bf16 v[26:29], v[172:175], v[188:191], v[26:29]
	s_add_u32 s16, s20, 0x400000
	v_mfma_f32_16x16x32_bf16 v[18:21], v[164:167], v[210:213], v[18:21]
	s_addc_u32 s17, s21, 0
	v_mfma_f32_16x16x32_bf16 v[10:13], v[172:175], v[210:213], v[10:13]
	s_add_i32 s40, 0, 0x10000
	v_mfma_f32_16x16x32_bf16 v[6:9], v[164:167], v[218:221], v[6:9]
	s_add_i32 s42, 0, 0x14000
	v_mfma_f32_16x16x32_bf16 v[2:5], v[172:175], v[218:221], v[2:5]
	s_setprio 0
	s_barrier
.LBB0_35:
	v_add_u32_e32 v156, s40, v153
	v_add_u32_e32 v172, s42, v153
	ds_read_b128 v[140:143], v156
	ds_read_b128 v[144:147], v156 offset:1024
	ds_read_b128 v[148:151], v156 offset:2048
	ds_read_b128 v[156:159], v156 offset:3072
	ds_read_b128 v[160:163], v172
	ds_read_b128 v[164:167], v172 offset:1024
	ds_read_b128 v[168:171], v172 offset:2048
	ds_read_b128 v[172:175], v172 offset:3072
	v_lshl_add_u64 v[192:193], s[0:1], 0, v[136:137]
	s_add_i32 m0, s23, 0xc000
	ds_read_b128 v[176:179], v155
	ds_read_b128 v[180:183], v155 offset:1024
	ds_read_b128 v[184:187], v155 offset:2048
	ds_read_b128 v[188:191], v155 offset:3072
	ds_read_b128 v[206:209], v155 offset:4096
	ds_read_b128 v[210:213], v155 offset:5120
	ds_read_b128 v[214:217], v155 offset:6144
	ds_read_b128 v[218:221], v155 offset:7168
	global_load_lds_dwordx4 v[192:193], off
	v_lshl_add_u64 v[192:193], s[0:1], 0, v[138:139]
	s_add_i32 m0, s23, 0xe000
	s_nop 0
	global_load_lds_dwordx4 v[192:193], off
	s_waitcnt vmcnt(8)
	s_waitcnt lgkmcnt(0)
	s_barrier
; #define PG8_STAGE(bufoff, gbase, voff) do { _Pragma("unroll") for (int _i = 0; _i < 2; ++_i) \
;         __builtin_amdgcn_global_load_lds((const unsigned*)((const char*)(gbase) + (voff)[_i]), (PG8_LAS unsigned*)(lds + (bufoff) + ldsw + _i * 8192), 16, 0, 0); } while (0)
; #define PG8_LDA(dst, b, h) do { _Pragma("unroll") for (int m = 0; m < 4; ++m) _Pragma("unroll") for (int k = 0; k < 2; ++k) dst[m][k] = *(const PG8_LAS bf16x8*)(lds + PG8_SA(b, h) + aoff + m * 2048 + k * 1024); } while (0)
; #define PG8_LDB(dst, b, h) do { _Pragma("unroll") for (int n = 0; n < 2; ++n) _Pragma("unroll") for (int k = 0; k < 2; ++k) dst[n][k] = *(const PG8_LAS bf16x8*)(lds + PG8_SB(b, h) + boff + n * 2048 + k * 1024); } while (0)
; #define PG8_MMA(ai, bj, At, Bt) do { __builtin_amdgcn_s_setprio(1); _Pragma("unroll") for (int m = 0; m < 4; ++m) _Pragma("unroll") for (int n = 0; n < 2; ++n) _Pragma("unroll") for (int k = 0; k < 2; ++k) \
;         acc[ai][bj][m][n] = __builtin_amdgcn_mfma_f32_16x16x32_bf16(Bt[n][k], At[m][k], acc[ai][bj][m][n], 0, 0, 0); __builtin_amdgcn_s_setprio(0); } while (0)
; #define PG8_WAIT_V(n) asm volatile("s_waitcnt vmcnt(" #n ")" ::: "memory")
; #define PG8_WAIT_L(n) asm volatile("s_waitcnt lgkmcnt(" #n ")" ::: "memory")
; #define PG8_BAR __builtin_amdgcn_s_barrier()
; #define PG8_SCHED __builtin_amdgcn_sched_barrier(0)
; template <class Epi, class Sched, bool ALIGN_EPI = false, bool SP2 = false>
; __device__ __forceinline__ void gemm_phase(PG8_LAS unsigned char* lds, const Gemm g, const Sched& S, const Epi& E) {
;     ...
;             PG8_LDB(B0, 0, 0); PG8_LDB(B1, 0, 1); PG8_SCHED; PG8_LDA(At, 0, 0); PG8_STAGE(PG8_SA(1, 1), a1 + hstepA, voffA);
;             PG8_WAIT_V(8); PG8_WAIT_L(0); PG8_BAR; PG8_MMA(0, 0, At, B0); PG8_MMA(0, 1, At, B1); PG8_BAR; PG8_SCHED;
;             PG8_LDA(At, 0, 1); PG8_STAGE(PG8_SB(0, 0), b2, voffB); PG8_STAGE(PG8_SB(0, 1), b2 + hstepB, voffB); PG8_STAGE(PG8_SA(0, 0), a2, voffA);
;             PG8_WAIT_V(8); PG8_WAIT_L(0); PG8_BAR; PG8_MMA(1, 0, At, B0); PG8_MMA(1, 1, At, B1); PG8_BAR; PG8_SCHED;
	s_setprio 1
	s_waitcnt lgkmcnt(0)
	v_mfma_f32_16x16x32_bf16 v[126:129], v[140:143], v[176:179], v[126:129]
	v_mfma_f32_16x16x32_bf16 v[122:125], v[148:151], v[176:179], v[122:125]
	v_mfma_f32_16x16x32_bf16 v[118:121], v[140:143], v[184:187], v[118:121]
	v_mfma_f32_16x16x32_bf16 v[114:117], v[148:151], v[184:187], v[114:117]
	v_mfma_f32_16x16x32_bf16 v[106:109], v[140:143], v[206:209], v[106:109]
	v_mfma_f32_16x16x32_bf16 v[98:101], v[148:151], v[206:209], v[98:101]
	v_mfma_f32_16x16x32_bf16 v[90:93], v[140:143], v[214:217], v[90:93]
	v_mfma_f32_16x16x32_bf16 v[82:85], v[148:151], v[214:217], v[82:85]
	v_mfma_f32_16x16x32_bf16 v[126:129], v[144:147], v[180:183], v[126:129]
	v_mfma_f32_16x16x32_bf16 v[122:125], v[156:159], v[180:183], v[122:125]
	v_mfma_f32_16x16x32_bf16 v[118:121], v[144:147], v[188:191], v[118:121]
	v_mfma_f32_16x16x32_bf16 v[114:117], v[156:159], v[188:191], v[114:117]
	v_mfma_f32_16x16x32_bf16 v[106:109], v[144:147], v[210:213], v[106:109]
	v_mfma_f32_16x16x32_bf16 v[98:101], v[156:159], v[210:213], v[98:101]
	v_mfma_f32_16x16x32_bf16 v[90:93], v[144:147], v[218:221], v[90:93]
	v_mfma_f32_16x16x32_bf16 v[82:85], v[156:159], v[218:221], v[82:85]
	s_setprio 0
	s_setprio 1
	v_mfma_f32_16x16x32_bf16 v[110:113], v[160:163], v[176:179], v[110:113]
	v_mfma_f32_16x16x32_bf16 v[102:105], v[168:171], v[176:179], v[102:105]
	v_mfma_f32_16x16x32_bf16 v[94:97], v[160:163], v[184:187], v[94:97]
	v_mfma_f32_16x16x32_bf16 v[86:89], v[168:171], v[184:187], v[86:89]
	v_mfma_f32_16x16x32_bf16 v[78:81], v[160:163], v[206:209], v[78:81]
	v_mfma_f32_16x16x32_bf16 v[74:77], v[168:171], v[206:209], v[74:77]
	v_mfma_f32_16x16x32_bf16 v[70:73], v[160:163], v[214:217], v[70:73]
	v_mfma_f32_16x16x32_bf16 v[66:69], v[168:171], v[214:217], v[66:69]
	v_mfma_f32_16x16x32_bf16 v[110:113], v[164:167], v[180:183], v[110:113]
	v_mfma_f32_16x16x32_bf16 v[102:105], v[172:175], v[180:183], v[102:105]
	v_mfma_f32_16x16x32_bf16 v[94:97], v[164:167], v[188:191], v[94:97]
	v_mfma_f32_16x16x32_bf16 v[86:89], v[172:175], v[188:191], v[86:89]
	v_mfma_f32_16x16x32_bf16 v[78:81], v[164:167], v[210:213], v[78:81]
	v_mfma_f32_16x16x32_bf16 v[74:77], v[172:175], v[210:213], v[74:77]
	v_mfma_f32_16x16x32_bf16 v[70:73], v[164:167], v[218:221], v[70:73]
	v_mfma_f32_16x16x32_bf16 v[66:69], v[172:175], v[218:221], v[66:69]
	s_setprio 0
	s_barrier
	s_add_i32 s40, s40, s22
	v_lshl_add_u64 v[192:193], s[18:19], 0, v[0:1]
	s_mov_b32 m0, s40
	ds_read_b128 v[176:179], v155 offset:16384
	ds_read_b128 v[180:183], v155 offset:17408
	ds_read_b128 v[184:187], v155 offset:18432
	ds_read_b128 v[188:191], v155 offset:19456
	ds_read_b128 v[206:209], v155 offset:20480
	ds_read_b128 v[210:213], v155 offset:21504
	ds_read_b128 v[214:217], v155 offset:22528
	ds_read_b128 v[218:221], v155 offset:23552
	global_load_lds_dwordx4 v[192:193], off
	s_add_i32 m0, s40, 0x2000
	s_add_u32 s40, s18, 0xb0000
	v_lshl_add_u64 v[222:223], s[18:19], 0, v[130:131]
	s_addc_u32 s41, s19, 0
	s_add_i32 s42, s42, s22
	global_load_lds_dwordx4 v[222:223], off
	v_lshl_add_u64 v[224:225], s[40:41], 0, v[0:1]
	s_mov_b32 m0, s42
	s_nop 0
	global_load_lds_dwordx4 v[224:225], off
	v_lshl_add_u64 v[224:225], s[40:41], 0, v[130:131]
	s_add_i32 m0, s42, 0x2000
	s_nop 0
	global_load_lds_dwordx4 v[224:225], off
	v_lshl_add_u64 v[224:225], s[20:21], 0, v[134:135]
	s_mov_b32 m0, s23
	s_nop 0
	global_load_lds_dwordx4 v[224:225], off
	v_lshl_add_u64 v[224:225], s[20:21], 0, v[132:133]
	s_mov_b32 m0, s25
	s_nop 0
	global_load_lds_dwordx4 v[224:225], off
	s_waitcnt vmcnt(8)
	s_waitcnt lgkmcnt(0)
	s_barrier
	s_setprio 1
	s_waitcnt lgkmcnt(0)
	v_mfma_f32_16x16x32_bf16 v[62:65], v[140:143], v[176:179], v[62:65]
	v_mfma_f32_16x16x32_bf16 v[58:61], v[148:151], v[176:179], v[58:61]
	v_mfma_f32_16x16x32_bf16 v[54:57], v[140:143], v[184:187], v[54:57]
	v_mfma_f32_16x16x32_bf16 v[46:49], v[148:151], v[184:187], v[46:49]
	v_mfma_f32_16x16x32_bf16 v[38:41], v[140:143], v[206:209], v[38:41]
	v_mfma_f32_16x16x32_bf16 v[30:33], v[148:151], v[206:209], v[30:33]
	v_mfma_f32_16x16x32_bf16 v[22:25], v[140:143], v[214:217], v[22:25]
	v_mfma_f32_16x16x32_bf16 v[14:17], v[148:151], v[214:217], v[14:17]
	v_mfma_f32_16x16x32_bf16 v[62:65], v[144:147], v[180:183], v[62:65]
	v_mfma_f32_16x16x32_bf16 v[58:61], v[156:159], v[180:183], v[58:61]
	v_mfma_f32_16x16x32_bf16 v[54:57], v[144:147], v[188:191], v[54:57]
	v_mfma_f32_16x16x32_bf16 v[46:49], v[156:159], v[188:191], v[46:49]
	v_mfma_f32_16x16x32_bf16 v[38:41], v[144:147], v[210:213], v[38:41]
	v_mfma_f32_16x16x32_bf16 v[30:33], v[156:159], v[210:213], v[30:33]
	v_mfma_f32_16x16x32_bf16 v[22:25], v[144:147], v[218:221], v[22:25]
	v_mfma_f32_16x16x32_bf16 v[14:17], v[156:159], v[218:221], v[14:17]
	s_setprio 0
	s_setprio 1
	v_mfma_f32_16x16x32_bf16 v[50:53], v[160:163], v[176:179], v[50:53]
	v_mfma_f32_16x16x32_bf16 v[42:45], v[168:171], v[176:179], v[42:45]
	v_mfma_f32_16x16x32_bf16 v[34:37], v[160:163], v[184:187], v[34:37]
	v_mfma_f32_16x16x32_bf16 v[26:29], v[168:171], v[184:187], v[26:29]
	v_mfma_f32_16x16x32_bf16 v[18:21], v[160:163], v[206:209], v[18:21]
	v_mfma_f32_16x16x32_bf16 v[10:13], v[168:171], v[206:209], v[10:13]
	v_mfma_f32_16x16x32_bf16 v[6:9], v[160:163], v[214:217], v[6:9]
	v_mfma_f32_16x16x32_bf16 v[2:5], v[168:171], v[214:217], v[2:5]
	v_mfma_f32_16x16x32_bf16 v[50:53], v[164:167], v[180:183], v[50:53]
	v_mfma_f32_16x16x32_bf16 v[42:45], v[172:175], v[180:183], v[42:45]
	v_mfma_f32_16x16x32_bf16 v[34:37], v[164:167], v[188:191], v[34:37]
	v_mfma_f32_16x16x32_bf16 v[26:29], v[172:175], v[188:191], v[26:29]
	v_mfma_f32_16x16x32_bf16 v[18:21], v[164:167], v[210:213], v[18:21]
	v_mfma_f32_16x16x32_bf16 v[10:13], v[172:175], v[210:213], v[10:13]
	v_mfma_f32_16x16x32_bf16 v[6:9], v[164:167], v[218:221], v[6:9]
	v_mfma_f32_16x16x32_bf16 v[2:5], v[172:175], v[218:221], v[2:5]
	s_setprio 0
	s_barrier
; #define PG8_STAGE(bufoff, gbase, voff) do { _Pragma("unroll") for (int _i = 0; _i < 2; ++_i) \
;         __builtin_amdgcn_global_load_lds((const unsigned*)((const char*)(gbase) + (voff)[_i]), (PG8_LAS unsigned*)(lds + (bufoff) + ldsw + _i * 8192), 16, 0, 0); } while (0)
; #define PG8_LDA(dst, b, h) do { _Pragma("unroll") for (int m = 0; m < 4; ++m) _Pragma("unroll") for (int k = 0; k < 2; ++k) dst[m][k] = *(const PG8_LAS bf16x8*)(lds + PG8_SA(b, h) + aoff + m * 2048 + k * 1024); } while (0)
; #define PG8_LDB(dst, b, h) do { _Pragma("unroll") for (int n = 0; n < 2; ++n) _Pragma("unroll") for (int k = 0; k < 2; ++k) dst[n][k] = *(const PG8_LAS bf16x8*)(lds + PG8_SB(b, h) + boff + n * 2048 + k * 1024); } while (0)
; #define PG8_MMA(ai, bj, At, Bt) do { __builtin_amdgcn_s_setprio(1); _Pragma("unroll") for (int m = 0; m < 4; ++m) _Pragma("unroll") for (int n = 0; n < 2; ++n) _Pragma("unroll") for (int k = 0; k < 2; ++k) \
;         acc[ai][bj][m][n] = __builtin_amdgcn_mfma_f32_16x16x32_bf16(Bt[n][k], At[m][k], acc[ai][bj][m][n], 0, 0, 0); __builtin_amdgcn_s_setprio(0); } while (0)
; #define PG8_WAIT_V(n) asm volatile("s_waitcnt vmcnt(" #n ")" ::: "memory")
; #define PG8_WAIT_L(n) asm volatile("s_waitcnt lgkmcnt(" #n ")" ::: "memory")
; #define PG8_BAR __builtin_amdgcn_s_barrier()
; #define PG8_SCHED __builtin_amdgcn_sched_barrier(0)
; template <class Epi, class Sched, bool ALIGN_EPI = false, bool SP2 = false>
; __device__ __forceinline__ void gemm_phase(PG8_LAS unsigned char* lds, const Gemm g, const Sched& S, const Epi& E) {
;     ...
;             PG8_LDB(B0, 1, 0); PG8_LDB(B1, 1, 1); PG8_SCHED; PG8_LDA(At, 1, 0); PG8_STAGE(PG8_SA(0, 1), a2 + hstepA, voffA);
;             PG8_WAIT_V(8); PG8_WAIT_L(0); PG8_BAR; PG8_MMA(0, 0, At, B0); PG8_MMA(0, 1, At, B1); PG8_BAR; PG8_SCHED;
	s_add_i32 s40, 0, 0x18000
	s_add_i32 s41, 0, 0x1c000
	v_add_u32_e32 v156, s40, v153
	v_add_u32_e32 v172, s41, v153
	ds_read_b128 v[140:143], v156
	ds_read_b128 v[144:147], v156 offset:1024
	ds_read_b128 v[148:151], v156 offset:2048
	ds_read_b128 v[156:159], v156 offset:3072
	ds_read_b128 v[160:163], v172
	ds_read_b128 v[164:167], v172 offset:1024
	ds_read_b128 v[168:171], v172 offset:2048
	ds_read_b128 v[172:175], v172 offset:3072
	s_add_u32 s20, s20, 0x4000
	s_addc_u32 s21, s21, 0
	s_mov_b32 m0, s26
	v_lshl_add_u64 v[224:225], s[20:21], 0, v[134:135]
	ds_read_b128 v[176:179], v155 offset:32768
	ds_read_b128 v[180:183], v155 offset:33792
	ds_read_b128 v[184:187], v155 offset:34816
	ds_read_b128 v[188:191], v155 offset:35840
	ds_read_b128 v[206:209], v155 offset:36864
	ds_read_b128 v[210:213], v155 offset:37888
	ds_read_b128 v[214:217], v155 offset:38912
	ds_read_b128 v[218:221], v155 offset:39936
	global_load_lds_dwordx4 v[224:225], off
	v_lshl_add_u64 v[224:225], s[20:21], 0, v[132:133]
	s_mov_b32 m0, s27
	s_nop 0
	global_load_lds_dwordx4 v[224:225], off
	s_waitcnt vmcnt(8)
	s_waitcnt lgkmcnt(0)
	s_barrier
	s_setprio 1
	s_waitcnt lgkmcnt(0)
	v_mfma_f32_16x16x32_bf16 v[126:129], v[140:143], v[176:179], v[126:129]
	v_mfma_f32_16x16x32_bf16 v[122:125], v[148:151], v[176:179], v[122:125]
	v_mfma_f32_16x16x32_bf16 v[118:121], v[140:143], v[184:187], v[118:121]
	v_mfma_f32_16x16x32_bf16 v[114:117], v[148:151], v[184:187], v[114:117]
	v_mfma_f32_16x16x32_bf16 v[106:109], v[140:143], v[206:209], v[106:109]
	v_mfma_f32_16x16x32_bf16 v[98:101], v[148:151], v[206:209], v[98:101]
	v_mfma_f32_16x16x32_bf16 v[90:93], v[140:143], v[214:217], v[90:93]
	v_mfma_f32_16x16x32_bf16 v[82:85], v[148:151], v[214:217], v[82:85]
	v_mfma_f32_16x16x32_bf16 v[126:129], v[144:147], v[180:183], v[126:129]
	v_mfma_f32_16x16x32_bf16 v[122:125], v[156:159], v[180:183], v[122:125]
	v_mfma_f32_16x16x32_bf16 v[118:121], v[144:147], v[188:191], v[118:121]
	v_mfma_f32_16x16x32_bf16 v[114:117], v[156:159], v[188:191], v[114:117]
	v_mfma_f32_16x16x32_bf16 v[106:109], v[144:147], v[210:213], v[106:109]
	v_mfma_f32_16x16x32_bf16 v[98:101], v[156:159], v[210:213], v[98:101]
	v_mfma_f32_16x16x32_bf16 v[90:93], v[144:147], v[218:221], v[90:93]
	v_mfma_f32_16x16x32_bf16 v[82:85], v[156:159], v[218:221], v[82:85]
	s_setprio 0
	s_setprio 1
	v_mfma_f32_16x16x32_bf16 v[110:113], v[160:163], v[176:179], v[110:113]
	v_mfma_f32_16x16x32_bf16 v[102:105], v[168:171], v[176:179], v[102:105]
	v_mfma_f32_16x16x32_bf16 v[94:97], v[160:163], v[184:187], v[94:97]
	v_mfma_f32_16x16x32_bf16 v[86:89], v[168:171], v[184:187], v[86:89]
	v_mfma_f32_16x16x32_bf16 v[78:81], v[160:163], v[206:209], v[78:81]
	v_mfma_f32_16x16x32_bf16 v[74:77], v[168:171], v[206:209], v[74:77]
	v_mfma_f32_16x16x32_bf16 v[70:73], v[160:163], v[214:217], v[70:73]
	v_mfma_f32_16x16x32_bf16 v[66:69], v[168:171], v[214:217], v[66:69]
	v_mfma_f32_16x16x32_bf16 v[110:113], v[164:167], v[180:183], v[110:113]
	v_mfma_f32_16x16x32_bf16 v[102:105], v[172:175], v[180:183], v[102:105]
	v_mfma_f32_16x16x32_bf16 v[94:97], v[164:167], v[188:191], v[94:97]
	v_mfma_f32_16x16x32_bf16 v[86:89], v[172:175], v[188:191], v[86:89]
	v_mfma_f32_16x16x32_bf16 v[78:81], v[164:167], v[210:213], v[78:81]
	v_mfma_f32_16x16x32_bf16 v[74:77], v[172:175], v[210:213], v[74:77]
	v_mfma_f32_16x16x32_bf16 v[70:73], v[164:167], v[218:221], v[70:73]
	v_mfma_f32_16x16x32_bf16 v[66:69], v[172:175], v[218:221], v[66:69]
	s_setprio 0
	s_barrier
; #define PG8_STAGE(bufoff, gbase, voff) do { _Pragma("unroll") for (int _i = 0; _i < 2; ++_i) \
;         __builtin_amdgcn_global_load_lds((const unsigned*)((const char*)(gbase) + (voff)[_i]), (PG8_LAS unsigned*)(lds + (bufoff) + ldsw + _i * 8192), 16, 0, 0); } while (0)
; #define PG8_LDA(dst, b, h) do { _Pragma("unroll") for (int m = 0; m < 4; ++m) _Pragma("unroll") for (int k = 0; k < 2; ++k) dst[m][k] = *(const PG8_LAS bf16x8*)(lds + PG8_SA(b, h) + aoff + m * 2048 + k * 1024); } while (0)
; #define PG8_LDB(dst, b, h) do { _Pragma("unroll") for (int n = 0; n < 2; ++n) _Pragma("unroll") for (int k = 0; k < 2; ++k) dst[n][k] = *(const PG8_LAS bf16x8*)(lds + PG8_SB(b, h) + boff + n * 2048 + k * 1024); } while (0)
; template <class Epi, class Sched, bool ALIGN_EPI = false, bool SP2 = false>
; __device__ __forceinline__ void gemm_phase(PG8_LAS unsigned char* lds, const Gemm g, const Sched& S, const Epi& E) {
;     ...
;         for (int t = 0; t < nt; t += 2) {
;             const bool last = (t == nt - 2);
;             const char* a1 = cA + (size_t)(t + 1) * kstepA;
;             const char* a2 = last ? nA : cA + (size_t)(t + 2) * kstepA; const char* b2 = last ? nB : cB + (size_t)(t + 2) * kstep;
;             const char* a3 = a2 + kstepA; const char* b3 = b2 + kstep;
;             if (last && has_next) S.a_ready(nxt);
;             if constexpr (SP2) {
;             PG8_LDB(B0, 0, 0); PG8_LDB(B1, 0, 1); PG8_SCHED; PG8_LDA(At, 0, 0); PG8_STAGE(PG8_SA(1, 1), a1 + hstepA, voffA);
;             PG8_WAIT_V(8); PG8_WAIT_L(0); PG8_BAR; PG8_MMA(0, 0, At, B0); PG8_MMA(0, 1, At, B1); PG8_BAR; PG8_SCHED;
;             PG8_LDA(At, 0, 1); PG8_STAGE(PG8_SB(0, 0), b2, voffB); PG8_STAGE(PG8_SB(0, 1), b2 + hstepB, voffB); PG8_STAGE(PG8_SA(0, 0), a2, voffA);
;             PG8_WAIT_V(8); PG8_WAIT_L(0); PG8_BAR; PG8_MMA(1, 0, At, B0); PG8_MMA(1, 1, At, B1); PG8_BAR; PG8_SCHED;
;             PG8_LDB(B0, 1, 0); PG8_LDB(B1, 1, 1); PG8_SCHED; PG8_LDA(At, 1, 0); PG8_STAGE(PG8_SA(0, 1), a2 + hstepA, voffA);
;             PG8_WAIT_V(8); PG8_WAIT_L(0); PG8_BAR; PG8_MMA(0, 0, At, B0); PG8_MMA(0, 1, At, B1); PG8_BAR; PG8_SCHED;
;             PG8_LDA(At, 1, 1); PG8_STAGE(PG8_SB(1, 0), b3, voffB); PG8_STAGE(PG8_SB(1, 1), b3 + hstepB, voffB); PG8_STAGE(PG8_SA(1, 0), a3, voffA);
;             PG8_WAIT_V(8); PG8_WAIT_L(0); PG8_BAR; PG8_MMA(1, 0, At, B0); PG8_MMA(1, 1, At, B1); PG8_BAR; PG8_SCHED;
	s_add_i32 s20, s40, s22
	v_lshl_add_u64 v[192:193], v[192:193], 0, s[78:79]
	s_mov_b32 m0, s20
	ds_read_b128 v[176:179], v155 offset:49152
	ds_read_b128 v[180:183], v155 offset:50176
	ds_read_b128 v[184:187], v155 offset:51200
	ds_read_b128 v[188:191], v155 offset:52224
	ds_read_b128 v[206:209], v155 offset:53248
	ds_read_b128 v[210:213], v155 offset:54272
	ds_read_b128 v[214:217], v155 offset:55296
	ds_read_b128 v[218:221], v155 offset:56320
	global_load_lds_dwordx4 v[192:193], off
	s_add_i32 m0, s20, 0x2000
	s_add_u32 s18, s18, 0xb0080
	v_lshl_add_u64 v[192:193], v[222:223], 0, s[78:79]
	s_addc_u32 s19, s19, 0
	s_add_i32 s20, s41, s22
	global_load_lds_dwordx4 v[192:193], off
	v_lshl_add_u64 v[192:193], s[18:19], 0, v[0:1]
	s_mov_b32 m0, s20
	s_nop 0
	global_load_lds_dwordx4 v[192:193], off
	v_lshl_add_u64 v[192:193], s[18:19], 0, v[130:131]
	s_add_i32 m0, s20, 0x2000
	s_nop 0
	global_load_lds_dwordx4 v[192:193], off
	v_lshl_add_u64 v[192:193], s[16:17], 0, v[134:135]
	s_mov_b32 m0, s28
	s_nop 0
	global_load_lds_dwordx4 v[192:193], off
	v_lshl_add_u64 v[192:193], s[16:17], 0, v[132:133]
	s_mov_b32 m0, s29
	s_nop 0
	global_load_lds_dwordx4 v[192:193], off
	s_waitcnt vmcnt(8)
	s_waitcnt lgkmcnt(0)
	s_barrier
	s_setprio 1
	s_waitcnt lgkmcnt(0)
	v_mfma_f32_16x16x32_bf16 v[62:65], v[140:143], v[176:179], v[62:65]
	v_mfma_f32_16x16x32_bf16 v[58:61], v[148:151], v[176:179], v[58:61]
	v_mfma_f32_16x16x32_bf16 v[54:57], v[140:143], v[184:187], v[54:57]
	v_mfma_f32_16x16x32_bf16 v[46:49], v[148:151], v[184:187], v[46:49]
	v_mfma_f32_16x16x32_bf16 v[38:41], v[140:143], v[206:209], v[38:41]
	v_mfma_f32_16x16x32_bf16 v[30:33], v[148:151], v[206:209], v[30:33]
	v_mfma_f32_16x16x32_bf16 v[22:25], v[140:143], v[214:217], v[22:25]
	v_mfma_f32_16x16x32_bf16 v[14:17], v[148:151], v[214:217], v[14:17]
	v_mfma_f32_16x16x32_bf16 v[62:65], v[144:147], v[180:183], v[62:65]
	v_mfma_f32_16x16x32_bf16 v[58:61], v[156:159], v[180:183], v[58:61]
	v_mfma_f32_16x16x32_bf16 v[54:57], v[144:147], v[188:191], v[54:57]
	v_mfma_f32_16x16x32_bf16 v[46:49], v[156:159], v[188:191], v[46:49]
	v_mfma_f32_16x16x32_bf16 v[38:41], v[144:147], v[210:213], v[38:41]
	v_mfma_f32_16x16x32_bf16 v[30:33], v[156:159], v[210:213], v[30:33]
	v_mfma_f32_16x16x32_bf16 v[22:25], v[144:147], v[218:221], v[22:25]
	s_add_i32 s39, s39, 2
	v_mfma_f32_16x16x32_bf16 v[14:17], v[156:159], v[218:221], v[14:17]
	s_add_u32 s0, s0, 0x800000
	s_setprio 0
	s_setprio 1
	v_mfma_f32_16x16x32_bf16 v[50:53], v[160:163], v[176:179], v[50:53]
	s_addc_u32 s1, s1, 0
	v_mfma_f32_16x16x32_bf16 v[42:45], v[168:171], v[176:179], v[42:45]
	s_add_u32 s37, s37, 0x100
	v_mfma_f32_16x16x32_bf16 v[34:37], v[160:163], v[184:187], v[34:37]
	s_addc_u32 s38, s38, 0
	v_mfma_f32_16x16x32_bf16 v[26:29], v[168:171], v[184:187], v[26:29]
	s_add_u32 s16, s0, 0x3fc000
	v_mfma_f32_16x16x32_bf16 v[18:21], v[160:163], v[206:209], v[18:21]
	s_addc_u32 s17, s1, 0
	v_mfma_f32_16x16x32_bf16 v[10:13], v[168:171], v[206:209], v[10:13]
	s_cmp_eq_u32 s39, 40
	v_mfma_f32_16x16x32_bf16 v[6:9], v[160:163], v[214:217], v[6:9]
	s_cselect_b32 s20, s36, s16
	v_mfma_f32_16x16x32_bf16 v[2:5], v[168:171], v[214:217], v[2:5]
	s_cselect_b32 s21, s11, s17
	v_mfma_f32_16x16x32_bf16 v[50:53], v[164:167], v[180:183], v[50:53]
	s_cselect_b32 s18, s12, s37
	v_mfma_f32_16x16x32_bf16 v[42:45], v[172:175], v[180:183], v[42:45]
	s_cselect_b32 s19, s13, s38
	v_mfma_f32_16x16x32_bf16 v[34:37], v[164:167], v[188:191], v[34:37]
	s_add_u32 s16, s20, 0x400000
	v_mfma_f32_16x16x32_bf16 v[26:29], v[172:175], v[188:191], v[26:29]
	s_addc_u32 s17, s21, 0
	v_mfma_f32_16x16x32_bf16 v[18:21], v[164:167], v[210:213], v[18:21]
	s_add_i32 s40, 0, 0x10000
	v_mfma_f32_16x16x32_bf16 v[10:13], v[172:175], v[210:213], v[10:13]
	s_add_i32 s42, 0, 0x14000
	v_mfma_f32_16x16x32_bf16 v[6:9], v[164:167], v[218:221], v[6:9]
	s_cmp_gt_u32 s39, 41
	v_mfma_f32_16x16x32_bf16 v[2:5], v[172:175], v[218:221], v[2:5]
	s_setprio 0
	s_barrier
	s_cbranch_scc0 .LBB0_35
	s_and_b64 vcc, exec, s[8:9]
	s_cbranch_vccz .LBB0_38
	s_barrier

; #define PG8_STAGE(bufoff, gbase, voff) do { _Pragma("unroll") for (int _i = 0; _i < 2; ++_i) \
;         __builtin_amdgcn_global_load_lds((const unsigned*)((const char*)(gbase) + (voff)[_i]), (PG8_LAS unsigned*)(lds + (bufoff) + ldsw + _i * 8192), 16, 0, 0); } while (0)
; #define PG8_LDA(dst, b, h) do { _Pragma("unroll") for (int m = 0; m < 4; ++m) _Pragma("unroll") for (int k = 0; k < 2; ++k) dst[m][k] = *(const PG8_LAS bf16x8*)(lds + PG8_SA(b, h) + aoff + m * 2048 + k * 1024); } while (0)
; #define PG8_LDB(dst, b, h) do { _Pragma("unroll") for (int n = 0; n < 2; ++n) _Pragma("unroll") for (int k = 0; k < 2; ++k) dst[n][k] = *(const PG8_LAS bf16x8*)(lds + PG8_SB(b, h) + boff + n * 2048 + k * 1024); } while (0)
; #define PG8_WAIT_V(n) asm volatile("s_waitcnt vmcnt(" #n ")" ::: "memory")
; #define PG8_WAIT_L(n) asm volatile("s_waitcnt lgkmcnt(" #n ")" ::: "memory")
; #define PG8_BAR __builtin_amdgcn_s_barrier()
; #define PG8_SCHED __builtin_amdgcn_sched_barrier(0)
; template <class Epi, class Sched, bool ALIGN_EPI = false, bool SP2 = false>
; __device__ __forceinline__ void gemm_phase(PG8_LAS unsigned char* lds, const Gemm g, const Sched& S, const Epi& E) {
;     ...
;     for (;;) {
;         const bool has_next = S.next(ui + 1, nxt);
;         const char* nA = has_next ? (const char*)g.A + (size_t)nxt.pm * tstepA + (size_t)nxt.pn * pnoffA : cA; const char* nB = has_next ? (const char*)g.Bt + (size_t)nxt.pn * tstepB : cB;
;         for (int t = 0; t < nt; t += 2) {
;             const bool last = (t == nt - 2);
;             const char* a1 = cA + (size_t)(t + 1) * kstepA;
;             const char* a2 = last ? nA : cA + (size_t)(t + 2) * kstepA; const char* b2 = last ? nB : cB + (size_t)(t + 2) * kstep;
;             const char* a3 = a2 + kstepA; const char* b3 = b2 + kstep;
;             if (last && has_next) S.a_ready(nxt);
;             if constexpr (SP2) {
;             PG8_LDB(B0, 0, 0); PG8_LDB(B1, 0, 1); PG8_SCHED; PG8_LDA(At, 0, 0); PG8_STAGE(PG8_SA(1, 1), a1 + hstepA, voffA);
;             PG8_WAIT_V(8); PG8_WAIT_L(0); PG8_BAR; PG8_MMA(0, 0, At, B0); PG8_MMA(0, 1, At, B1); PG8_BAR; PG8_SCHED;
;             PG8_LDA(At, 0, 1); PG8_STAGE(PG8_SB(0, 0), b2, voffB); PG8_STAGE(PG8_SB(0, 1), b2 + hstepB, voffB); PG8_STAGE(PG8_SA(0, 0), a2, voffA);
;             PG8_WAIT_V(8); PG8_WAIT_L(0); PG8_BAR; PG8_MMA(1, 0, At, B0); PG8_MMA(1, 1, At, B1); PG8_BAR; PG8_SCHED;
.LBB0_52:
	s_ashr_i32 s11, s10, 31
	s_lshl_b64 s[12:13], s[10:11], 15
	s_add_u32 s12, s72, s12
	s_addc_u32 s13, s73, s13
	s_and_b64 s[14:15], s[4:5], exec
	s_cselect_b32 s11, s13, s17
	s_cselect_b32 s38, s12, s16
	s_ashr_i32 s9, s8, 31
	s_lshl_b64 s[14:15], s[8:9], 19
	s_add_u32 s14, s66, s14
	s_addc_u32 s15, s67, s15
	s_and_b64 s[20:21], s[4:5], exec
	s_cselect_b32 s9, s15, s19
	s_cselect_b32 s39, s14, s18
	s_add_u32 s40, s18, 0x100
	s_addc_u32 s41, s19, 0
	s_add_u32 s16, s16, 0x404000
	s_addc_u32 s17, s17, 0
	s_mov_b32 s42, -2
	s_add_u32 s18, s16, 0x3fc000
	s_addc_u32 s19, s17, 0
	s_cmp_eq_u32 s42, 12
	s_cselect_b32 s22, s38, s18
	s_cselect_b32 s23, s11, s19
	s_cselect_b32 s20, s39, s40
	s_cselect_b32 s21, s9, s41
	s_add_u32 s18, s22, 0x400000
	s_addc_u32 s19, s23, 0
	s_add_i32 s43, 0, 0x10000
	v_add_u32_e32 v149, s43, v147
	s_add_i32 s46, 0, 0x14000
	ds_read_b128 v[142:145], v149
	ds_read_b128 v[150:153], v149 offset:1024
	ds_read_b128 v[154:157], v149 offset:2048
	ds_read_b128 v[158:161], v149 offset:3072
	v_add_u32_e32 v149, s46, v147
	ds_read_b128 v[162:165], v149
	ds_read_b128 v[166:169], v149 offset:1024
	ds_read_b128 v[170:173], v149 offset:2048
	ds_read_b128 v[174:177], v149 offset:3072
	v_lshl_add_u64 v[222:223], s[16:17], 0, v[138:139]
	s_add_i32 m0, s26, 0xc000
	ds_read_b128 v[178:181], v148
	ds_read_b128 v[182:185], v148 offset:1024
	ds_read_b128 v[186:189], v148 offset:2048
	ds_read_b128 v[190:193], v148 offset:3072
	ds_read_b128 v[206:209], v148 offset:4096
	ds_read_b128 v[210:213], v148 offset:5120
	ds_read_b128 v[214:217], v148 offset:6144
	ds_read_b128 v[218:221], v148 offset:7168
	global_load_lds_dwordx4 v[222:223], off
	v_lshl_add_u64 v[222:223], s[16:17], 0, v[140:141]
	s_add_i32 m0, s26, 0xe000
	s_nop 0
	global_load_lds_dwordx4 v[222:223], off
	s_waitcnt vmcnt(8)
	s_waitcnt lgkmcnt(0)
	s_barrier
	s_setprio 1
	s_waitcnt lgkmcnt(0)
	v_mfma_f32_16x16x32_bf16 v[126:129], v[142:145], v[178:181], 0
	v_mfma_f32_16x16x32_bf16 v[122:125], v[154:157], v[178:181], 0
	v_mfma_f32_16x16x32_bf16 v[110:113], v[142:145], v[186:189], 0
	v_mfma_f32_16x16x32_bf16 v[106:109], v[154:157], v[186:189], 0
	v_mfma_f32_16x16x32_bf16 v[94:97], v[142:145], v[206:209], 0
	v_mfma_f32_16x16x32_bf16 v[90:93], v[154:157], v[206:209], 0
	v_mfma_f32_16x16x32_bf16 v[78:81], v[142:145], v[214:217], 0
	v_mfma_f32_16x16x32_bf16 v[74:77], v[154:157], v[214:217], 0
	v_mfma_f32_16x16x32_bf16 v[126:129], v[150:153], v[182:185], v[126:129]
	v_mfma_f32_16x16x32_bf16 v[122:125], v[158:161], v[182:185], v[122:125]
	v_mfma_f32_16x16x32_bf16 v[110:113], v[150:153], v[190:193], v[110:113]
	v_mfma_f32_16x16x32_bf16 v[106:109], v[158:161], v[190:193], v[106:109]
	v_mfma_f32_16x16x32_bf16 v[94:97], v[150:153], v[210:213], v[94:97]
	v_mfma_f32_16x16x32_bf16 v[90:93], v[158:161], v[210:213], v[90:93]
	v_mfma_f32_16x16x32_bf16 v[78:81], v[150:153], v[218:221], v[78:81]
	v_mfma_f32_16x16x32_bf16 v[74:77], v[158:161], v[218:221], v[74:77]
	s_setprio 0
	s_setprio 1
	v_mfma_f32_16x16x32_bf16 v[118:121], v[162:165], v[178:181], 0
	v_mfma_f32_16x16x32_bf16 v[114:117], v[170:173], v[178:181], 0
	v_mfma_f32_16x16x32_bf16 v[102:105], v[162:165], v[186:189], 0
	v_mfma_f32_16x16x32_bf16 v[98:101], v[170:173], v[186:189], 0
	v_mfma_f32_16x16x32_bf16 v[86:89], v[162:165], v[206:209], 0
	v_mfma_f32_16x16x32_bf16 v[82:85], v[170:173], v[206:209], 0
	v_mfma_f32_16x16x32_bf16 v[70:73], v[162:165], v[214:217], 0
	v_mfma_f32_16x16x32_bf16 v[66:69], v[170:173], v[214:217], 0
	v_mfma_f32_16x16x32_bf16 v[118:121], v[166:169], v[182:185], v[118:121]
	v_mfma_f32_16x16x32_bf16 v[114:117], v[174:177], v[182:185], v[114:117]
	v_mfma_f32_16x16x32_bf16 v[102:105], v[166:169], v[190:193], v[102:105]
	v_mfma_f32_16x16x32_bf16 v[98:101], v[174:177], v[190:193], v[98:101]
	v_mfma_f32_16x16x32_bf16 v[86:89], v[166:169], v[210:213], v[86:89]
	v_mfma_f32_16x16x32_bf16 v[82:85], v[174:177], v[210:213], v[82:85]
	v_mfma_f32_16x16x32_bf16 v[70:73], v[166:169], v[218:221], v[70:73]
	v_mfma_f32_16x16x32_bf16 v[66:69], v[174:177], v[218:221], v[66:69]
	s_setprio 0
	s_barrier
	s_add_i32 s43, s43, s25
	v_lshl_add_u64 v[222:223], s[20:21], 0, v[0:1]
	s_mov_b32 m0, s43
	ds_read_b128 v[178:181], v148 offset:16384
	ds_read_b128 v[182:185], v148 offset:17408
	ds_read_b128 v[186:189], v148 offset:18432
	ds_read_b128 v[190:193], v148 offset:19456
	ds_read_b128 v[206:209], v148 offset:20480
	ds_read_b128 v[210:213], v148 offset:21504
	ds_read_b128 v[214:217], v148 offset:22528
	ds_read_b128 v[218:221], v148 offset:23552
	global_load_lds_dwordx4 v[222:223], off
	s_add_i32 m0, s43, 0x2000
	s_add_u32 s44, s20, 0x40000
	v_lshl_add_u64 v[224:225], s[20:21], 0, v[130:131]
	s_addc_u32 s45, s21, 0
	s_add_i32 s43, s46, s25
	global_load_lds_dwordx4 v[224:225], off
	v_lshl_add_u64 v[226:227], s[44:45], 0, v[0:1]
	s_mov_b32 m0, s43
	s_nop 0
	global_load_lds_dwordx4 v[226:227], off
	v_lshl_add_u64 v[226:227], s[44:45], 0, v[130:131]
	s_add_i32 m0, s43, 0x2000
	s_nop 0
	global_load_lds_dwordx4 v[226:227], off
	v_lshl_add_u64 v[226:227], s[22:23], 0, v[134:135]
	s_mov_b32 m0, s26
	s_nop 0
	global_load_lds_dwordx4 v[226:227], off
	v_lshl_add_u64 v[226:227], s[22:23], 0, v[132:133]
	s_mov_b32 m0, s27
	s_nop 0
	global_load_lds_dwordx4 v[226:227], off
	s_waitcnt vmcnt(8)
	s_waitcnt lgkmcnt(0)
	s_barrier
; #define PG8_STAGE(bufoff, gbase, voff) do { _Pragma("unroll") for (int _i = 0; _i < 2; ++_i) \
;         __builtin_amdgcn_global_load_lds((const unsigned*)((const char*)(gbase) + (voff)[_i]), (PG8_LAS unsigned*)(lds + (bufoff) + ldsw + _i * 8192), 16, 0, 0); } while (0)
; #define PG8_LDA(dst, b, h) do { _Pragma("unroll") for (int m = 0; m < 4; ++m) _Pragma("unroll") for (int k = 0; k < 2; ++k) dst[m][k] = *(const PG8_LAS bf16x8*)(lds + PG8_SA(b, h) + aoff + m * 2048 + k * 1024); } while (0)
; #define PG8_LDB(dst, b, h) do { _Pragma("unroll") for (int n = 0; n < 2; ++n) _Pragma("unroll") for (int k = 0; k < 2; ++k) dst[n][k] = *(const PG8_LAS bf16x8*)(lds + PG8_SB(b, h) + boff + n * 2048 + k * 1024); } while (0)
; #define PG8_MMA(ai, bj, At, Bt) do { __builtin_amdgcn_s_setprio(1); _Pragma("unroll") for (int m = 0; m < 4; ++m) _Pragma("unroll") for (int n = 0; n < 2; ++n) _Pragma("unroll") for (int k = 0; k < 2; ++k) \
;         acc[ai][bj][m][n] = __builtin_amdgcn_mfma_f32_16x16x32_bf16(Bt[n][k], At[m][k], acc[ai][bj][m][n], 0, 0, 0); __builtin_amdgcn_s_setprio(0); } while (0)
; #define PG8_WAIT_V(n) asm volatile("s_waitcnt vmcnt(" #n ")" ::: "memory")
; #define PG8_WAIT_L(n) asm volatile("s_waitcnt lgkmcnt(" #n ")" ::: "memory")
; #define PG8_BAR __builtin_amdgcn_s_barrier()
; #define PG8_SCHED __builtin_amdgcn_sched_barrier(0)
; template <class Epi, class Sched, bool ALIGN_EPI = false, bool SP2 = false>
; __device__ __forceinline__ void gemm_phase(PG8_LAS unsigned char* lds, const Gemm g, const Sched& S, const Epi& E) {
;     ...
;             PG8_WAIT_V(8); PG8_WAIT_L(0); PG8_BAR; PG8_MMA(1, 0, At, B0); PG8_MMA(1, 1, At, B1); PG8_BAR; PG8_SCHED;
;             PG8_LDB(B0, 1, 0); PG8_LDB(B1, 1, 1); PG8_SCHED; PG8_LDA(At, 1, 0); PG8_STAGE(PG8_SA(0, 1), a2 + hstepA, voffA);
;             PG8_WAIT_V(8); PG8_WAIT_L(0); PG8_BAR; PG8_MMA(0, 0, At, B0); PG8_MMA(0, 1, At, B1); PG8_BAR; PG8_SCHED;
	s_setprio 1
	s_waitcnt lgkmcnt(0)
	v_mfma_f32_16x16x32_bf16 v[62:65], v[142:145], v[178:181], 0
	v_mfma_f32_16x16x32_bf16 v[58:61], v[154:157], v[178:181], 0
	v_mfma_f32_16x16x32_bf16 v[46:49], v[142:145], v[186:189], 0
	v_mfma_f32_16x16x32_bf16 v[42:45], v[154:157], v[186:189], 0
	v_mfma_f32_16x16x32_bf16 v[30:33], v[142:145], v[206:209], 0
	v_mfma_f32_16x16x32_bf16 v[26:29], v[154:157], v[206:209], 0
	v_mfma_f32_16x16x32_bf16 v[14:17], v[142:145], v[214:217], 0
	v_mfma_f32_16x16x32_bf16 v[10:13], v[154:157], v[214:217], 0
	v_mfma_f32_16x16x32_bf16 v[62:65], v[150:153], v[182:185], v[62:65]
	v_mfma_f32_16x16x32_bf16 v[58:61], v[158:161], v[182:185], v[58:61]
	v_mfma_f32_16x16x32_bf16 v[46:49], v[150:153], v[190:193], v[46:49]
	v_mfma_f32_16x16x32_bf16 v[42:45], v[158:161], v[190:193], v[42:45]
	v_mfma_f32_16x16x32_bf16 v[30:33], v[150:153], v[210:213], v[30:33]
	v_mfma_f32_16x16x32_bf16 v[26:29], v[158:161], v[210:213], v[26:29]
	v_mfma_f32_16x16x32_bf16 v[14:17], v[150:153], v[218:221], v[14:17]
	v_mfma_f32_16x16x32_bf16 v[10:13], v[158:161], v[218:221], v[10:13]
	s_setprio 0
	s_setprio 1
	v_mfma_f32_16x16x32_bf16 v[54:57], v[162:165], v[178:181], 0
	v_mfma_f32_16x16x32_bf16 v[50:53], v[170:173], v[178:181], 0
	v_mfma_f32_16x16x32_bf16 v[38:41], v[162:165], v[186:189], 0
	v_mfma_f32_16x16x32_bf16 v[34:37], v[170:173], v[186:189], 0
	v_mfma_f32_16x16x32_bf16 v[22:25], v[162:165], v[206:209], 0
	v_mfma_f32_16x16x32_bf16 v[18:21], v[170:173], v[206:209], 0
	v_mfma_f32_16x16x32_bf16 v[6:9], v[162:165], v[214:217], 0
	v_mfma_f32_16x16x32_bf16 v[2:5], v[170:173], v[214:217], 0
	v_mfma_f32_16x16x32_bf16 v[54:57], v[166:169], v[182:185], v[54:57]
	v_mfma_f32_16x16x32_bf16 v[50:53], v[174:177], v[182:185], v[50:53]
	v_mfma_f32_16x16x32_bf16 v[38:41], v[166:169], v[190:193], v[38:41]
	v_mfma_f32_16x16x32_bf16 v[34:37], v[174:177], v[190:193], v[34:37]
	v_mfma_f32_16x16x32_bf16 v[22:25], v[166:169], v[210:213], v[22:25]
	v_mfma_f32_16x16x32_bf16 v[18:21], v[174:177], v[210:213], v[18:21]
	v_mfma_f32_16x16x32_bf16 v[6:9], v[166:169], v[218:221], v[6:9]
	v_mfma_f32_16x16x32_bf16 v[2:5], v[174:177], v[218:221], v[2:5]
	s_setprio 0
	s_barrier
	s_add_i32 s43, 0, 0x18000
	v_add_u32_e32 v149, s43, v147
	s_add_i32 s44, 0, 0x1c000
	ds_read_b128 v[142:145], v149
	ds_read_b128 v[150:153], v149 offset:1024
	ds_read_b128 v[154:157], v149 offset:2048
	ds_read_b128 v[158:161], v149 offset:3072
	v_add_u32_e32 v149, s44, v147
	ds_read_b128 v[162:165], v149
	ds_read_b128 v[166:169], v149 offset:1024
	ds_read_b128 v[170:173], v149 offset:2048
	ds_read_b128 v[174:177], v149 offset:3072
	s_add_u32 s22, s22, 0x4000
	s_addc_u32 s23, s23, 0
	s_mov_b32 m0, s28
	v_lshl_add_u64 v[226:227], s[22:23], 0, v[134:135]
	ds_read_b128 v[178:181], v148 offset:32768
	ds_read_b128 v[182:185], v148 offset:33792
	ds_read_b128 v[186:189], v148 offset:34816
	ds_read_b128 v[190:193], v148 offset:35840
	ds_read_b128 v[206:209], v148 offset:36864
	ds_read_b128 v[210:213], v148 offset:37888
	ds_read_b128 v[214:217], v148 offset:38912
	ds_read_b128 v[218:221], v148 offset:39936
	global_load_lds_dwordx4 v[226:227], off
	v_lshl_add_u64 v[226:227], s[22:23], 0, v[132:133]
	s_mov_b32 m0, s29
	s_nop 0
	global_load_lds_dwordx4 v[226:227], off
	s_waitcnt vmcnt(8)
	s_waitcnt lgkmcnt(0)
	s_barrier
	s_setprio 1
	s_waitcnt lgkmcnt(0)
	v_mfma_f32_16x16x32_bf16 v[126:129], v[142:145], v[178:181], v[126:129]
	v_mfma_f32_16x16x32_bf16 v[122:125], v[154:157], v[178:181], v[122:125]
	v_mfma_f32_16x16x32_bf16 v[110:113], v[142:145], v[186:189], v[110:113]
	v_mfma_f32_16x16x32_bf16 v[106:109], v[154:157], v[186:189], v[106:109]
	v_mfma_f32_16x16x32_bf16 v[94:97], v[142:145], v[206:209], v[94:97]
	v_mfma_f32_16x16x32_bf16 v[90:93], v[154:157], v[206:209], v[90:93]
	v_mfma_f32_16x16x32_bf16 v[78:81], v[142:145], v[214:217], v[78:81]
	v_mfma_f32_16x16x32_bf16 v[74:77], v[154:157], v[214:217], v[74:77]
	v_mfma_f32_16x16x32_bf16 v[126:129], v[150:153], v[182:185], v[126:129]
	v_mfma_f32_16x16x32_bf16 v[122:125], v[158:161], v[182:185], v[122:125]
	v_mfma_f32_16x16x32_bf16 v[110:113], v[150:153], v[190:193], v[110:113]
	v_mfma_f32_16x16x32_bf16 v[106:109], v[158:161], v[190:193], v[106:109]
	v_mfma_f32_16x16x32_bf16 v[94:97], v[150:153], v[210:213], v[94:97]
	v_mfma_f32_16x16x32_bf16 v[90:93], v[158:161], v[210:213], v[90:93]
	v_mfma_f32_16x16x32_bf16 v[78:81], v[150:153], v[218:221], v[78:81]
	v_mfma_f32_16x16x32_bf16 v[74:77], v[158:161], v[218:221], v[74:77]
	s_setprio 0
	s_setprio 1
	v_mfma_f32_16x16x32_bf16 v[118:121], v[162:165], v[178:181], v[118:121]
	v_mfma_f32_16x16x32_bf16 v[114:117], v[170:173], v[178:181], v[114:117]
	v_mfma_f32_16x16x32_bf16 v[102:105], v[162:165], v[186:189], v[102:105]
	v_mfma_f32_16x16x32_bf16 v[98:101], v[170:173], v[186:189], v[98:101]
	v_mfma_f32_16x16x32_bf16 v[86:89], v[162:165], v[206:209], v[86:89]
	v_mfma_f32_16x16x32_bf16 v[82:85], v[170:173], v[206:209], v[82:85]
	v_mfma_f32_16x16x32_bf16 v[70:73], v[162:165], v[214:217], v[70:73]
	v_mfma_f32_16x16x32_bf16 v[66:69], v[170:173], v[214:217], v[66:69]
	v_mfma_f32_16x16x32_bf16 v[118:121], v[166:169], v[182:185], v[118:121]
	v_mfma_f32_16x16x32_bf16 v[114:117], v[174:177], v[182:185], v[114:117]
	v_mfma_f32_16x16x32_bf16 v[102:105], v[166:169], v[190:193], v[102:105]
	v_mfma_f32_16x16x32_bf16 v[98:101], v[174:177], v[190:193], v[98:101]
	v_mfma_f32_16x16x32_bf16 v[86:89], v[166:169], v[210:213], v[86:89]
	v_mfma_f32_16x16x32_bf16 v[82:85], v[174:177], v[210:213], v[82:85]
	v_mfma_f32_16x16x32_bf16 v[70:73], v[166:169], v[218:221], v[70:73]
	v_mfma_f32_16x16x32_bf16 v[66:69], v[174:177], v[218:221], v[66:69]
	s_setprio 0
	s_barrier
; #define PG8_STAGE(bufoff, gbase, voff) do { _Pragma("unroll") for (int _i = 0; _i < 2; ++_i) \
;         __builtin_amdgcn_global_load_lds((const unsigned*)((const char*)(gbase) + (voff)[_i]), (PG8_LAS unsigned*)(lds + (bufoff) + ldsw + _i * 8192), 16, 0, 0); } while (0)
; #define PG8_LDA(dst, b, h) do { _Pragma("unroll") for (int m = 0; m < 4; ++m) _Pragma("unroll") for (int k = 0; k < 2; ++k) dst[m][k] = *(const PG8_LAS bf16x8*)(lds + PG8_SA(b, h) + aoff + m * 2048 + k * 1024); } while (0)
; #define PG8_LDB(dst, b, h) do { _Pragma("unroll") for (int n = 0; n < 2; ++n) _Pragma("unroll") for (int k = 0; k < 2; ++k) dst[n][k] = *(const PG8_LAS bf16x8*)(lds + PG8_SB(b, h) + boff + n * 2048 + k * 1024); } while (0)
; template <class Epi, class Sched, bool ALIGN_EPI = false, bool SP2 = false>
; __device__ __forceinline__ void gemm_phase(PG8_LAS unsigned char* lds, const Gemm g, const Sched& S, const Epi& E) {
;     ...
;         for (int t = 0; t < nt; t += 2) {
;             const bool last = (t == nt - 2);
;             const char* a1 = cA + (size_t)(t + 1) * kstepA;
;             const char* a2 = last ? nA : cA + (size_t)(t + 2) * kstepA; const char* b2 = last ? nB : cB + (size_t)(t + 2) * kstep;
;             const char* a3 = a2 + kstepA; const char* b3 = b2 + kstep;
;             if (last && has_next) S.a_ready(nxt);
;             if constexpr (SP2) {
;             PG8_LDB(B0, 0, 0); PG8_LDB(B1, 0, 1); PG8_SCHED; PG8_LDA(At, 0, 0); PG8_STAGE(PG8_SA(1, 1), a1 + hstepA, voffA);
;             PG8_WAIT_V(8); PG8_WAIT_L(0); PG8_BAR; PG8_MMA(0, 0, At, B0); PG8_MMA(0, 1, At, B1); PG8_BAR; PG8_SCHED;
;             PG8_LDA(At, 0, 1); PG8_STAGE(PG8_SB(0, 0), b2, voffB); PG8_STAGE(PG8_SB(0, 1), b2 + hstepB, voffB); PG8_STAGE(PG8_SA(0, 0), a2, voffA);
;             PG8_WAIT_V(8); PG8_WAIT_L(0); PG8_BAR; PG8_MMA(1, 0, At, B0); PG8_MMA(1, 1, At, B1); PG8_BAR; PG8_SCHED;
;             PG8_LDB(B0, 1, 0); PG8_LDB(B1, 1, 1); PG8_SCHED; PG8_LDA(At, 1, 0); PG8_STAGE(PG8_SA(0, 1), a2 + hstepA, voffA);
;             PG8_WAIT_V(8); PG8_WAIT_L(0); PG8_BAR; PG8_MMA(0, 0, At, B0); PG8_MMA(0, 1, At, B1); PG8_BAR; PG8_SCHED;
;             PG8_LDA(At, 1, 1); PG8_STAGE(PG8_SB(1, 0), b3, voffB); PG8_STAGE(PG8_SB(1, 1), b3 + hstepB, voffB); PG8_STAGE(PG8_SA(1, 0), a3, voffA);
;             PG8_WAIT_V(8); PG8_WAIT_L(0); PG8_BAR; PG8_MMA(1, 0, At, B0); PG8_MMA(1, 1, At, B1); PG8_BAR; PG8_SCHED;
	s_add_i32 s22, s43, s25
	v_lshl_add_u64 v[222:223], v[222:223], 0, s[78:79]
	s_mov_b32 m0, s22
	ds_read_b128 v[178:181], v148 offset:49152
	ds_read_b128 v[182:185], v148 offset:50176
	ds_read_b128 v[186:189], v148 offset:51200
	ds_read_b128 v[190:193], v148 offset:52224
	ds_read_b128 v[206:209], v148 offset:53248
	ds_read_b128 v[210:213], v148 offset:54272
	ds_read_b128 v[214:217], v148 offset:55296
	ds_read_b128 v[218:221], v148 offset:56320
	global_load_lds_dwordx4 v[222:223], off
	s_add_i32 m0, s22, 0x2000
	s_add_u32 s20, s20, 0x40080
	v_lshl_add_u64 v[222:223], v[224:225], 0, s[78:79]
	s_addc_u32 s21, s21, 0
	s_add_i32 s22, s44, s25
	global_load_lds_dwordx4 v[222:223], off
	v_lshl_add_u64 v[222:223], s[20:21], 0, v[0:1]
	s_mov_b32 m0, s22
	s_nop 0
	global_load_lds_dwordx4 v[222:223], off
	v_lshl_add_u64 v[222:223], s[20:21], 0, v[130:131]
	s_add_i32 m0, s22, 0x2000
	s_nop 0
	global_load_lds_dwordx4 v[222:223], off
	v_lshl_add_u64 v[222:223], s[18:19], 0, v[134:135]
	s_mov_b32 m0, s30
	s_nop 0
	global_load_lds_dwordx4 v[222:223], off
	v_lshl_add_u64 v[222:223], s[18:19], 0, v[132:133]
	s_mov_b32 m0, s31
	s_nop 0
	global_load_lds_dwordx4 v[222:223], off
	s_waitcnt vmcnt(8)
	s_waitcnt lgkmcnt(0)
	s_barrier
	s_setprio 1
	s_waitcnt lgkmcnt(0)
	v_mfma_f32_16x16x32_bf16 v[62:65], v[142:145], v[178:181], v[62:65]
	v_mfma_f32_16x16x32_bf16 v[58:61], v[154:157], v[178:181], v[58:61]
	v_mfma_f32_16x16x32_bf16 v[46:49], v[142:145], v[186:189], v[46:49]
	v_mfma_f32_16x16x32_bf16 v[42:45], v[154:157], v[186:189], v[42:45]
	v_mfma_f32_16x16x32_bf16 v[30:33], v[142:145], v[206:209], v[30:33]
	v_mfma_f32_16x16x32_bf16 v[26:29], v[154:157], v[206:209], v[26:29]
	v_mfma_f32_16x16x32_bf16 v[14:17], v[142:145], v[214:217], v[14:17]
	v_mfma_f32_16x16x32_bf16 v[10:13], v[154:157], v[214:217], v[10:13]
	v_mfma_f32_16x16x32_bf16 v[62:65], v[150:153], v[182:185], v[62:65]
	v_mfma_f32_16x16x32_bf16 v[58:61], v[158:161], v[182:185], v[58:61]
	v_mfma_f32_16x16x32_bf16 v[46:49], v[150:153], v[190:193], v[46:49]
	v_mfma_f32_16x16x32_bf16 v[42:45], v[158:161], v[190:193], v[42:45]
	v_mfma_f32_16x16x32_bf16 v[30:33], v[150:153], v[210:213], v[30:33]
	v_mfma_f32_16x16x32_bf16 v[26:29], v[158:161], v[210:213], v[26:29]
	v_mfma_f32_16x16x32_bf16 v[14:17], v[150:153], v[218:221], v[14:17]
	v_mfma_f32_16x16x32_bf16 v[10:13], v[158:161], v[218:221], v[10:13]
	s_setprio 0
	s_setprio 1
	v_mfma_f32_16x16x32_bf16 v[54:57], v[162:165], v[178:181], v[54:57]
	s_add_i32 s42, s42, 2
	v_mfma_f32_16x16x32_bf16 v[50:53], v[170:173], v[178:181], v[50:53]
	s_add_u32 s40, s40, 0x100
	v_mfma_f32_16x16x32_bf16 v[38:41], v[162:165], v[186:189], v[38:41]
	s_addc_u32 s41, s41, 0
	v_mfma_f32_16x16x32_bf16 v[34:37], v[170:173], v[186:189], v[34:37]
	s_add_u32 s16, s16, 0x800000
	v_mfma_f32_16x16x32_bf16 v[22:25], v[162:165], v[206:209], v[22:25]
	s_addc_u32 s17, s17, 0
	v_mfma_f32_16x16x32_bf16 v[18:21], v[170:173], v[206:209], v[18:21]
	s_add_u32 s18, s16, 0x3fc000
	v_mfma_f32_16x16x32_bf16 v[6:9], v[162:165], v[214:217], v[6:9]
	s_addc_u32 s19, s17, 0
	v_mfma_f32_16x16x32_bf16 v[2:5], v[170:173], v[214:217], v[2:5]
	s_cmp_eq_u32 s42, 12
	v_mfma_f32_16x16x32_bf16 v[54:57], v[166:169], v[182:185], v[54:57]
	s_cselect_b32 s22, s38, s18
	v_mfma_f32_16x16x32_bf16 v[50:53], v[174:177], v[182:185], v[50:53]
	s_cselect_b32 s23, s11, s19
	v_mfma_f32_16x16x32_bf16 v[38:41], v[166:169], v[190:193], v[38:41]
	s_cselect_b32 s20, s39, s40
	v_mfma_f32_16x16x32_bf16 v[34:37], v[174:177], v[190:193], v[34:37]
	s_cselect_b32 s21, s9, s41
	v_mfma_f32_16x16x32_bf16 v[22:25], v[166:169], v[210:213], v[22:25]
	s_add_u32 s18, s22, 0x400000
	v_mfma_f32_16x16x32_bf16 v[18:21], v[174:177], v[210:213], v[18:21]
	s_addc_u32 s19, s23, 0
	v_mfma_f32_16x16x32_bf16 v[6:9], v[166:169], v[218:221], v[6:9]
	s_add_i32 s43, 0, 0x10000
	v_mfma_f32_16x16x32_bf16 v[2:5], v[174:177], v[218:221], v[2:5]
	s_setprio 0
	s_barrier
.LBB0_53:
	v_add_u32_e32 v149, s43, v147
	s_add_i32 s46, 0, 0x14000
	ds_read_b128 v[142:145], v149
	ds_read_b128 v[150:153], v149 offset:1024
	ds_read_b128 v[154:157], v149 offset:2048
	ds_read_b128 v[158:161], v149 offset:3072
	v_add_u32_e32 v149, s46, v147
	ds_read_b128 v[162:165], v149
	ds_read_b128 v[166:169], v149 offset:1024
	ds_read_b128 v[170:173], v149 offset:2048
	ds_read_b128 v[174:177], v149 offset:3072
	v_lshl_add_u64 v[222:223], s[16:17], 0, v[138:139]
	s_add_i32 m0, s26, 0xc000
	ds_read_b128 v[178:181], v148
	ds_read_b128 v[182:185], v148 offset:1024
	ds_read_b128 v[186:189], v148 offset:2048
	ds_read_b128 v[190:193], v148 offset:3072
	ds_read_b128 v[206:209], v148 offset:4096
	ds_read_b128 v[210:213], v148 offset:5120
	ds_read_b128 v[214:217], v148 offset:6144
	ds_read_b128 v[218:221], v148 offset:7168
	global_load_lds_dwordx4 v[222:223], off
	v_lshl_add_u64 v[222:223], s[16:17], 0, v[140:141]
	s_add_i32 m0, s26, 0xe000
	s_nop 0
	global_load_lds_dwordx4 v[222:223], off
	s_waitcnt vmcnt(8)
	s_waitcnt lgkmcnt(0)
	s_barrier
; #define PG8_STAGE(bufoff, gbase, voff) do { _Pragma("unroll") for (int _i = 0; _i < 2; ++_i) \
;         __builtin_amdgcn_global_load_lds((const unsigned*)((const char*)(gbase) + (voff)[_i]), (PG8_LAS unsigned*)(lds + (bufoff) + ldsw + _i * 8192), 16, 0, 0); } while (0)
; #define PG8_LDA(dst, b, h) do { _Pragma("unroll") for (int m = 0; m < 4; ++m) _Pragma("unroll") for (int k = 0; k < 2; ++k) dst[m][k] = *(const PG8_LAS bf16x8*)(lds + PG8_SA(b, h) + aoff + m * 2048 + k * 1024); } while (0)
; #define PG8_MMA(ai, bj, At, Bt) do { __builtin_amdgcn_s_setprio(1); _Pragma("unroll") for (int m = 0; m < 4; ++m) _Pragma("unroll") for (int n = 0; n < 2; ++n) _Pragma("unroll") for (int k = 0; k < 2; ++k) \
;         acc[ai][bj][m][n] = __builtin_amdgcn_mfma_f32_16x16x32_bf16(Bt[n][k], At[m][k], acc[ai][bj][m][n], 0, 0, 0); __builtin_amdgcn_s_setprio(0); } while (0)
; #define PG8_WAIT_V(n) asm volatile("s_waitcnt vmcnt(" #n ")" ::: "memory")
; #define PG8_WAIT_L(n) asm volatile("s_waitcnt lgkmcnt(" #n ")" ::: "memory")
; #define PG8_BAR __builtin_amdgcn_s_barrier()
; #define PG8_SCHED __builtin_amdgcn_sched_barrier(0)
; template <class Epi, class Sched, bool ALIGN_EPI = false, bool SP2 = false>
; __device__ __forceinline__ void gemm_phase(PG8_LAS unsigned char* lds, const Gemm g, const Sched& S, const Epi& E) {
;     ...
;             PG8_WAIT_V(8); PG8_WAIT_L(0); PG8_BAR; PG8_MMA(0, 0, At, B0); PG8_MMA(0, 1, At, B1); PG8_BAR; PG8_SCHED;
;             PG8_LDA(At, 0, 1); PG8_STAGE(PG8_SB(0, 0), b2, voffB); PG8_STAGE(PG8_SB(0, 1), b2 + hstepB, voffB); PG8_STAGE(PG8_SA(0, 0), a2, voffA);
;             PG8_WAIT_V(8); PG8_WAIT_L(0); PG8_BAR; PG8_MMA(1, 0, At, B0); PG8_MMA(1, 1, At, B1); PG8_BAR; PG8_SCHED;
	s_setprio 1
	s_waitcnt lgkmcnt(0)
	v_mfma_f32_16x16x32_bf16 v[126:129], v[142:145], v[178:181], v[126:129]
	v_mfma_f32_16x16x32_bf16 v[122:125], v[154:157], v[178:181], v[122:125]
	v_mfma_f32_16x16x32_bf16 v[110:113], v[142:145], v[186:189], v[110:113]
	v_mfma_f32_16x16x32_bf16 v[106:109], v[154:157], v[186:189], v[106:109]
	v_mfma_f32_16x16x32_bf16 v[94:97], v[142:145], v[206:209], v[94:97]
	v_mfma_f32_16x16x32_bf16 v[90:93], v[154:157], v[206:209], v[90:93]
	v_mfma_f32_16x16x32_bf16 v[78:81], v[142:145], v[214:217], v[78:81]
	v_mfma_f32_16x16x32_bf16 v[74:77], v[154:157], v[214:217], v[74:77]
	v_mfma_f32_16x16x32_bf16 v[126:129], v[150:153], v[182:185], v[126:129]
	v_mfma_f32_16x16x32_bf16 v[122:125], v[158:161], v[182:185], v[122:125]
	v_mfma_f32_16x16x32_bf16 v[110:113], v[150:153], v[190:193], v[110:113]
	v_mfma_f32_16x16x32_bf16 v[106:109], v[158:161], v[190:193], v[106:109]
	v_mfma_f32_16x16x32_bf16 v[94:97], v[150:153], v[210:213], v[94:97]
	v_mfma_f32_16x16x32_bf16 v[90:93], v[158:161], v[210:213], v[90:93]
	v_mfma_f32_16x16x32_bf16 v[78:81], v[150:153], v[218:221], v[78:81]
	v_mfma_f32_16x16x32_bf16 v[74:77], v[158:161], v[218:221], v[74:77]
	s_setprio 0
	s_setprio 1
	v_mfma_f32_16x16x32_bf16 v[118:121], v[162:165], v[178:181], v[118:121]
	v_mfma_f32_16x16x32_bf16 v[114:117], v[170:173], v[178:181], v[114:117]
	v_mfma_f32_16x16x32_bf16 v[102:105], v[162:165], v[186:189], v[102:105]
	v_mfma_f32_16x16x32_bf16 v[98:101], v[170:173], v[186:189], v[98:101]
	v_mfma_f32_16x16x32_bf16 v[86:89], v[162:165], v[206:209], v[86:89]
	v_mfma_f32_16x16x32_bf16 v[82:85], v[170:173], v[206:209], v[82:85]
	v_mfma_f32_16x16x32_bf16 v[70:73], v[162:165], v[214:217], v[70:73]
	v_mfma_f32_16x16x32_bf16 v[66:69], v[170:173], v[214:217], v[66:69]
	v_mfma_f32_16x16x32_bf16 v[118:121], v[166:169], v[182:185], v[118:121]
	v_mfma_f32_16x16x32_bf16 v[114:117], v[174:177], v[182:185], v[114:117]
	v_mfma_f32_16x16x32_bf16 v[102:105], v[166:169], v[190:193], v[102:105]
	v_mfma_f32_16x16x32_bf16 v[98:101], v[174:177], v[190:193], v[98:101]
	v_mfma_f32_16x16x32_bf16 v[86:89], v[166:169], v[210:213], v[86:89]
	v_mfma_f32_16x16x32_bf16 v[82:85], v[174:177], v[210:213], v[82:85]
	v_mfma_f32_16x16x32_bf16 v[70:73], v[166:169], v[218:221], v[70:73]
	v_mfma_f32_16x16x32_bf16 v[66:69], v[174:177], v[218:221], v[66:69]
	s_setprio 0
	s_barrier
	s_add_i32 s43, s43, s25
	v_lshl_add_u64 v[222:223], s[20:21], 0, v[0:1]
	s_mov_b32 m0, s43
	ds_read_b128 v[178:181], v148 offset:16384
	ds_read_b128 v[182:185], v148 offset:17408
	ds_read_b128 v[186:189], v148 offset:18432
	ds_read_b128 v[190:193], v148 offset:19456
	ds_read_b128 v[206:209], v148 offset:20480
	ds_read_b128 v[210:213], v148 offset:21504
	ds_read_b128 v[214:217], v148 offset:22528
	ds_read_b128 v[218:221], v148 offset:23552
	global_load_lds_dwordx4 v[222:223], off
	s_add_i32 m0, s43, 0x2000
	s_add_u32 s44, s20, 0x40000
	v_lshl_add_u64 v[224:225], s[20:21], 0, v[130:131]
	s_addc_u32 s45, s21, 0
	s_add_i32 s43, s46, s25
	global_load_lds_dwordx4 v[224:225], off
	v_lshl_add_u64 v[226:227], s[44:45], 0, v[0:1]
	s_mov_b32 m0, s43
	s_nop 0
	global_load_lds_dwordx4 v[226:227], off
	v_lshl_add_u64 v[226:227], s[44:45], 0, v[130:131]
	s_add_i32 m0, s43, 0x2000
	s_nop 0
	global_load_lds_dwordx4 v[226:227], off
	v_lshl_add_u64 v[226:227], s[22:23], 0, v[134:135]
	s_mov_b32 m0, s26
	s_nop 0
	global_load_lds_dwordx4 v[226:227], off
	v_lshl_add_u64 v[226:227], s[22:23], 0, v[132:133]
	s_mov_b32 m0, s27
	s_nop 0
	global_load_lds_dwordx4 v[226:227], off
	s_waitcnt vmcnt(8)
	s_waitcnt lgkmcnt(0)
	s_barrier
	s_setprio 1
	s_waitcnt lgkmcnt(0)
	v_mfma_f32_16x16x32_bf16 v[62:65], v[142:145], v[178:181], v[62:65]
	v_mfma_f32_16x16x32_bf16 v[58:61], v[154:157], v[178:181], v[58:61]
	v_mfma_f32_16x16x32_bf16 v[46:49], v[142:145], v[186:189], v[46:49]
	v_mfma_f32_16x16x32_bf16 v[42:45], v[154:157], v[186:189], v[42:45]
	v_mfma_f32_16x16x32_bf16 v[30:33], v[142:145], v[206:209], v[30:33]
	v_mfma_f32_16x16x32_bf16 v[26:29], v[154:157], v[206:209], v[26:29]
	v_mfma_f32_16x16x32_bf16 v[14:17], v[142:145], v[214:217], v[14:17]
	v_mfma_f32_16x16x32_bf16 v[10:13], v[154:157], v[214:217], v[10:13]
	v_mfma_f32_16x16x32_bf16 v[62:65], v[150:153], v[182:185], v[62:65]
	v_mfma_f32_16x16x32_bf16 v[58:61], v[158:161], v[182:185], v[58:61]
	v_mfma_f32_16x16x32_bf16 v[46:49], v[150:153], v[190:193], v[46:49]
	v_mfma_f32_16x16x32_bf16 v[42:45], v[158:161], v[190:193], v[42:45]
	v_mfma_f32_16x16x32_bf16 v[30:33], v[150:153], v[210:213], v[30:33]
	v_mfma_f32_16x16x32_bf16 v[26:29], v[158:161], v[210:213], v[26:29]
	v_mfma_f32_16x16x32_bf16 v[14:17], v[150:153], v[218:221], v[14:17]
	v_mfma_f32_16x16x32_bf16 v[10:13], v[158:161], v[218:221], v[10:13]
	s_setprio 0
	s_setprio 1
	v_mfma_f32_16x16x32_bf16 v[54:57], v[162:165], v[178:181], v[54:57]
	v_mfma_f32_16x16x32_bf16 v[50:53], v[170:173], v[178:181], v[50:53]
	v_mfma_f32_16x16x32_bf16 v[38:41], v[162:165], v[186:189], v[38:41]
	v_mfma_f32_16x16x32_bf16 v[34:37], v[170:173], v[186:189], v[34:37]
	v_mfma_f32_16x16x32_bf16 v[22:25], v[162:165], v[206:209], v[22:25]
	v_mfma_f32_16x16x32_bf16 v[18:21], v[170:173], v[206:209], v[18:21]
	v_mfma_f32_16x16x32_bf16 v[6:9], v[162:165], v[214:217], v[6:9]
	v_mfma_f32_16x16x32_bf16 v[2:5], v[170:173], v[214:217], v[2:5]
	v_mfma_f32_16x16x32_bf16 v[54:57], v[166:169], v[182:185], v[54:57]
	v_mfma_f32_16x16x32_bf16 v[50:53], v[174:177], v[182:185], v[50:53]
	v_mfma_f32_16x16x32_bf16 v[38:41], v[166:169], v[190:193], v[38:41]
	v_mfma_f32_16x16x32_bf16 v[34:37], v[174:177], v[190:193], v[34:37]
	v_mfma_f32_16x16x32_bf16 v[22:25], v[166:169], v[210:213], v[22:25]
	v_mfma_f32_16x16x32_bf16 v[18:21], v[174:177], v[210:213], v[18:21]
	v_mfma_f32_16x16x32_bf16 v[6:9], v[166:169], v[218:221], v[6:9]
	v_mfma_f32_16x16x32_bf16 v[2:5], v[174:177], v[218:221], v[2:5]
	s_setprio 0
	s_barrier
; #define PG8_STAGE(bufoff, gbase, voff) do { _Pragma("unroll") for (int _i = 0; _i < 2; ++_i) \
;         __builtin_amdgcn_global_load_lds((const unsigned*)((const char*)(gbase) + (voff)[_i]), (PG8_LAS unsigned*)(lds + (bufoff) + ldsw + _i * 8192), 16, 0, 0); } while (0)
; #define PG8_LDA(dst, b, h) do { _Pragma("unroll") for (int m = 0; m < 4; ++m) _Pragma("unroll") for (int k = 0; k < 2; ++k) dst[m][k] = *(const PG8_LAS bf16x8*)(lds + PG8_SA(b, h) + aoff + m * 2048 + k * 1024); } while (0)
; #define PG8_LDB(dst, b, h) do { _Pragma("unroll") for (int n = 0; n < 2; ++n) _Pragma("unroll") for (int k = 0; k < 2; ++k) dst[n][k] = *(const PG8_LAS bf16x8*)(lds + PG8_SB(b, h) + boff + n * 2048 + k * 1024); } while (0)
; #define PG8_MMA(ai, bj, At, Bt) do { __builtin_amdgcn_s_setprio(1); _Pragma("unroll") for (int m = 0; m < 4; ++m) _Pragma("unroll") for (int n = 0; n < 2; ++n) _Pragma("unroll") for (int k = 0; k < 2; ++k) \
;         acc[ai][bj][m][n] = __builtin_amdgcn_mfma_f32_16x16x32_bf16(Bt[n][k], At[m][k], acc[ai][bj][m][n], 0, 0, 0); __builtin_amdgcn_s_setprio(0); } while (0)
; #define PG8_WAIT_V(n) asm volatile("s_waitcnt vmcnt(" #n ")" ::: "memory")
; #define PG8_WAIT_L(n) asm volatile("s_waitcnt lgkmcnt(" #n ")" ::: "memory")
; #define PG8_BAR __builtin_amdgcn_s_barrier()
; #define PG8_SCHED __builtin_amdgcn_sched_barrier(0)
; template <class Epi, class Sched, bool ALIGN_EPI = false, bool SP2 = false>
; __device__ __forceinline__ void gemm_phase(PG8_LAS unsigned char* lds, const Gemm g, const Sched& S, const Epi& E) {
;     ...
;             PG8_LDB(B0, 1, 0); PG8_LDB(B1, 1, 1); PG8_SCHED; PG8_LDA(At, 1, 0); PG8_STAGE(PG8_SA(0, 1), a2 + hstepA, voffA);
;             PG8_WAIT_V(8); PG8_WAIT_L(0); PG8_BAR; PG8_MMA(0, 0, At, B0); PG8_MMA(0, 1, At, B1); PG8_BAR; PG8_SCHED;
	s_add_i32 s43, 0, 0x18000
	v_add_u32_e32 v149, s43, v147
	s_add_i32 s44, 0, 0x1c000
	ds_read_b128 v[142:145], v149
	ds_read_b128 v[150:153], v149 offset:1024
	ds_read_b128 v[154:157], v149 offset:2048
	ds_read_b128 v[158:161], v149 offset:3072
	v_add_u32_e32 v149, s44, v147
	ds_read_b128 v[162:165], v149
	ds_read_b128 v[166:169], v149 offset:1024
	ds_read_b128 v[170:173], v149 offset:2048
	ds_read_b128 v[174:177], v149 offset:3072
	s_add_u32 s22, s22, 0x4000
	s_addc_u32 s23, s23, 0
	s_mov_b32 m0, s28
	v_lshl_add_u64 v[226:227], s[22:23], 0, v[134:135]
	ds_read_b128 v[178:181], v148 offset:32768
	ds_read_b128 v[182:185], v148 offset:33792
	ds_read_b128 v[186:189], v148 offset:34816
	ds_read_b128 v[190:193], v148 offset:35840
	ds_read_b128 v[206:209], v148 offset:36864
	ds_read_b128 v[210:213], v148 offset:37888
	ds_read_b128 v[214:217], v148 offset:38912
	ds_read_b128 v[218:221], v148 offset:39936
	global_load_lds_dwordx4 v[226:227], off
	v_lshl_add_u64 v[226:227], s[22:23], 0, v[132:133]
	s_mov_b32 m0, s29
	s_nop 0
	global_load_lds_dwordx4 v[226:227], off
	s_waitcnt vmcnt(8)
	s_waitcnt lgkmcnt(0)
	s_barrier
	s_setprio 1
	s_waitcnt lgkmcnt(0)
	v_mfma_f32_16x16x32_bf16 v[126:129], v[142:145], v[178:181], v[126:129]
	v_mfma_f32_16x16x32_bf16 v[122:125], v[154:157], v[178:181], v[122:125]
	v_mfma_f32_16x16x32_bf16 v[110:113], v[142:145], v[186:189], v[110:113]
	v_mfma_f32_16x16x32_bf16 v[106:109], v[154:157], v[186:189], v[106:109]
	v_mfma_f32_16x16x32_bf16 v[94:97], v[142:145], v[206:209], v[94:97]
	v_mfma_f32_16x16x32_bf16 v[90:93], v[154:157], v[206:209], v[90:93]
	v_mfma_f32_16x16x32_bf16 v[78:81], v[142:145], v[214:217], v[78:81]
	v_mfma_f32_16x16x32_bf16 v[74:77], v[154:157], v[214:217], v[74:77]
	v_mfma_f32_16x16x32_bf16 v[126:129], v[150:153], v[182:185], v[126:129]
	v_mfma_f32_16x16x32_bf16 v[122:125], v[158:161], v[182:185], v[122:125]
	v_mfma_f32_16x16x32_bf16 v[110:113], v[150:153], v[190:193], v[110:113]
	v_mfma_f32_16x16x32_bf16 v[106:109], v[158:161], v[190:193], v[106:109]
	v_mfma_f32_16x16x32_bf16 v[94:97], v[150:153], v[210:213], v[94:97]
	v_mfma_f32_16x16x32_bf16 v[90:93], v[158:161], v[210:213], v[90:93]
	v_mfma_f32_16x16x32_bf16 v[78:81], v[150:153], v[218:221], v[78:81]
	v_mfma_f32_16x16x32_bf16 v[74:77], v[158:161], v[218:221], v[74:77]
	s_setprio 0
	s_setprio 1
	v_mfma_f32_16x16x32_bf16 v[118:121], v[162:165], v[178:181], v[118:121]
	v_mfma_f32_16x16x32_bf16 v[114:117], v[170:173], v[178:181], v[114:117]
	v_mfma_f32_16x16x32_bf16 v[102:105], v[162:165], v[186:189], v[102:105]
	v_mfma_f32_16x16x32_bf16 v[98:101], v[170:173], v[186:189], v[98:101]
	v_mfma_f32_16x16x32_bf16 v[86:89], v[162:165], v[206:209], v[86:89]
	v_mfma_f32_16x16x32_bf16 v[82:85], v[170:173], v[206:209], v[82:85]
	v_mfma_f32_16x16x32_bf16 v[70:73], v[162:165], v[214:217], v[70:73]
	v_mfma_f32_16x16x32_bf16 v[66:69], v[170:173], v[214:217], v[66:69]
	v_mfma_f32_16x16x32_bf16 v[118:121], v[166:169], v[182:185], v[118:121]
	v_mfma_f32_16x16x32_bf16 v[114:117], v[174:177], v[182:185], v[114:117]
	v_mfma_f32_16x16x32_bf16 v[102:105], v[166:169], v[190:193], v[102:105]
	v_mfma_f32_16x16x32_bf16 v[98:101], v[174:177], v[190:193], v[98:101]
	v_mfma_f32_16x16x32_bf16 v[86:89], v[166:169], v[210:213], v[86:89]
	v_mfma_f32_16x16x32_bf16 v[82:85], v[174:177], v[210:213], v[82:85]
	v_mfma_f32_16x16x32_bf16 v[70:73], v[166:169], v[218:221], v[70:73]
	v_mfma_f32_16x16x32_bf16 v[66:69], v[174:177], v[218:221], v[66:69]
	s_setprio 0
	s_barrier
; #define PG8_STAGE(bufoff, gbase, voff) do { _Pragma("unroll") for (int _i = 0; _i < 2; ++_i) \
;         __builtin_amdgcn_global_load_lds((const unsigned*)((const char*)(gbase) + (voff)[_i]), (PG8_LAS unsigned*)(lds + (bufoff) + ldsw + _i * 8192), 16, 0, 0); } while (0)
; #define PG8_LDA(dst, b, h) do { _Pragma("unroll") for (int m = 0; m < 4; ++m) _Pragma("unroll") for (int k = 0; k < 2; ++k) dst[m][k] = *(const PG8_LAS bf16x8*)(lds + PG8_SA(b, h) + aoff + m * 2048 + k * 1024); } while (0)
; #define PG8_LDB(dst, b, h) do { _Pragma("unroll") for (int n = 0; n < 2; ++n) _Pragma("unroll") for (int k = 0; k < 2; ++k) dst[n][k] = *(const PG8_LAS bf16x8*)(lds + PG8_SB(b, h) + boff + n * 2048 + k * 1024); } while (0)
; template <class Epi, class Sched, bool ALIGN_EPI = false, bool SP2 = false>
; __device__ __forceinline__ void gemm_phase(PG8_LAS unsigned char* lds, const Gemm g, const Sched& S, const Epi& E) {
;     ...
;         for (int t = 0; t < nt; t += 2) {
;             const bool last = (t == nt - 2);
;             const char* a1 = cA + (size_t)(t + 1) * kstepA;
;             const char* a2 = last ? nA : cA + (size_t)(t + 2) * kstepA; const char* b2 = last ? nB : cB + (size_t)(t + 2) * kstep;
;             const char* a3 = a2 + kstepA; const char* b3 = b2 + kstep;
;             if (last && has_next) S.a_ready(nxt);
;             if constexpr (SP2) {
;             PG8_LDB(B0, 0, 0); PG8_LDB(B1, 0, 1); PG8_SCHED; PG8_LDA(At, 0, 0); PG8_STAGE(PG8_SA(1, 1), a1 + hstepA, voffA);
;             PG8_WAIT_V(8); PG8_WAIT_L(0); PG8_BAR; PG8_MMA(0, 0, At, B0); PG8_MMA(0, 1, At, B1); PG8_BAR; PG8_SCHED;
;             PG8_LDA(At, 0, 1); PG8_STAGE(PG8_SB(0, 0), b2, voffB); PG8_STAGE(PG8_SB(0, 1), b2 + hstepB, voffB); PG8_STAGE(PG8_SA(0, 0), a2, voffA);
;             PG8_WAIT_V(8); PG8_WAIT_L(0); PG8_BAR; PG8_MMA(1, 0, At, B0); PG8_MMA(1, 1, At, B1); PG8_BAR; PG8_SCHED;
;             PG8_LDB(B0, 1, 0); PG8_LDB(B1, 1, 1); PG8_SCHED; PG8_LDA(At, 1, 0); PG8_STAGE(PG8_SA(0, 1), a2 + hstepA, voffA);
;             PG8_WAIT_V(8); PG8_WAIT_L(0); PG8_BAR; PG8_MMA(0, 0, At, B0); PG8_MMA(0, 1, At, B1); PG8_BAR; PG8_SCHED;
;             PG8_LDA(At, 1, 1); PG8_STAGE(PG8_SB(1, 0), b3, voffB); PG8_STAGE(PG8_SB(1, 1), b3 + hstepB, voffB); PG8_STAGE(PG8_SA(1, 0), a3, voffA);
;             PG8_WAIT_V(8); PG8_WAIT_L(0); PG8_BAR; PG8_MMA(1, 0, At, B0); PG8_MMA(1, 1, At, B1); PG8_BAR; PG8_SCHED;
	s_add_i32 s22, s43, s25
	v_lshl_add_u64 v[222:223], v[222:223], 0, s[78:79]
	s_mov_b32 m0, s22
	ds_read_b128 v[178:181], v148 offset:49152
	ds_read_b128 v[182:185], v148 offset:50176
	ds_read_b128 v[186:189], v148 offset:51200
	ds_read_b128 v[190:193], v148 offset:52224
	ds_read_b128 v[206:209], v148 offset:53248
	ds_read_b128 v[210:213], v148 offset:54272
	ds_read_b128 v[214:217], v148 offset:55296
	ds_read_b128 v[218:221], v148 offset:56320
	global_load_lds_dwordx4 v[222:223], off
	s_add_i32 m0, s22, 0x2000
	s_add_u32 s20, s20, 0x40080
	v_lshl_add_u64 v[222:223], v[224:225], 0, s[78:79]
	s_addc_u32 s21, s21, 0
	s_add_i32 s22, s44, s25
	global_load_lds_dwordx4 v[222:223], off
	v_lshl_add_u64 v[222:223], s[20:21], 0, v[0:1]
	s_mov_b32 m0, s22
	s_nop 0
	global_load_lds_dwordx4 v[222:223], off
	v_lshl_add_u64 v[222:223], s[20:21], 0, v[130:131]
	s_add_i32 m0, s22, 0x2000
	s_nop 0
	global_load_lds_dwordx4 v[222:223], off
	v_lshl_add_u64 v[222:223], s[18:19], 0, v[134:135]
	s_mov_b32 m0, s30
	s_nop 0
	global_load_lds_dwordx4 v[222:223], off
	v_lshl_add_u64 v[222:223], s[18:19], 0, v[132:133]
	s_mov_b32 m0, s31
	s_nop 0
	global_load_lds_dwordx4 v[222:223], off
	s_waitcnt vmcnt(8)
	s_waitcnt lgkmcnt(0)
	s_barrier
	s_setprio 1
	s_waitcnt lgkmcnt(0)
	v_mfma_f32_16x16x32_bf16 v[62:65], v[142:145], v[178:181], v[62:65]
	v_mfma_f32_16x16x32_bf16 v[58:61], v[154:157], v[178:181], v[58:61]
	v_mfma_f32_16x16x32_bf16 v[46:49], v[142:145], v[186:189], v[46:49]
	v_mfma_f32_16x16x32_bf16 v[42:45], v[154:157], v[186:189], v[42:45]
	v_mfma_f32_16x16x32_bf16 v[30:33], v[142:145], v[206:209], v[30:33]
	v_mfma_f32_16x16x32_bf16 v[26:29], v[154:157], v[206:209], v[26:29]
	v_mfma_f32_16x16x32_bf16 v[14:17], v[142:145], v[214:217], v[14:17]
	v_mfma_f32_16x16x32_bf16 v[10:13], v[154:157], v[214:217], v[10:13]
	v_mfma_f32_16x16x32_bf16 v[62:65], v[150:153], v[182:185], v[62:65]
	v_mfma_f32_16x16x32_bf16 v[58:61], v[158:161], v[182:185], v[58:61]
	v_mfma_f32_16x16x32_bf16 v[46:49], v[150:153], v[190:193], v[46:49]
	v_mfma_f32_16x16x32_bf16 v[42:45], v[158:161], v[190:193], v[42:45]
	v_mfma_f32_16x16x32_bf16 v[30:33], v[150:153], v[210:213], v[30:33]
	v_mfma_f32_16x16x32_bf16 v[26:29], v[158:161], v[210:213], v[26:29]
	v_mfma_f32_16x16x32_bf16 v[14:17], v[150:153], v[218:221], v[14:17]
	v_mfma_f32_16x16x32_bf16 v[10:13], v[158:161], v[218:221], v[10:13]
	s_add_i32 s42, s42, 2
	s_setprio 0
	s_setprio 1
	v_mfma_f32_16x16x32_bf16 v[54:57], v[162:165], v[178:181], v[54:57]
	s_add_u32 s40, s40, 0x100
	v_mfma_f32_16x16x32_bf16 v[50:53], v[170:173], v[178:181], v[50:53]
	s_addc_u32 s41, s41, 0
	v_mfma_f32_16x16x32_bf16 v[38:41], v[162:165], v[186:189], v[38:41]
	s_add_u32 s16, s16, 0x800000
	v_mfma_f32_16x16x32_bf16 v[34:37], v[170:173], v[186:189], v[34:37]
	s_addc_u32 s17, s17, 0
	v_mfma_f32_16x16x32_bf16 v[22:25], v[162:165], v[206:209], v[22:25]
	s_add_u32 s18, s16, 0x3fc000
	v_mfma_f32_16x16x32_bf16 v[18:21], v[170:173], v[206:209], v[18:21]
	s_addc_u32 s19, s17, 0
	v_mfma_f32_16x16x32_bf16 v[6:9], v[162:165], v[214:217], v[6:9]
	s_cmp_eq_u32 s42, 12
	v_mfma_f32_16x16x32_bf16 v[2:5], v[170:173], v[214:217], v[2:5]
	s_cselect_b32 s22, s38, s18
	v_mfma_f32_16x16x32_bf16 v[54:57], v[166:169], v[182:185], v[54:57]
	s_cselect_b32 s23, s11, s19
	v_mfma_f32_16x16x32_bf16 v[50:53], v[174:177], v[182:185], v[50:53]
	s_cselect_b32 s20, s39, s40
	v_mfma_f32_16x16x32_bf16 v[38:41], v[166:169], v[190:193], v[38:41]
	s_cselect_b32 s21, s9, s41
	v_mfma_f32_16x16x32_bf16 v[34:37], v[174:177], v[190:193], v[34:37]
	s_add_u32 s18, s22, 0x400000
	v_mfma_f32_16x16x32_bf16 v[22:25], v[166:169], v[210:213], v[22:25]
	s_addc_u32 s19, s23, 0
	v_mfma_f32_16x16x32_bf16 v[18:21], v[174:177], v[210:213], v[18:21]
	s_add_i32 s43, 0, 0x10000
	v_mfma_f32_16x16x32_bf16 v[6:9], v[166:169], v[218:221], v[6:9]
	s_cmp_gt_u32 s42, 13
	v_mfma_f32_16x16x32_bf16 v[2:5], v[174:177], v[218:221], v[2:5]
	s_setprio 0
	s_barrier
	s_cbranch_scc0 .LBB0_53
	s_and_b64 vcc, exec, s[6:7]
	s_cbranch_vccz .LBB0_56
	s_barrier

; #define PG8_STAGE(bufoff, gbase, voff) do { _Pragma("unroll") for (int _i = 0; _i < 2; ++_i) \
;         __builtin_amdgcn_global_load_lds((const unsigned*)((const char*)(gbase) + (voff)[_i]), (PG8_LAS unsigned*)(lds + (bufoff) + ldsw + _i * 8192), 16, 0, 0); } while (0)
; #define PG8_LDA(dst, b, h) do { _Pragma("unroll") for (int m = 0; m < 4; ++m) _Pragma("unroll") for (int k = 0; k < 2; ++k) dst[m][k] = *(const PG8_LAS bf16x8*)(lds + PG8_SA(b, h) + aoff + m * 2048 + k * 1024); } while (0)
; #define PG8_LDB(dst, b, h) do { _Pragma("unroll") for (int n = 0; n < 2; ++n) _Pragma("unroll") for (int k = 0; k < 2; ++k) dst[n][k] = *(const PG8_LAS bf16x8*)(lds + PG8_SB(b, h) + boff + n * 2048 + k * 1024); } while (0)
; #define PG8_WAIT_V(n) asm volatile("s_waitcnt vmcnt(" #n ")" ::: "memory")
; #define PG8_WAIT_L(n) asm volatile("s_waitcnt lgkmcnt(" #n ")" ::: "memory")
; #define PG8_BAR __builtin_amdgcn_s_barrier()
; #define PG8_SCHED __builtin_amdgcn_sched_barrier(0)
; template <class Epi, class Sched, bool ALIGN_EPI = false, bool SP2 = false>
; __device__ __forceinline__ void gemm_phase(PG8_LAS unsigned char* lds, const Gemm g, const Sched& S, const Epi& E) {
;     ...
;     for (;;) {
;         const bool has_next = S.next(ui + 1, nxt);
;         const char* nA = has_next ? (const char*)g.A + (size_t)nxt.pm * tstepA + (size_t)nxt.pn * pnoffA : cA; const char* nB = has_next ? (const char*)g.Bt + (size_t)nxt.pn * tstepB : cB;
;         for (int t = 0; t < nt; t += 2) {
;             const bool last = (t == nt - 2);
;             const char* a1 = cA + (size_t)(t + 1) * kstepA;
;             const char* a2 = last ? nA : cA + (size_t)(t + 2) * kstepA; const char* b2 = last ? nB : cB + (size_t)(t + 2) * kstep;
;             const char* a3 = a2 + kstepA; const char* b3 = b2 + kstep;
;             if (last && has_next) S.a_ready(nxt);
;             if constexpr (SP2) {
;             PG8_LDB(B0, 0, 0); PG8_LDB(B1, 0, 1); PG8_SCHED; PG8_LDA(At, 0, 0); PG8_STAGE(PG8_SA(1, 1), a1 + hstepA, voffA);
;             PG8_WAIT_V(8); PG8_WAIT_L(0); PG8_BAR; PG8_MMA(0, 0, At, B0); PG8_MMA(0, 1, At, B1); PG8_BAR; PG8_SCHED;
;             PG8_LDA(At, 0, 1); PG8_STAGE(PG8_SB(0, 0), b2, voffB); PG8_STAGE(PG8_SB(0, 1), b2 + hstepB, voffB); PG8_STAGE(PG8_SA(0, 0), a2, voffA);
;             PG8_WAIT_V(8); PG8_WAIT_L(0); PG8_BAR; PG8_MMA(1, 0, At, B0); PG8_MMA(1, 1, At, B1); PG8_BAR; PG8_SCHED;
.LBB0_86:
	s_ashr_i32 s17, s16, 31
	s_lshl_b64 s[18:19], s[16:17], 15
	s_add_u32 s18, s70, s18
	s_addc_u32 s19, s71, s19
	s_and_b64 s[20:21], s[6:7], exec
	s_cselect_b32 s17, s19, s23
	s_cselect_b32 s42, s18, s22
	s_ashr_i32 s15, s14, 31
	s_lshl_b64 s[20:21], s[14:15], 19
	v_readlane_b32 s26, v253, 55
	v_readlane_b32 s27, v253, 56
	s_add_u32 s20, s26, s20
	s_addc_u32 s21, s27, s21
	s_and_b64 s[26:27], s[6:7], exec
	s_cselect_b32 s15, s21, s25
	s_cselect_b32 s43, s20, s24
	s_add_u32 s22, s22, 0x204000
	s_addc_u32 s23, s23, 0
	s_add_u32 s44, s24, 0x100
	s_addc_u32 s45, s25, 0
	s_mov_b32 s46, -2
	s_add_u32 s24, s22, 0x1fc000
	s_addc_u32 s25, s23, 0
	s_cmp_eq_u32 s46, 12
	s_cselect_b32 s28, s42, s24
	s_cselect_b32 s29, s17, s25
	s_cselect_b32 s26, s43, s44
	s_cselect_b32 s27, s15, s45
	s_add_u32 s24, s28, 0x200000
	s_addc_u32 s25, s29, 0
	s_add_i32 s47, 0, 0x10000
	s_add_i32 s50, 0, 0x14000
	v_add_u32_e32 v152, s47, v161
	v_add_u32_e32 v172, s50, v161
	ds_read_b128 v[130:133], v152
	ds_read_b128 v[134:137], v152 offset:1024
	ds_read_b128 v[138:141], v152 offset:2048
	ds_read_b128 v[152:155], v152 offset:3072
	ds_read_b128 v[156:159], v172
	ds_read_b128 v[164:167], v172 offset:1024
	ds_read_b128 v[168:171], v172 offset:2048
	ds_read_b128 v[172:175], v172 offset:3072
	v_lshl_add_u64 v[192:193], s[22:23], 0, v[148:149]
	s_add_i32 m0, s31, 0xc000
	ds_read_b128 v[176:179], v163
	ds_read_b128 v[180:183], v163 offset:1024
	ds_read_b128 v[184:187], v163 offset:2048
	ds_read_b128 v[188:191], v163 offset:3072
	ds_read_b128 v[206:209], v163 offset:4096
	ds_read_b128 v[210:213], v163 offset:5120
	ds_read_b128 v[214:217], v163 offset:6144
	ds_read_b128 v[218:221], v163 offset:7168
	global_load_lds_dwordx4 v[192:193], off
	v_lshl_add_u64 v[192:193], s[22:23], 0, v[150:151]
	s_add_i32 m0, s31, 0xe000
	s_nop 0
	global_load_lds_dwordx4 v[192:193], off
	s_waitcnt vmcnt(8)
	s_waitcnt lgkmcnt(0)
	s_barrier
	s_setprio 1
	s_waitcnt lgkmcnt(0)
	v_mfma_f32_16x16x32_bf16 v[126:129], v[130:133], v[176:179], 0
	v_mfma_f32_16x16x32_bf16 v[122:125], v[138:141], v[176:179], 0
	v_mfma_f32_16x16x32_bf16 v[118:121], v[130:133], v[184:187], 0
	v_mfma_f32_16x16x32_bf16 v[106:109], v[138:141], v[184:187], 0
	v_mfma_f32_16x16x32_bf16 v[102:105], v[130:133], v[206:209], 0
	v_mfma_f32_16x16x32_bf16 v[90:93], v[138:141], v[206:209], 0
	v_mfma_f32_16x16x32_bf16 v[86:89], v[130:133], v[214:217], 0
	v_mfma_f32_16x16x32_bf16 v[74:77], v[138:141], v[214:217], 0
	v_mfma_f32_16x16x32_bf16 v[126:129], v[134:137], v[180:183], v[126:129]
	v_mfma_f32_16x16x32_bf16 v[122:125], v[152:155], v[180:183], v[122:125]
	v_mfma_f32_16x16x32_bf16 v[118:121], v[134:137], v[188:191], v[118:121]
	v_mfma_f32_16x16x32_bf16 v[106:109], v[152:155], v[188:191], v[106:109]
	v_mfma_f32_16x16x32_bf16 v[102:105], v[134:137], v[210:213], v[102:105]
	v_mfma_f32_16x16x32_bf16 v[90:93], v[152:155], v[210:213], v[90:93]
	v_mfma_f32_16x16x32_bf16 v[86:89], v[134:137], v[218:221], v[86:89]
	v_mfma_f32_16x16x32_bf16 v[74:77], v[152:155], v[218:221], v[74:77]
	s_setprio 0
	s_setprio 1
	v_mfma_f32_16x16x32_bf16 v[114:117], v[156:159], v[176:179], 0
	v_mfma_f32_16x16x32_bf16 v[110:113], v[168:171], v[176:179], 0
	v_mfma_f32_16x16x32_bf16 v[98:101], v[156:159], v[184:187], 0
	v_mfma_f32_16x16x32_bf16 v[94:97], v[168:171], v[184:187], 0
	v_mfma_f32_16x16x32_bf16 v[82:85], v[156:159], v[206:209], 0
	v_mfma_f32_16x16x32_bf16 v[78:81], v[168:171], v[206:209], 0
	v_mfma_f32_16x16x32_bf16 v[70:73], v[156:159], v[214:217], 0
	v_mfma_f32_16x16x32_bf16 v[66:69], v[168:171], v[214:217], 0
	v_mfma_f32_16x16x32_bf16 v[114:117], v[164:167], v[180:183], v[114:117]
	v_mfma_f32_16x16x32_bf16 v[110:113], v[172:175], v[180:183], v[110:113]
	v_mfma_f32_16x16x32_bf16 v[98:101], v[164:167], v[188:191], v[98:101]
	v_mfma_f32_16x16x32_bf16 v[94:97], v[172:175], v[188:191], v[94:97]
	v_mfma_f32_16x16x32_bf16 v[82:85], v[164:167], v[210:213], v[82:85]
	v_mfma_f32_16x16x32_bf16 v[78:81], v[172:175], v[210:213], v[78:81]
	v_mfma_f32_16x16x32_bf16 v[70:73], v[164:167], v[218:221], v[70:73]
	v_mfma_f32_16x16x32_bf16 v[66:69], v[172:175], v[218:221], v[66:69]
	s_setprio 0
	s_barrier
	s_add_i32 s47, s47, s30
	v_lshl_add_u64 v[192:193], s[26:27], 0, v[0:1]
	s_mov_b32 m0, s47
	ds_read_b128 v[176:179], v163 offset:16384
	ds_read_b128 v[180:183], v163 offset:17408
	ds_read_b128 v[184:187], v163 offset:18432
	ds_read_b128 v[188:191], v163 offset:19456
	ds_read_b128 v[206:209], v163 offset:20480
	ds_read_b128 v[210:213], v163 offset:21504
	ds_read_b128 v[214:217], v163 offset:22528
	ds_read_b128 v[218:221], v163 offset:23552
	global_load_lds_dwordx4 v[192:193], off
	s_add_i32 m0, s47, 0x2000
	s_add_u32 s48, s26, 0x40000
	v_lshl_add_u64 v[222:223], s[26:27], 0, v[142:143]
	s_addc_u32 s49, s27, 0
	s_add_i32 s47, s50, s30
	global_load_lds_dwordx4 v[222:223], off
	v_lshl_add_u64 v[224:225], s[48:49], 0, v[0:1]
	s_mov_b32 m0, s47
	s_nop 0
	global_load_lds_dwordx4 v[224:225], off
	v_lshl_add_u64 v[224:225], s[48:49], 0, v[142:143]
	s_add_i32 m0, s47, 0x2000
	s_nop 0
	global_load_lds_dwordx4 v[224:225], off
	v_lshl_add_u64 v[224:225], s[28:29], 0, v[146:147]
	s_mov_b32 m0, s31
	s_nop 0
	global_load_lds_dwordx4 v[224:225], off
	v_lshl_add_u64 v[224:225], s[28:29], 0, v[144:145]
	s_mov_b32 m0, s34
	s_nop 0
	global_load_lds_dwordx4 v[224:225], off
	s_waitcnt vmcnt(8)
	s_waitcnt lgkmcnt(0)
	s_barrier
; #define PG8_STAGE(bufoff, gbase, voff) do { _Pragma("unroll") for (int _i = 0; _i < 2; ++_i) \
;         __builtin_amdgcn_global_load_lds((const unsigned*)((const char*)(gbase) + (voff)[_i]), (PG8_LAS unsigned*)(lds + (bufoff) + ldsw + _i * 8192), 16, 0, 0); } while (0)
; #define PG8_LDA(dst, b, h) do { _Pragma("unroll") for (int m = 0; m < 4; ++m) _Pragma("unroll") for (int k = 0; k < 2; ++k) dst[m][k] = *(const PG8_LAS bf16x8*)(lds + PG8_SA(b, h) + aoff + m * 2048 + k * 1024); } while (0)
; #define PG8_LDB(dst, b, h) do { _Pragma("unroll") for (int n = 0; n < 2; ++n) _Pragma("unroll") for (int k = 0; k < 2; ++k) dst[n][k] = *(const PG8_LAS bf16x8*)(lds + PG8_SB(b, h) + boff + n * 2048 + k * 1024); } while (0)
; #define PG8_MMA(ai, bj, At, Bt) do { __builtin_amdgcn_s_setprio(1); _Pragma("unroll") for (int m = 0; m < 4; ++m) _Pragma("unroll") for (int n = 0; n < 2; ++n) _Pragma("unroll") for (int k = 0; k < 2; ++k) \
;         acc[ai][bj][m][n] = __builtin_amdgcn_mfma_f32_16x16x32_bf16(Bt[n][k], At[m][k], acc[ai][bj][m][n], 0, 0, 0); __builtin_amdgcn_s_setprio(0); } while (0)
; #define PG8_WAIT_V(n) asm volatile("s_waitcnt vmcnt(" #n ")" ::: "memory")
; #define PG8_WAIT_L(n) asm volatile("s_waitcnt lgkmcnt(" #n ")" ::: "memory")
; #define PG8_BAR __builtin_amdgcn_s_barrier()
; #define PG8_SCHED __builtin_amdgcn_sched_barrier(0)
; template <class Epi, class Sched, bool ALIGN_EPI = false, bool SP2 = false>
; __device__ __forceinline__ void gemm_phase(PG8_LAS unsigned char* lds, const Gemm g, const Sched& S, const Epi& E) {
;     ...
;             PG8_WAIT_V(8); PG8_WAIT_L(0); PG8_BAR; PG8_MMA(1, 0, At, B0); PG8_MMA(1, 1, At, B1); PG8_BAR; PG8_SCHED;
;             PG8_LDB(B0, 1, 0); PG8_LDB(B1, 1, 1); PG8_SCHED; PG8_LDA(At, 1, 0); PG8_STAGE(PG8_SA(0, 1), a2 + hstepA, voffA);
;             PG8_WAIT_V(8); PG8_WAIT_L(0); PG8_BAR; PG8_MMA(0, 0, At, B0); PG8_MMA(0, 1, At, B1); PG8_BAR; PG8_SCHED;
	s_setprio 1
	s_waitcnt lgkmcnt(0)
	v_mfma_f32_16x16x32_bf16 v[62:65], v[130:133], v[176:179], 0
	v_mfma_f32_16x16x32_bf16 v[58:61], v[138:141], v[176:179], 0
	v_mfma_f32_16x16x32_bf16 v[54:57], v[130:133], v[184:187], 0
	v_mfma_f32_16x16x32_bf16 v[42:45], v[138:141], v[184:187], 0
	v_mfma_f32_16x16x32_bf16 v[38:41], v[130:133], v[206:209], 0
	v_mfma_f32_16x16x32_bf16 v[26:29], v[138:141], v[206:209], 0
	v_mfma_f32_16x16x32_bf16 v[22:25], v[130:133], v[214:217], 0
	v_mfma_f32_16x16x32_bf16 v[10:13], v[138:141], v[214:217], 0
	v_mfma_f32_16x16x32_bf16 v[62:65], v[134:137], v[180:183], v[62:65]
	v_mfma_f32_16x16x32_bf16 v[58:61], v[152:155], v[180:183], v[58:61]
	v_mfma_f32_16x16x32_bf16 v[54:57], v[134:137], v[188:191], v[54:57]
	v_mfma_f32_16x16x32_bf16 v[42:45], v[152:155], v[188:191], v[42:45]
	v_mfma_f32_16x16x32_bf16 v[38:41], v[134:137], v[210:213], v[38:41]
	v_mfma_f32_16x16x32_bf16 v[26:29], v[152:155], v[210:213], v[26:29]
	v_mfma_f32_16x16x32_bf16 v[22:25], v[134:137], v[218:221], v[22:25]
	v_mfma_f32_16x16x32_bf16 v[10:13], v[152:155], v[218:221], v[10:13]
	s_setprio 0
	s_setprio 1
	v_mfma_f32_16x16x32_bf16 v[50:53], v[156:159], v[176:179], 0
	v_mfma_f32_16x16x32_bf16 v[46:49], v[168:171], v[176:179], 0
	v_mfma_f32_16x16x32_bf16 v[34:37], v[156:159], v[184:187], 0
	v_mfma_f32_16x16x32_bf16 v[30:33], v[168:171], v[184:187], 0
	v_mfma_f32_16x16x32_bf16 v[18:21], v[156:159], v[206:209], 0
	v_mfma_f32_16x16x32_bf16 v[14:17], v[168:171], v[206:209], 0
	v_mfma_f32_16x16x32_bf16 v[6:9], v[156:159], v[214:217], 0
	v_mfma_f32_16x16x32_bf16 v[2:5], v[168:171], v[214:217], 0
	v_mfma_f32_16x16x32_bf16 v[50:53], v[164:167], v[180:183], v[50:53]
	v_mfma_f32_16x16x32_bf16 v[46:49], v[172:175], v[180:183], v[46:49]
	v_mfma_f32_16x16x32_bf16 v[34:37], v[164:167], v[188:191], v[34:37]
	v_mfma_f32_16x16x32_bf16 v[30:33], v[172:175], v[188:191], v[30:33]
	v_mfma_f32_16x16x32_bf16 v[18:21], v[164:167], v[210:213], v[18:21]
	v_mfma_f32_16x16x32_bf16 v[14:17], v[172:175], v[210:213], v[14:17]
	v_mfma_f32_16x16x32_bf16 v[6:9], v[164:167], v[218:221], v[6:9]
	v_mfma_f32_16x16x32_bf16 v[2:5], v[172:175], v[218:221], v[2:5]
	s_setprio 0
	s_barrier
	s_add_i32 s47, 0, 0x18000
	s_add_i32 s48, 0, 0x1c000
	v_add_u32_e32 v152, s47, v161
	v_add_u32_e32 v172, s48, v161
	ds_read_b128 v[130:133], v152
	ds_read_b128 v[134:137], v152 offset:1024
	ds_read_b128 v[138:141], v152 offset:2048
	ds_read_b128 v[152:155], v152 offset:3072
	ds_read_b128 v[156:159], v172
	ds_read_b128 v[164:167], v172 offset:1024
	ds_read_b128 v[168:171], v172 offset:2048
	ds_read_b128 v[172:175], v172 offset:3072
	s_add_u32 s28, s28, 0x4000
	s_addc_u32 s29, s29, 0
	s_mov_b32 m0, s35
	v_lshl_add_u64 v[224:225], s[28:29], 0, v[146:147]
	ds_read_b128 v[176:179], v163 offset:32768
	ds_read_b128 v[180:183], v163 offset:33792
	ds_read_b128 v[184:187], v163 offset:34816
	ds_read_b128 v[188:191], v163 offset:35840
	ds_read_b128 v[206:209], v163 offset:36864
	ds_read_b128 v[210:213], v163 offset:37888
	ds_read_b128 v[214:217], v163 offset:38912
	ds_read_b128 v[218:221], v163 offset:39936
	global_load_lds_dwordx4 v[224:225], off
	v_lshl_add_u64 v[224:225], s[28:29], 0, v[144:145]
	s_mov_b32 m0, s36
	s_nop 0
	global_load_lds_dwordx4 v[224:225], off
	s_waitcnt vmcnt(8)
	s_waitcnt lgkmcnt(0)
	s_barrier
	s_setprio 1
	s_waitcnt lgkmcnt(0)
	v_mfma_f32_16x16x32_bf16 v[126:129], v[130:133], v[176:179], v[126:129]
	v_mfma_f32_16x16x32_bf16 v[122:125], v[138:141], v[176:179], v[122:125]
	v_mfma_f32_16x16x32_bf16 v[118:121], v[130:133], v[184:187], v[118:121]
	v_mfma_f32_16x16x32_bf16 v[106:109], v[138:141], v[184:187], v[106:109]
	v_mfma_f32_16x16x32_bf16 v[102:105], v[130:133], v[206:209], v[102:105]
	v_mfma_f32_16x16x32_bf16 v[90:93], v[138:141], v[206:209], v[90:93]
	v_mfma_f32_16x16x32_bf16 v[86:89], v[130:133], v[214:217], v[86:89]
	v_mfma_f32_16x16x32_bf16 v[74:77], v[138:141], v[214:217], v[74:77]
	v_mfma_f32_16x16x32_bf16 v[126:129], v[134:137], v[180:183], v[126:129]
	v_mfma_f32_16x16x32_bf16 v[122:125], v[152:155], v[180:183], v[122:125]
	v_mfma_f32_16x16x32_bf16 v[118:121], v[134:137], v[188:191], v[118:121]
	v_mfma_f32_16x16x32_bf16 v[106:109], v[152:155], v[188:191], v[106:109]
	v_mfma_f32_16x16x32_bf16 v[102:105], v[134:137], v[210:213], v[102:105]
	v_mfma_f32_16x16x32_bf16 v[90:93], v[152:155], v[210:213], v[90:93]
	v_mfma_f32_16x16x32_bf16 v[86:89], v[134:137], v[218:221], v[86:89]
	v_mfma_f32_16x16x32_bf16 v[74:77], v[152:155], v[218:221], v[74:77]
	s_setprio 0
	s_setprio 1
	v_mfma_f32_16x16x32_bf16 v[114:117], v[156:159], v[176:179], v[114:117]
	v_mfma_f32_16x16x32_bf16 v[110:113], v[168:171], v[176:179], v[110:113]
	v_mfma_f32_16x16x32_bf16 v[98:101], v[156:159], v[184:187], v[98:101]
	v_mfma_f32_16x16x32_bf16 v[94:97], v[168:171], v[184:187], v[94:97]
	v_mfma_f32_16x16x32_bf16 v[82:85], v[156:159], v[206:209], v[82:85]
	v_mfma_f32_16x16x32_bf16 v[78:81], v[168:171], v[206:209], v[78:81]
	v_mfma_f32_16x16x32_bf16 v[70:73], v[156:159], v[214:217], v[70:73]
	v_mfma_f32_16x16x32_bf16 v[66:69], v[168:171], v[214:217], v[66:69]
	v_mfma_f32_16x16x32_bf16 v[114:117], v[164:167], v[180:183], v[114:117]
	v_mfma_f32_16x16x32_bf16 v[110:113], v[172:175], v[180:183], v[110:113]
	v_mfma_f32_16x16x32_bf16 v[98:101], v[164:167], v[188:191], v[98:101]
	v_mfma_f32_16x16x32_bf16 v[94:97], v[172:175], v[188:191], v[94:97]
	v_mfma_f32_16x16x32_bf16 v[82:85], v[164:167], v[210:213], v[82:85]
	v_mfma_f32_16x16x32_bf16 v[78:81], v[172:175], v[210:213], v[78:81]
	v_mfma_f32_16x16x32_bf16 v[70:73], v[164:167], v[218:221], v[70:73]
	v_mfma_f32_16x16x32_bf16 v[66:69], v[172:175], v[218:221], v[66:69]
	s_setprio 0
	s_barrier
; #define PG8_STAGE(bufoff, gbase, voff) do { _Pragma("unroll") for (int _i = 0; _i < 2; ++_i) \
;         __builtin_amdgcn_global_load_lds((const unsigned*)((const char*)(gbase) + (voff)[_i]), (PG8_LAS unsigned*)(lds + (bufoff) + ldsw + _i * 8192), 16, 0, 0); } while (0)
; #define PG8_LDA(dst, b, h) do { _Pragma("unroll") for (int m = 0; m < 4; ++m) _Pragma("unroll") for (int k = 0; k < 2; ++k) dst[m][k] = *(const PG8_LAS bf16x8*)(lds + PG8_SA(b, h) + aoff + m * 2048 + k * 1024); } while (0)
; #define PG8_LDB(dst, b, h) do { _Pragma("unroll") for (int n = 0; n < 2; ++n) _Pragma("unroll") for (int k = 0; k < 2; ++k) dst[n][k] = *(const PG8_LAS bf16x8*)(lds + PG8_SB(b, h) + boff + n * 2048 + k * 1024); } while (0)
; template <class Epi, class Sched, bool ALIGN_EPI = false, bool SP2 = false>
; __device__ __forceinline__ void gemm_phase(PG8_LAS unsigned char* lds, const Gemm g, const Sched& S, const Epi& E) {
;     ...
;         for (int t = 0; t < nt; t += 2) {
;             const bool last = (t == nt - 2);
;             const char* a1 = cA + (size_t)(t + 1) * kstepA;
;             const char* a2 = last ? nA : cA + (size_t)(t + 2) * kstepA; const char* b2 = last ? nB : cB + (size_t)(t + 2) * kstep;
;             const char* a3 = a2 + kstepA; const char* b3 = b2 + kstep;
;             if (last && has_next) S.a_ready(nxt);
;             if constexpr (SP2) {
;             PG8_LDB(B0, 0, 0); PG8_LDB(B1, 0, 1); PG8_SCHED; PG8_LDA(At, 0, 0); PG8_STAGE(PG8_SA(1, 1), a1 + hstepA, voffA);
;             PG8_WAIT_V(8); PG8_WAIT_L(0); PG8_BAR; PG8_MMA(0, 0, At, B0); PG8_MMA(0, 1, At, B1); PG8_BAR; PG8_SCHED;
;             PG8_LDA(At, 0, 1); PG8_STAGE(PG8_SB(0, 0), b2, voffB); PG8_STAGE(PG8_SB(0, 1), b2 + hstepB, voffB); PG8_STAGE(PG8_SA(0, 0), a2, voffA);
;             PG8_WAIT_V(8); PG8_WAIT_L(0); PG8_BAR; PG8_MMA(1, 0, At, B0); PG8_MMA(1, 1, At, B1); PG8_BAR; PG8_SCHED;
;             PG8_LDB(B0, 1, 0); PG8_LDB(B1, 1, 1); PG8_SCHED; PG8_LDA(At, 1, 0); PG8_STAGE(PG8_SA(0, 1), a2 + hstepA, voffA);
;             PG8_WAIT_V(8); PG8_WAIT_L(0); PG8_BAR; PG8_MMA(0, 0, At, B0); PG8_MMA(0, 1, At, B1); PG8_BAR; PG8_SCHED;
;             PG8_LDA(At, 1, 1); PG8_STAGE(PG8_SB(1, 0), b3, voffB); PG8_STAGE(PG8_SB(1, 1), b3 + hstepB, voffB); PG8_STAGE(PG8_SA(1, 0), a3, voffA);
;             PG8_WAIT_V(8); PG8_WAIT_L(0); PG8_BAR; PG8_MMA(1, 0, At, B0); PG8_MMA(1, 1, At, B1); PG8_BAR; PG8_SCHED;
	s_add_i32 s28, s47, s30
	v_lshl_add_u64 v[192:193], v[192:193], 0, s[78:79]
	s_mov_b32 m0, s28
	ds_read_b128 v[176:179], v163 offset:49152
	ds_read_b128 v[180:183], v163 offset:50176
	ds_read_b128 v[184:187], v163 offset:51200
	ds_read_b128 v[188:191], v163 offset:52224
	ds_read_b128 v[206:209], v163 offset:53248
	ds_read_b128 v[210:213], v163 offset:54272
	ds_read_b128 v[214:217], v163 offset:55296
	ds_read_b128 v[218:221], v163 offset:56320
	global_load_lds_dwordx4 v[192:193], off
	s_add_i32 m0, s28, 0x2000
	s_add_u32 s26, s26, 0x40080
	v_lshl_add_u64 v[192:193], v[222:223], 0, s[78:79]
	s_addc_u32 s27, s27, 0
	s_add_i32 s28, s48, s30
	global_load_lds_dwordx4 v[192:193], off
	v_lshl_add_u64 v[192:193], s[26:27], 0, v[0:1]
	s_mov_b32 m0, s28
	s_nop 0
	global_load_lds_dwordx4 v[192:193], off
	v_lshl_add_u64 v[192:193], s[26:27], 0, v[142:143]
	s_add_i32 m0, s28, 0x2000
	s_nop 0
	global_load_lds_dwordx4 v[192:193], off
	v_lshl_add_u64 v[192:193], s[24:25], 0, v[146:147]
	s_mov_b32 m0, s37
	s_nop 0
	global_load_lds_dwordx4 v[192:193], off
	v_lshl_add_u64 v[192:193], s[24:25], 0, v[144:145]
	s_mov_b32 m0, s38
	s_nop 0
	global_load_lds_dwordx4 v[192:193], off
	s_waitcnt vmcnt(8)
	s_waitcnt lgkmcnt(0)
	s_barrier
	s_setprio 1
	s_waitcnt lgkmcnt(0)
	v_mfma_f32_16x16x32_bf16 v[62:65], v[130:133], v[176:179], v[62:65]
	v_mfma_f32_16x16x32_bf16 v[58:61], v[138:141], v[176:179], v[58:61]
	v_mfma_f32_16x16x32_bf16 v[54:57], v[130:133], v[184:187], v[54:57]
	v_mfma_f32_16x16x32_bf16 v[42:45], v[138:141], v[184:187], v[42:45]
	v_mfma_f32_16x16x32_bf16 v[38:41], v[130:133], v[206:209], v[38:41]
	v_mfma_f32_16x16x32_bf16 v[26:29], v[138:141], v[206:209], v[26:29]
	v_mfma_f32_16x16x32_bf16 v[22:25], v[130:133], v[214:217], v[22:25]
	v_mfma_f32_16x16x32_bf16 v[10:13], v[138:141], v[214:217], v[10:13]
	v_mfma_f32_16x16x32_bf16 v[62:65], v[134:137], v[180:183], v[62:65]
	v_mfma_f32_16x16x32_bf16 v[58:61], v[152:155], v[180:183], v[58:61]
	v_mfma_f32_16x16x32_bf16 v[54:57], v[134:137], v[188:191], v[54:57]
	v_mfma_f32_16x16x32_bf16 v[42:45], v[152:155], v[188:191], v[42:45]
	v_mfma_f32_16x16x32_bf16 v[38:41], v[134:137], v[210:213], v[38:41]
	v_mfma_f32_16x16x32_bf16 v[26:29], v[152:155], v[210:213], v[26:29]
	v_mfma_f32_16x16x32_bf16 v[22:25], v[134:137], v[218:221], v[22:25]
	v_mfma_f32_16x16x32_bf16 v[10:13], v[152:155], v[218:221], v[10:13]
	s_add_i32 s46, s46, 2
	s_setprio 0
	s_setprio 1
	v_mfma_f32_16x16x32_bf16 v[50:53], v[156:159], v[176:179], v[50:53]
	s_add_u32 s22, s22, 0x400000
	v_mfma_f32_16x16x32_bf16 v[46:49], v[168:171], v[176:179], v[46:49]
	s_addc_u32 s23, s23, 0
	v_mfma_f32_16x16x32_bf16 v[34:37], v[156:159], v[184:187], v[34:37]
	s_add_u32 s44, s44, 0x100
	v_mfma_f32_16x16x32_bf16 v[30:33], v[168:171], v[184:187], v[30:33]
	s_addc_u32 s45, s45, 0
	v_mfma_f32_16x16x32_bf16 v[18:21], v[156:159], v[206:209], v[18:21]
	s_add_u32 s24, s22, 0x1fc000
	v_mfma_f32_16x16x32_bf16 v[14:17], v[168:171], v[206:209], v[14:17]
	s_addc_u32 s25, s23, 0
	v_mfma_f32_16x16x32_bf16 v[6:9], v[156:159], v[214:217], v[6:9]
	s_cmp_eq_u32 s46, 12
	v_mfma_f32_16x16x32_bf16 v[2:5], v[168:171], v[214:217], v[2:5]
	s_cselect_b32 s28, s42, s24
	v_mfma_f32_16x16x32_bf16 v[50:53], v[164:167], v[180:183], v[50:53]
	s_cselect_b32 s29, s17, s25
	v_mfma_f32_16x16x32_bf16 v[46:49], v[172:175], v[180:183], v[46:49]
	s_cselect_b32 s26, s43, s44
	v_mfma_f32_16x16x32_bf16 v[34:37], v[164:167], v[188:191], v[34:37]
	s_cselect_b32 s27, s15, s45
	v_mfma_f32_16x16x32_bf16 v[30:33], v[172:175], v[188:191], v[30:33]
	s_add_u32 s24, s28, 0x200000
	v_mfma_f32_16x16x32_bf16 v[18:21], v[164:167], v[210:213], v[18:21]
	s_addc_u32 s25, s29, 0
	v_mfma_f32_16x16x32_bf16 v[14:17], v[172:175], v[210:213], v[14:17]
	s_add_i32 s47, 0, 0x10000
	v_mfma_f32_16x16x32_bf16 v[6:9], v[164:167], v[218:221], v[6:9]
	s_add_i32 s50, 0, 0x14000
	v_mfma_f32_16x16x32_bf16 v[2:5], v[172:175], v[218:221], v[2:5]
	s_setprio 0
	s_barrier
.LBB0_87:
	v_add_u32_e32 v152, s47, v161
	v_add_u32_e32 v172, s50, v161
	ds_read_b128 v[130:133], v152
	ds_read_b128 v[134:137], v152 offset:1024
	ds_read_b128 v[138:141], v152 offset:2048
	ds_read_b128 v[152:155], v152 offset:3072
	ds_read_b128 v[156:159], v172
	ds_read_b128 v[164:167], v172 offset:1024
	ds_read_b128 v[168:171], v172 offset:2048
	ds_read_b128 v[172:175], v172 offset:3072
	v_lshl_add_u64 v[192:193], s[22:23], 0, v[148:149]
	s_add_i32 m0, s31, 0xc000
	ds_read_b128 v[176:179], v163
	ds_read_b128 v[180:183], v163 offset:1024
	ds_read_b128 v[184:187], v163 offset:2048
	ds_read_b128 v[188:191], v163 offset:3072
	ds_read_b128 v[206:209], v163 offset:4096
	ds_read_b128 v[210:213], v163 offset:5120
	ds_read_b128 v[214:217], v163 offset:6144
	ds_read_b128 v[218:221], v163 offset:7168
	global_load_lds_dwordx4 v[192:193], off
	v_lshl_add_u64 v[192:193], s[22:23], 0, v[150:151]
	s_add_i32 m0, s31, 0xe000
	s_nop 0
	global_load_lds_dwordx4 v[192:193], off
	s_waitcnt vmcnt(8)
	s_waitcnt lgkmcnt(0)
	s_barrier
; #define PG8_STAGE(bufoff, gbase, voff) do { _Pragma("unroll") for (int _i = 0; _i < 2; ++_i) \
;         __builtin_amdgcn_global_load_lds((const unsigned*)((const char*)(gbase) + (voff)[_i]), (PG8_LAS unsigned*)(lds + (bufoff) + ldsw + _i * 8192), 16, 0, 0); } while (0)
; #define PG8_LDA(dst, b, h) do { _Pragma("unroll") for (int m = 0; m < 4; ++m) _Pragma("unroll") for (int k = 0; k < 2; ++k) dst[m][k] = *(const PG8_LAS bf16x8*)(lds + PG8_SA(b, h) + aoff + m * 2048 + k * 1024); } while (0)
; #define PG8_MMA(ai, bj, At, Bt) do { __builtin_amdgcn_s_setprio(1); _Pragma("unroll") for (int m = 0; m < 4; ++m) _Pragma("unroll") for (int n = 0; n < 2; ++n) _Pragma("unroll") for (int k = 0; k < 2; ++k) \
;         acc[ai][bj][m][n] = __builtin_amdgcn_mfma_f32_16x16x32_bf16(Bt[n][k], At[m][k], acc[ai][bj][m][n], 0, 0, 0); __builtin_amdgcn_s_setprio(0); } while (0)
; #define PG8_WAIT_V(n) asm volatile("s_waitcnt vmcnt(" #n ")" ::: "memory")
; #define PG8_WAIT_L(n) asm volatile("s_waitcnt lgkmcnt(" #n ")" ::: "memory")
; #define PG8_BAR __builtin_amdgcn_s_barrier()
; #define PG8_SCHED __builtin_amdgcn_sched_barrier(0)
; template <class Epi, class Sched, bool ALIGN_EPI = false, bool SP2 = false>
; __device__ __forceinline__ void gemm_phase(PG8_LAS unsigned char* lds, const Gemm g, const Sched& S, const Epi& E) {
;     ...
;             PG8_WAIT_V(8); PG8_WAIT_L(0); PG8_BAR; PG8_MMA(0, 0, At, B0); PG8_MMA(0, 1, At, B1); PG8_BAR; PG8_SCHED;
;             PG8_LDA(At, 0, 1); PG8_STAGE(PG8_SB(0, 0), b2, voffB); PG8_STAGE(PG8_SB(0, 1), b2 + hstepB, voffB); PG8_STAGE(PG8_SA(0, 0), a2, voffA);
;             PG8_WAIT_V(8); PG8_WAIT_L(0); PG8_BAR; PG8_MMA(1, 0, At, B0); PG8_MMA(1, 1, At, B1); PG8_BAR; PG8_SCHED;
	s_setprio 1
	s_waitcnt lgkmcnt(0)
	v_mfma_f32_16x16x32_bf16 v[126:129], v[130:133], v[176:179], v[126:129]
	v_mfma_f32_16x16x32_bf16 v[122:125], v[138:141], v[176:179], v[122:125]
	v_mfma_f32_16x16x32_bf16 v[118:121], v[130:133], v[184:187], v[118:121]
	v_mfma_f32_16x16x32_bf16 v[106:109], v[138:141], v[184:187], v[106:109]
	v_mfma_f32_16x16x32_bf16 v[102:105], v[130:133], v[206:209], v[102:105]
	v_mfma_f32_16x16x32_bf16 v[90:93], v[138:141], v[206:209], v[90:93]
	v_mfma_f32_16x16x32_bf16 v[86:89], v[130:133], v[214:217], v[86:89]
	v_mfma_f32_16x16x32_bf16 v[74:77], v[138:141], v[214:217], v[74:77]
	v_mfma_f32_16x16x32_bf16 v[126:129], v[134:137], v[180:183], v[126:129]
	v_mfma_f32_16x16x32_bf16 v[122:125], v[152:155], v[180:183], v[122:125]
	v_mfma_f32_16x16x32_bf16 v[118:121], v[134:137], v[188:191], v[118:121]
	v_mfma_f32_16x16x32_bf16 v[106:109], v[152:155], v[188:191], v[106:109]
	v_mfma_f32_16x16x32_bf16 v[102:105], v[134:137], v[210:213], v[102:105]
	v_mfma_f32_16x16x32_bf16 v[90:93], v[152:155], v[210:213], v[90:93]
	v_mfma_f32_16x16x32_bf16 v[86:89], v[134:137], v[218:221], v[86:89]
	v_mfma_f32_16x16x32_bf16 v[74:77], v[152:155], v[218:221], v[74:77]
	s_setprio 0
	s_setprio 1
	v_mfma_f32_16x16x32_bf16 v[114:117], v[156:159], v[176:179], v[114:117]
	v_mfma_f32_16x16x32_bf16 v[110:113], v[168:171], v[176:179], v[110:113]
	v_mfma_f32_16x16x32_bf16 v[98:101], v[156:159], v[184:187], v[98:101]
	v_mfma_f32_16x16x32_bf16 v[94:97], v[168:171], v[184:187], v[94:97]
	v_mfma_f32_16x16x32_bf16 v[82:85], v[156:159], v[206:209], v[82:85]
	v_mfma_f32_16x16x32_bf16 v[78:81], v[168:171], v[206:209], v[78:81]
	v_mfma_f32_16x16x32_bf16 v[70:73], v[156:159], v[214:217], v[70:73]
	v_mfma_f32_16x16x32_bf16 v[66:69], v[168:171], v[214:217], v[66:69]
	v_mfma_f32_16x16x32_bf16 v[114:117], v[164:167], v[180:183], v[114:117]
	v_mfma_f32_16x16x32_bf16 v[110:113], v[172:175], v[180:183], v[110:113]
	v_mfma_f32_16x16x32_bf16 v[98:101], v[164:167], v[188:191], v[98:101]
	v_mfma_f32_16x16x32_bf16 v[94:97], v[172:175], v[188:191], v[94:97]
	v_mfma_f32_16x16x32_bf16 v[82:85], v[164:167], v[210:213], v[82:85]
	v_mfma_f32_16x16x32_bf16 v[78:81], v[172:175], v[210:213], v[78:81]
	v_mfma_f32_16x16x32_bf16 v[70:73], v[164:167], v[218:221], v[70:73]
	v_mfma_f32_16x16x32_bf16 v[66:69], v[172:175], v[218:221], v[66:69]
	s_setprio 0
	s_barrier
	s_add_i32 s47, s47, s30
	v_lshl_add_u64 v[192:193], s[26:27], 0, v[0:1]
	s_mov_b32 m0, s47
	ds_read_b128 v[176:179], v163 offset:16384
	ds_read_b128 v[180:183], v163 offset:17408
	ds_read_b128 v[184:187], v163 offset:18432
	ds_read_b128 v[188:191], v163 offset:19456
	ds_read_b128 v[206:209], v163 offset:20480
	ds_read_b128 v[210:213], v163 offset:21504
	ds_read_b128 v[214:217], v163 offset:22528
	ds_read_b128 v[218:221], v163 offset:23552
	global_load_lds_dwordx4 v[192:193], off
	s_add_i32 m0, s47, 0x2000
	s_add_u32 s48, s26, 0x40000
	v_lshl_add_u64 v[222:223], s[26:27], 0, v[142:143]
	s_addc_u32 s49, s27, 0
	s_add_i32 s47, s50, s30
	global_load_lds_dwordx4 v[222:223], off
	v_lshl_add_u64 v[224:225], s[48:49], 0, v[0:1]
	s_mov_b32 m0, s47
	s_nop 0
	global_load_lds_dwordx4 v[224:225], off
	v_lshl_add_u64 v[224:225], s[48:49], 0, v[142:143]
	s_add_i32 m0, s47, 0x2000
	s_nop 0
	global_load_lds_dwordx4 v[224:225], off
	v_lshl_add_u64 v[224:225], s[28:29], 0, v[146:147]
	s_mov_b32 m0, s31
	s_nop 0
	global_load_lds_dwordx4 v[224:225], off
	v_lshl_add_u64 v[224:225], s[28:29], 0, v[144:145]
	s_mov_b32 m0, s34
	s_nop 0
	global_load_lds_dwordx4 v[224:225], off
	s_waitcnt vmcnt(8)
	s_waitcnt lgkmcnt(0)
	s_barrier
	s_setprio 1
	s_waitcnt lgkmcnt(0)
	v_mfma_f32_16x16x32_bf16 v[62:65], v[130:133], v[176:179], v[62:65]
	v_mfma_f32_16x16x32_bf16 v[58:61], v[138:141], v[176:179], v[58:61]
	v_mfma_f32_16x16x32_bf16 v[54:57], v[130:133], v[184:187], v[54:57]
	v_mfma_f32_16x16x32_bf16 v[42:45], v[138:141], v[184:187], v[42:45]
	v_mfma_f32_16x16x32_bf16 v[38:41], v[130:133], v[206:209], v[38:41]
	v_mfma_f32_16x16x32_bf16 v[26:29], v[138:141], v[206:209], v[26:29]
	v_mfma_f32_16x16x32_bf16 v[22:25], v[130:133], v[214:217], v[22:25]
	v_mfma_f32_16x16x32_bf16 v[10:13], v[138:141], v[214:217], v[10:13]
	v_mfma_f32_16x16x32_bf16 v[62:65], v[134:137], v[180:183], v[62:65]
	v_mfma_f32_16x16x32_bf16 v[58:61], v[152:155], v[180:183], v[58:61]
	v_mfma_f32_16x16x32_bf16 v[54:57], v[134:137], v[188:191], v[54:57]
	v_mfma_f32_16x16x32_bf16 v[42:45], v[152:155], v[188:191], v[42:45]
	v_mfma_f32_16x16x32_bf16 v[38:41], v[134:137], v[210:213], v[38:41]
	v_mfma_f32_16x16x32_bf16 v[26:29], v[152:155], v[210:213], v[26:29]
	v_mfma_f32_16x16x32_bf16 v[22:25], v[134:137], v[218:221], v[22:25]
	v_mfma_f32_16x16x32_bf16 v[10:13], v[152:155], v[218:221], v[10:13]
	s_setprio 0
	s_setprio 1
	v_mfma_f32_16x16x32_bf16 v[50:53], v[156:159], v[176:179], v[50:53]
	v_mfma_f32_16x16x32_bf16 v[46:49], v[168:171], v[176:179], v[46:49]
	v_mfma_f32_16x16x32_bf16 v[34:37], v[156:159], v[184:187], v[34:37]
	v_mfma_f32_16x16x32_bf16 v[30:33], v[168:171], v[184:187], v[30:33]
	v_mfma_f32_16x16x32_bf16 v[18:21], v[156:159], v[206:209], v[18:21]
	v_mfma_f32_16x16x32_bf16 v[14:17], v[168:171], v[206:209], v[14:17]
	v_mfma_f32_16x16x32_bf16 v[6:9], v[156:159], v[214:217], v[6:9]
	v_mfma_f32_16x16x32_bf16 v[2:5], v[168:171], v[214:217], v[2:5]
	v_mfma_f32_16x16x32_bf16 v[50:53], v[164:167], v[180:183], v[50:53]
	v_mfma_f32_16x16x32_bf16 v[46:49], v[172:175], v[180:183], v[46:49]
	v_mfma_f32_16x16x32_bf16 v[34:37], v[164:167], v[188:191], v[34:37]
	v_mfma_f32_16x16x32_bf16 v[30:33], v[172:175], v[188:191], v[30:33]
	v_mfma_f32_16x16x32_bf16 v[18:21], v[164:167], v[210:213], v[18:21]
	v_mfma_f32_16x16x32_bf16 v[14:17], v[172:175], v[210:213], v[14:17]
	v_mfma_f32_16x16x32_bf16 v[6:9], v[164:167], v[218:221], v[6:9]
	v_mfma_f32_16x16x32_bf16 v[2:5], v[172:175], v[218:221], v[2:5]
	s_setprio 0
	s_barrier
; #define PG8_STAGE(bufoff, gbase, voff) do { _Pragma("unroll") for (int _i = 0; _i < 2; ++_i) \
;         __builtin_amdgcn_global_load_lds((const unsigned*)((const char*)(gbase) + (voff)[_i]), (PG8_LAS unsigned*)(lds + (bufoff) + ldsw + _i * 8192), 16, 0, 0); } while (0)
; #define PG8_LDA(dst, b, h) do { _Pragma("unroll") for (int m = 0; m < 4; ++m) _Pragma("unroll") for (int k = 0; k < 2; ++k) dst[m][k] = *(const PG8_LAS bf16x8*)(lds + PG8_SA(b, h) + aoff + m * 2048 + k * 1024); } while (0)
; #define PG8_LDB(dst, b, h) do { _Pragma("unroll") for (int n = 0; n < 2; ++n) _Pragma("unroll") for (int k = 0; k < 2; ++k) dst[n][k] = *(const PG8_LAS bf16x8*)(lds + PG8_SB(b, h) + boff + n * 2048 + k * 1024); } while (0)
; #define PG8_MMA(ai, bj, At, Bt) do { __builtin_amdgcn_s_setprio(1); _Pragma("unroll") for (int m = 0; m < 4; ++m) _Pragma("unroll") for (int n = 0; n < 2; ++n) _Pragma("unroll") for (int k = 0; k < 2; ++k) \
;         acc[ai][bj][m][n] = __builtin_amdgcn_mfma_f32_16x16x32_bf16(Bt[n][k], At[m][k], acc[ai][bj][m][n], 0, 0, 0); __builtin_amdgcn_s_setprio(0); } while (0)
; #define PG8_WAIT_V(n) asm volatile("s_waitcnt vmcnt(" #n ")" ::: "memory")
; #define PG8_WAIT_L(n) asm volatile("s_waitcnt lgkmcnt(" #n ")" ::: "memory")
; #define PG8_BAR __builtin_amdgcn_s_barrier()
; #define PG8_SCHED __builtin_amdgcn_sched_barrier(0)
; template <class Epi, class Sched, bool ALIGN_EPI = false, bool SP2 = false>
; __device__ __forceinline__ void gemm_phase(PG8_LAS unsigned char* lds, const Gemm g, const Sched& S, const Epi& E) {
;     ...
;             PG8_LDB(B0, 1, 0); PG8_LDB(B1, 1, 1); PG8_SCHED; PG8_LDA(At, 1, 0); PG8_STAGE(PG8_SA(0, 1), a2 + hstepA, voffA);
;             PG8_WAIT_V(8); PG8_WAIT_L(0); PG8_BAR; PG8_MMA(0, 0, At, B0); PG8_MMA(0, 1, At, B1); PG8_BAR; PG8_SCHED;
	s_add_i32 s47, 0, 0x18000
	s_add_i32 s48, 0, 0x1c000
	v_add_u32_e32 v152, s47, v161
	v_add_u32_e32 v172, s48, v161
	ds_read_b128 v[130:133], v152
	ds_read_b128 v[134:137], v152 offset:1024
	ds_read_b128 v[138:141], v152 offset:2048
	ds_read_b128 v[152:155], v152 offset:3072
	ds_read_b128 v[156:159], v172
	ds_read_b128 v[164:167], v172 offset:1024
	ds_read_b128 v[168:171], v172 offset:2048
	ds_read_b128 v[172:175], v172 offset:3072
	s_add_u32 s28, s28, 0x4000
	s_addc_u32 s29, s29, 0
	s_mov_b32 m0, s35
	v_lshl_add_u64 v[224:225], s[28:29], 0, v[146:147]
	ds_read_b128 v[176:179], v163 offset:32768
	ds_read_b128 v[180:183], v163 offset:33792
	ds_read_b128 v[184:187], v163 offset:34816
	ds_read_b128 v[188:191], v163 offset:35840
	ds_read_b128 v[206:209], v163 offset:36864
	ds_read_b128 v[210:213], v163 offset:37888
	ds_read_b128 v[214:217], v163 offset:38912
	ds_read_b128 v[218:221], v163 offset:39936
	global_load_lds_dwordx4 v[224:225], off
	v_lshl_add_u64 v[224:225], s[28:29], 0, v[144:145]
	s_mov_b32 m0, s36
	s_nop 0
	global_load_lds_dwordx4 v[224:225], off
	s_waitcnt vmcnt(8)
	s_waitcnt lgkmcnt(0)
	s_barrier
	s_setprio 1
	s_waitcnt lgkmcnt(0)
	v_mfma_f32_16x16x32_bf16 v[126:129], v[130:133], v[176:179], v[126:129]
	v_mfma_f32_16x16x32_bf16 v[122:125], v[138:141], v[176:179], v[122:125]
	v_mfma_f32_16x16x32_bf16 v[118:121], v[130:133], v[184:187], v[118:121]
	v_mfma_f32_16x16x32_bf16 v[106:109], v[138:141], v[184:187], v[106:109]
	v_mfma_f32_16x16x32_bf16 v[102:105], v[130:133], v[206:209], v[102:105]
	v_mfma_f32_16x16x32_bf16 v[90:93], v[138:141], v[206:209], v[90:93]
	v_mfma_f32_16x16x32_bf16 v[86:89], v[130:133], v[214:217], v[86:89]
	v_mfma_f32_16x16x32_bf16 v[74:77], v[138:141], v[214:217], v[74:77]
	v_mfma_f32_16x16x32_bf16 v[126:129], v[134:137], v[180:183], v[126:129]
	v_mfma_f32_16x16x32_bf16 v[122:125], v[152:155], v[180:183], v[122:125]
	v_mfma_f32_16x16x32_bf16 v[118:121], v[134:137], v[188:191], v[118:121]
	v_mfma_f32_16x16x32_bf16 v[106:109], v[152:155], v[188:191], v[106:109]
	v_mfma_f32_16x16x32_bf16 v[102:105], v[134:137], v[210:213], v[102:105]
	v_mfma_f32_16x16x32_bf16 v[90:93], v[152:155], v[210:213], v[90:93]
	v_mfma_f32_16x16x32_bf16 v[86:89], v[134:137], v[218:221], v[86:89]
	v_mfma_f32_16x16x32_bf16 v[74:77], v[152:155], v[218:221], v[74:77]
	s_setprio 0
	s_setprio 1
	v_mfma_f32_16x16x32_bf16 v[114:117], v[156:159], v[176:179], v[114:117]
	v_mfma_f32_16x16x32_bf16 v[110:113], v[168:171], v[176:179], v[110:113]
	v_mfma_f32_16x16x32_bf16 v[98:101], v[156:159], v[184:187], v[98:101]
	v_mfma_f32_16x16x32_bf16 v[94:97], v[168:171], v[184:187], v[94:97]
	v_mfma_f32_16x16x32_bf16 v[82:85], v[156:159], v[206:209], v[82:85]
	v_mfma_f32_16x16x32_bf16 v[78:81], v[168:171], v[206:209], v[78:81]
	v_mfma_f32_16x16x32_bf16 v[70:73], v[156:159], v[214:217], v[70:73]
	v_mfma_f32_16x16x32_bf16 v[66:69], v[168:171], v[214:217], v[66:69]
	v_mfma_f32_16x16x32_bf16 v[114:117], v[164:167], v[180:183], v[114:117]
	v_mfma_f32_16x16x32_bf16 v[110:113], v[172:175], v[180:183], v[110:113]
	v_mfma_f32_16x16x32_bf16 v[98:101], v[164:167], v[188:191], v[98:101]
	v_mfma_f32_16x16x32_bf16 v[94:97], v[172:175], v[188:191], v[94:97]
	v_mfma_f32_16x16x32_bf16 v[82:85], v[164:167], v[210:213], v[82:85]
	v_mfma_f32_16x16x32_bf16 v[78:81], v[172:175], v[210:213], v[78:81]
	v_mfma_f32_16x16x32_bf16 v[70:73], v[164:167], v[218:221], v[70:73]
	v_mfma_f32_16x16x32_bf16 v[66:69], v[172:175], v[218:221], v[66:69]
	s_setprio 0
	s_barrier
; #define PG8_STAGE(bufoff, gbase, voff) do { _Pragma("unroll") for (int _i = 0; _i < 2; ++_i) \
;         __builtin_amdgcn_global_load_lds((const unsigned*)((const char*)(gbase) + (voff)[_i]), (PG8_LAS unsigned*)(lds + (bufoff) + ldsw + _i * 8192), 16, 0, 0); } while (0)
; #define PG8_LDA(dst, b, h) do { _Pragma("unroll") for (int m = 0; m < 4; ++m) _Pragma("unroll") for (int k = 0; k < 2; ++k) dst[m][k] = *(const PG8_LAS bf16x8*)(lds + PG8_SA(b, h) + aoff + m * 2048 + k * 1024); } while (0)
; #define PG8_LDB(dst, b, h) do { _Pragma("unroll") for (int n = 0; n < 2; ++n) _Pragma("unroll") for (int k = 0; k < 2; ++k) dst[n][k] = *(const PG8_LAS bf16x8*)(lds + PG8_SB(b, h) + boff + n * 2048 + k * 1024); } while (0)
; template <class Epi, class Sched, bool ALIGN_EPI = false, bool SP2 = false>
; __device__ __forceinline__ void gemm_phase(PG8_LAS unsigned char* lds, const Gemm g, const Sched& S, const Epi& E) {
;     ...
;         for (int t = 0; t < nt; t += 2) {
;             const bool last = (t == nt - 2);
;             const char* a1 = cA + (size_t)(t + 1) * kstepA;
;             const char* a2 = last ? nA : cA + (size_t)(t + 2) * kstepA; const char* b2 = last ? nB : cB + (size_t)(t + 2) * kstep;
;             const char* a3 = a2 + kstepA; const char* b3 = b2 + kstep;
;             if (last && has_next) S.a_ready(nxt);
;             if constexpr (SP2) {
;             PG8_LDB(B0, 0, 0); PG8_LDB(B1, 0, 1); PG8_SCHED; PG8_LDA(At, 0, 0); PG8_STAGE(PG8_SA(1, 1), a1 + hstepA, voffA);
;             PG8_WAIT_V(8); PG8_WAIT_L(0); PG8_BAR; PG8_MMA(0, 0, At, B0); PG8_MMA(0, 1, At, B1); PG8_BAR; PG8_SCHED;
;             PG8_LDA(At, 0, 1); PG8_STAGE(PG8_SB(0, 0), b2, voffB); PG8_STAGE(PG8_SB(0, 1), b2 + hstepB, voffB); PG8_STAGE(PG8_SA(0, 0), a2, voffA);
;             PG8_WAIT_V(8); PG8_WAIT_L(0); PG8_BAR; PG8_MMA(1, 0, At, B0); PG8_MMA(1, 1, At, B1); PG8_BAR; PG8_SCHED;
;             PG8_LDB(B0, 1, 0); PG8_LDB(B1, 1, 1); PG8_SCHED; PG8_LDA(At, 1, 0); PG8_STAGE(PG8_SA(0, 1), a2 + hstepA, voffA);
;             PG8_WAIT_V(8); PG8_WAIT_L(0); PG8_BAR; PG8_MMA(0, 0, At, B0); PG8_MMA(0, 1, At, B1); PG8_BAR; PG8_SCHED;
;             PG8_LDA(At, 1, 1); PG8_STAGE(PG8_SB(1, 0), b3, voffB); PG8_STAGE(PG8_SB(1, 1), b3 + hstepB, voffB); PG8_STAGE(PG8_SA(1, 0), a3, voffA);
;             PG8_WAIT_V(8); PG8_WAIT_L(0); PG8_BAR; PG8_MMA(1, 0, At, B0); PG8_MMA(1, 1, At, B1); PG8_BAR; PG8_SCHED;
	s_add_i32 s28, s47, s30
	v_lshl_add_u64 v[192:193], v[192:193], 0, s[78:79]
	s_mov_b32 m0, s28
	ds_read_b128 v[176:179], v163 offset:49152
	ds_read_b128 v[180:183], v163 offset:50176
	ds_read_b128 v[184:187], v163 offset:51200
	ds_read_b128 v[188:191], v163 offset:52224
	ds_read_b128 v[206:209], v163 offset:53248
	ds_read_b128 v[210:213], v163 offset:54272
	ds_read_b128 v[214:217], v163 offset:55296
	ds_read_b128 v[218:221], v163 offset:56320
	global_load_lds_dwordx4 v[192:193], off
	s_add_i32 m0, s28, 0x2000
	s_add_u32 s26, s26, 0x40080
	v_lshl_add_u64 v[192:193], v[222:223], 0, s[78:79]
	s_addc_u32 s27, s27, 0
	s_add_i32 s28, s48, s30
	global_load_lds_dwordx4 v[192:193], off
	v_lshl_add_u64 v[192:193], s[26:27], 0, v[0:1]
	s_mov_b32 m0, s28
	s_nop 0
	global_load_lds_dwordx4 v[192:193], off
	v_lshl_add_u64 v[192:193], s[26:27], 0, v[142:143]
	s_add_i32 m0, s28, 0x2000
	s_nop 0
	global_load_lds_dwordx4 v[192:193], off
	v_lshl_add_u64 v[192:193], s[24:25], 0, v[146:147]
	s_mov_b32 m0, s37
	s_nop 0
	global_load_lds_dwordx4 v[192:193], off
	v_lshl_add_u64 v[192:193], s[24:25], 0, v[144:145]
	s_mov_b32 m0, s38
	s_nop 0
	global_load_lds_dwordx4 v[192:193], off
	s_waitcnt vmcnt(8)
	s_waitcnt lgkmcnt(0)
	s_barrier
	s_setprio 1
	s_waitcnt lgkmcnt(0)
	v_mfma_f32_16x16x32_bf16 v[62:65], v[130:133], v[176:179], v[62:65]
	v_mfma_f32_16x16x32_bf16 v[58:61], v[138:141], v[176:179], v[58:61]
	v_mfma_f32_16x16x32_bf16 v[54:57], v[130:133], v[184:187], v[54:57]
	v_mfma_f32_16x16x32_bf16 v[42:45], v[138:141], v[184:187], v[42:45]
	v_mfma_f32_16x16x32_bf16 v[38:41], v[130:133], v[206:209], v[38:41]
	v_mfma_f32_16x16x32_bf16 v[26:29], v[138:141], v[206:209], v[26:29]
	v_mfma_f32_16x16x32_bf16 v[22:25], v[130:133], v[214:217], v[22:25]
	v_mfma_f32_16x16x32_bf16 v[10:13], v[138:141], v[214:217], v[10:13]
	v_mfma_f32_16x16x32_bf16 v[62:65], v[134:137], v[180:183], v[62:65]
	v_mfma_f32_16x16x32_bf16 v[58:61], v[152:155], v[180:183], v[58:61]
	v_mfma_f32_16x16x32_bf16 v[54:57], v[134:137], v[188:191], v[54:57]
	v_mfma_f32_16x16x32_bf16 v[42:45], v[152:155], v[188:191], v[42:45]
	v_mfma_f32_16x16x32_bf16 v[38:41], v[134:137], v[210:213], v[38:41]
	v_mfma_f32_16x16x32_bf16 v[26:29], v[152:155], v[210:213], v[26:29]
	v_mfma_f32_16x16x32_bf16 v[22:25], v[134:137], v[218:221], v[22:25]
	s_add_i32 s46, s46, 2
	v_mfma_f32_16x16x32_bf16 v[10:13], v[152:155], v[218:221], v[10:13]
	s_add_u32 s22, s22, 0x400000
	s_setprio 0
	s_setprio 1
	v_mfma_f32_16x16x32_bf16 v[50:53], v[156:159], v[176:179], v[50:53]
	s_addc_u32 s23, s23, 0
	v_mfma_f32_16x16x32_bf16 v[46:49], v[168:171], v[176:179], v[46:49]
	s_add_u32 s44, s44, 0x100
	v_mfma_f32_16x16x32_bf16 v[34:37], v[156:159], v[184:187], v[34:37]
	s_addc_u32 s45, s45, 0
	v_mfma_f32_16x16x32_bf16 v[30:33], v[168:171], v[184:187], v[30:33]
	s_add_u32 s24, s22, 0x1fc000
	v_mfma_f32_16x16x32_bf16 v[18:21], v[156:159], v[206:209], v[18:21]
	s_addc_u32 s25, s23, 0
	v_mfma_f32_16x16x32_bf16 v[14:17], v[168:171], v[206:209], v[14:17]
	s_cmp_eq_u32 s46, 12
	v_mfma_f32_16x16x32_bf16 v[6:9], v[156:159], v[214:217], v[6:9]
	s_cselect_b32 s28, s42, s24
	v_mfma_f32_16x16x32_bf16 v[2:5], v[168:171], v[214:217], v[2:5]
	s_cselect_b32 s29, s17, s25
	v_mfma_f32_16x16x32_bf16 v[50:53], v[164:167], v[180:183], v[50:53]
	s_cselect_b32 s26, s43, s44
	v_mfma_f32_16x16x32_bf16 v[46:49], v[172:175], v[180:183], v[46:49]
	s_cselect_b32 s27, s15, s45
	v_mfma_f32_16x16x32_bf16 v[34:37], v[164:167], v[188:191], v[34:37]
	s_add_u32 s24, s28, 0x200000
	v_mfma_f32_16x16x32_bf16 v[30:33], v[172:175], v[188:191], v[30:33]
	s_addc_u32 s25, s29, 0
	v_mfma_f32_16x16x32_bf16 v[18:21], v[164:167], v[210:213], v[18:21]
	s_add_i32 s47, 0, 0x10000
	v_mfma_f32_16x16x32_bf16 v[14:17], v[172:175], v[210:213], v[14:17]
	s_add_i32 s50, 0, 0x14000
	v_mfma_f32_16x16x32_bf16 v[6:9], v[164:167], v[218:221], v[6:9]
	s_cmp_gt_u32 s46, 13
	v_mfma_f32_16x16x32_bf16 v[2:5], v[172:175], v[218:221], v[2:5]
	s_setprio 0
	s_barrier
	s_cbranch_scc0 .LBB0_87
	s_and_b64 vcc, exec, s[12:13]
	s_cbranch_vccz .LBB0_90
	s_barrier

; #define PG8_STAGE(bufoff, gbase, voff) do { _Pragma("unroll") for (int _i = 0; _i < 2; ++_i) \
;         __builtin_amdgcn_global_load_lds((const unsigned*)((const char*)(gbase) + (voff)[_i]), (PG8_LAS unsigned*)(lds + (bufoff) + ldsw + _i * 8192), 16, 0, 0); } while (0)
; #define PG8_LDA(dst, b, h) do { _Pragma("unroll") for (int m = 0; m < 4; ++m) _Pragma("unroll") for (int k = 0; k < 2; ++k) dst[m][k] = *(const PG8_LAS bf16x8*)(lds + PG8_SA(b, h) + aoff + m * 2048 + k * 1024); } while (0)
; #define PG8_LDB(dst, b, h) do { _Pragma("unroll") for (int n = 0; n < 2; ++n) _Pragma("unroll") for (int k = 0; k < 2; ++k) dst[n][k] = *(const PG8_LAS bf16x8*)(lds + PG8_SB(b, h) + boff + n * 2048 + k * 1024); } while (0)
; #define PG8_WAIT_V(n) asm volatile("s_waitcnt vmcnt(" #n ")" ::: "memory")
; #define PG8_WAIT_L(n) asm volatile("s_waitcnt lgkmcnt(" #n ")" ::: "memory")
; #define PG8_BAR __builtin_amdgcn_s_barrier()
; #define PG8_SCHED __builtin_amdgcn_sched_barrier(0)
; template <class Epi, class Sched, bool ALIGN_EPI = false, bool SP2 = false>
; __device__ __forceinline__ void gemm_phase(PG8_LAS unsigned char* lds, const Gemm g, const Sched& S, const Epi& E) {
;     ...
;     for (;;) {
;         const bool has_next = S.next(ui + 1, nxt);
;         const char* nA = has_next ? (const char*)g.A + (size_t)nxt.pm * tstepA + (size_t)nxt.pn * pnoffA : cA; const char* nB = has_next ? (const char*)g.Bt + (size_t)nxt.pn * tstepB : cB;
;         for (int t = 0; t < nt; t += 2) {
;             const bool last = (t == nt - 2);
;             const char* a1 = cA + (size_t)(t + 1) * kstepA;
;             const char* a2 = last ? nA : cA + (size_t)(t + 2) * kstepA; const char* b2 = last ? nB : cB + (size_t)(t + 2) * kstep;
;             const char* a3 = a2 + kstepA; const char* b3 = b2 + kstep;
;             if (last && has_next) S.a_ready(nxt);
;             if constexpr (SP2) {
;             PG8_LDB(B0, 0, 0); PG8_LDB(B1, 0, 1); PG8_SCHED; PG8_LDA(At, 0, 0); PG8_STAGE(PG8_SA(1, 1), a1 + hstepA, voffA);
;             PG8_WAIT_V(8); PG8_WAIT_L(0); PG8_BAR; PG8_MMA(0, 0, At, B0); PG8_MMA(0, 1, At, B1); PG8_BAR; PG8_SCHED;
;             PG8_LDA(At, 0, 1); PG8_STAGE(PG8_SB(0, 0), b2, voffB); PG8_STAGE(PG8_SB(0, 1), b2 + hstepB, voffB); PG8_STAGE(PG8_SA(0, 0), a2, voffA);
;             PG8_WAIT_V(8); PG8_WAIT_L(0); PG8_BAR; PG8_MMA(1, 0, At, B0); PG8_MMA(1, 1, At, B1); PG8_BAR; PG8_SCHED;
.LBB0_332:
	s_ashr_i32 s13, s12, 31
	s_lshl_b64 s[14:15], s[12:13], 15
	s_add_u32 s14, s72, s14
	s_addc_u32 s15, s73, s15
	s_and_b64 s[16:17], s[4:5], exec
	s_cselect_b32 s13, s15, s7
	s_cselect_b32 s36, s14, s6
	s_ashr_i32 s11, s10, 31
	s_lshl_b64 s[16:17], s[10:11], 19
	v_readlane_b32 s20, v254, 7
	v_readlane_b32 s21, v254, 8
	s_add_u32 s16, s20, s16
	s_addc_u32 s17, s21, s17
	s_and_b64 s[20:21], s[4:5], exec
	s_cselect_b32 s11, s17, s19
	s_cselect_b32 s37, s16, s18
	s_add_u32 s38, s18, 0x100
	s_addc_u32 s39, s19, 0
	s_add_u32 s6, s6, 0x204000
	s_addc_u32 s7, s7, 0
	s_mov_b32 s40, -2
	s_add_u32 s18, s6, 0x1fc000
	s_addc_u32 s19, s7, 0
	s_cmp_eq_u32 s40, 12
	s_cselect_b32 s22, s36, s18
	s_cselect_b32 s23, s13, s19
	s_cselect_b32 s20, s37, s38
	s_cselect_b32 s21, s11, s39
	s_add_u32 s18, s22, 0x200000
	s_addc_u32 s19, s23, 0
	s_add_i32 s41, 0, 0x10000
	v_add_u32_e32 v0, s41, v149
	s_add_i32 s44, 0, 0x14000
	ds_read_b128 v[142:145], v0
	ds_read_b128 v[152:155], v0 offset:1024
	ds_read_b128 v[156:159], v0 offset:2048
	ds_read_b128 v[160:163], v0 offset:3072
	v_add_u32_e32 v0, s44, v149
	ds_read_b128 v[164:167], v0
	ds_read_b128 v[168:171], v0 offset:1024
	ds_read_b128 v[172:175], v0 offset:2048
	ds_read_b128 v[176:179], v0 offset:3072
	v_lshl_add_u64 v[146:147], s[6:7], 0, v[138:139]
	s_add_i32 m0, s25, 0xc000
	ds_read_b128 v[180:183], v151
	ds_read_b128 v[184:187], v151 offset:1024
	ds_read_b128 v[188:191], v151 offset:2048
	ds_read_b128 v[206:209], v151 offset:3072
	ds_read_b128 v[210:213], v151 offset:4096
	ds_read_b128 v[214:217], v151 offset:5120
	ds_read_b128 v[218:221], v151 offset:6144
	ds_read_b128 v[222:225], v151 offset:7168
	global_load_lds_dwordx4 v[146:147], off
	v_lshl_add_u64 v[146:147], s[6:7], 0, v[140:141]
	s_add_i32 m0, s25, 0xe000
	s_nop 0
	global_load_lds_dwordx4 v[146:147], off
	s_waitcnt vmcnt(8)
	s_waitcnt lgkmcnt(0)
	s_barrier
	s_setprio 1
	s_waitcnt lgkmcnt(0)
	v_mfma_f32_16x16x32_bf16 v[126:129], v[142:145], v[180:183], 0
	v_mfma_f32_16x16x32_bf16 v[122:125], v[156:159], v[180:183], 0
	v_mfma_f32_16x16x32_bf16 v[110:113], v[142:145], v[188:191], 0
	v_mfma_f32_16x16x32_bf16 v[106:109], v[156:159], v[188:191], 0
	v_mfma_f32_16x16x32_bf16 v[94:97], v[142:145], v[210:213], 0
	v_mfma_f32_16x16x32_bf16 v[90:93], v[156:159], v[210:213], 0
	v_mfma_f32_16x16x32_bf16 v[78:81], v[142:145], v[218:221], 0
	v_mfma_f32_16x16x32_bf16 v[74:77], v[156:159], v[218:221], 0
	v_mfma_f32_16x16x32_bf16 v[126:129], v[152:155], v[184:187], v[126:129]
	v_mfma_f32_16x16x32_bf16 v[122:125], v[160:163], v[184:187], v[122:125]
	v_mfma_f32_16x16x32_bf16 v[110:113], v[152:155], v[206:209], v[110:113]
	v_mfma_f32_16x16x32_bf16 v[106:109], v[160:163], v[206:209], v[106:109]
	v_mfma_f32_16x16x32_bf16 v[94:97], v[152:155], v[214:217], v[94:97]
	v_mfma_f32_16x16x32_bf16 v[90:93], v[160:163], v[214:217], v[90:93]
	v_mfma_f32_16x16x32_bf16 v[78:81], v[152:155], v[222:225], v[78:81]
	v_mfma_f32_16x16x32_bf16 v[74:77], v[160:163], v[222:225], v[74:77]
	s_setprio 0
	s_setprio 1
	v_mfma_f32_16x16x32_bf16 v[118:121], v[164:167], v[180:183], 0
	v_mfma_f32_16x16x32_bf16 v[114:117], v[172:175], v[180:183], 0
	v_mfma_f32_16x16x32_bf16 v[102:105], v[164:167], v[188:191], 0
	v_mfma_f32_16x16x32_bf16 v[98:101], v[172:175], v[188:191], 0
	v_mfma_f32_16x16x32_bf16 v[86:89], v[164:167], v[210:213], 0
	v_mfma_f32_16x16x32_bf16 v[82:85], v[172:175], v[210:213], 0
	v_mfma_f32_16x16x32_bf16 v[70:73], v[164:167], v[218:221], 0
	v_mfma_f32_16x16x32_bf16 v[66:69], v[172:175], v[218:221], 0
	v_mfma_f32_16x16x32_bf16 v[118:121], v[168:171], v[184:187], v[118:121]
	v_mfma_f32_16x16x32_bf16 v[114:117], v[176:179], v[184:187], v[114:117]
	v_mfma_f32_16x16x32_bf16 v[102:105], v[168:171], v[206:209], v[102:105]
	v_mfma_f32_16x16x32_bf16 v[98:101], v[176:179], v[206:209], v[98:101]
	v_mfma_f32_16x16x32_bf16 v[86:89], v[168:171], v[214:217], v[86:89]
	v_mfma_f32_16x16x32_bf16 v[82:85], v[176:179], v[214:217], v[82:85]
	v_mfma_f32_16x16x32_bf16 v[70:73], v[168:171], v[222:225], v[70:73]
	v_mfma_f32_16x16x32_bf16 v[66:69], v[176:179], v[222:225], v[66:69]
	s_setprio 0
	s_barrier
	s_add_i32 s41, s41, s24
	v_lshl_add_u64 v[146:147], s[20:21], 0, v[134:135]
	s_mov_b32 m0, s41
	ds_read_b128 v[180:183], v151 offset:16384
	ds_read_b128 v[184:187], v151 offset:17408
	ds_read_b128 v[188:191], v151 offset:18432
	ds_read_b128 v[206:209], v151 offset:19456
	ds_read_b128 v[210:213], v151 offset:20480
	ds_read_b128 v[214:217], v151 offset:21504
	ds_read_b128 v[218:221], v151 offset:22528
	ds_read_b128 v[222:225], v151 offset:23552
	global_load_lds_dwordx4 v[146:147], off
	s_add_i32 m0, s41, 0x2000
	s_add_u32 s42, s20, 0x40000
	v_lshl_add_u64 v[192:193], s[20:21], 0, v[130:131]
	s_addc_u32 s43, s21, 0
	s_add_i32 s41, s44, s24
	global_load_lds_dwordx4 v[192:193], off
	v_lshl_add_u64 v[226:227], s[42:43], 0, v[134:135]
	s_mov_b32 m0, s41
	s_nop 0
	global_load_lds_dwordx4 v[226:227], off
	v_lshl_add_u64 v[226:227], s[42:43], 0, v[130:131]
	s_add_i32 m0, s41, 0x2000
	s_nop 0
	global_load_lds_dwordx4 v[226:227], off
	v_lshl_add_u64 v[226:227], s[22:23], 0, v[136:137]
	s_mov_b32 m0, s25
	s_nop 0
	global_load_lds_dwordx4 v[226:227], off
	v_lshl_add_u64 v[226:227], s[22:23], 0, v[132:133]
	s_mov_b32 m0, s26
	s_nop 0
	global_load_lds_dwordx4 v[226:227], off
	s_waitcnt vmcnt(8)
	s_waitcnt lgkmcnt(0)
	s_barrier
; #define PG8_STAGE(bufoff, gbase, voff) do { _Pragma("unroll") for (int _i = 0; _i < 2; ++_i) \
;         __builtin_amdgcn_global_load_lds((const unsigned*)((const char*)(gbase) + (voff)[_i]), (PG8_LAS unsigned*)(lds + (bufoff) + ldsw + _i * 8192), 16, 0, 0); } while (0)
; #define PG8_LDA(dst, b, h) do { _Pragma("unroll") for (int m = 0; m < 4; ++m) _Pragma("unroll") for (int k = 0; k < 2; ++k) dst[m][k] = *(const PG8_LAS bf16x8*)(lds + PG8_SA(b, h) + aoff + m * 2048 + k * 1024); } while (0)
; #define PG8_LDB(dst, b, h) do { _Pragma("unroll") for (int n = 0; n < 2; ++n) _Pragma("unroll") for (int k = 0; k < 2; ++k) dst[n][k] = *(const PG8_LAS bf16x8*)(lds + PG8_SB(b, h) + boff + n * 2048 + k * 1024); } while (0)
; #define PG8_MMA(ai, bj, At, Bt) do { __builtin_amdgcn_s_setprio(1); _Pragma("unroll") for (int m = 0; m < 4; ++m) _Pragma("unroll") for (int n = 0; n < 2; ++n) _Pragma("unroll") for (int k = 0; k < 2; ++k) \
;         acc[ai][bj][m][n] = __builtin_amdgcn_mfma_f32_16x16x32_bf16(Bt[n][k], At[m][k], acc[ai][bj][m][n], 0, 0, 0); __builtin_amdgcn_s_setprio(0); } while (0)
; #define PG8_WAIT_V(n) asm volatile("s_waitcnt vmcnt(" #n ")" ::: "memory")
; #define PG8_WAIT_L(n) asm volatile("s_waitcnt lgkmcnt(" #n ")" ::: "memory")
; #define PG8_BAR __builtin_amdgcn_s_barrier()
; #define PG8_SCHED __builtin_amdgcn_sched_barrier(0)
; template <class Epi, class Sched, bool ALIGN_EPI = false, bool SP2 = false>
; __device__ __forceinline__ void gemm_phase(PG8_LAS unsigned char* lds, const Gemm g, const Sched& S, const Epi& E) {
;     ...
;             PG8_WAIT_V(8); PG8_WAIT_L(0); PG8_BAR; PG8_MMA(1, 0, At, B0); PG8_MMA(1, 1, At, B1); PG8_BAR; PG8_SCHED;
;             PG8_LDB(B0, 1, 0); PG8_LDB(B1, 1, 1); PG8_SCHED; PG8_LDA(At, 1, 0); PG8_STAGE(PG8_SA(0, 1), a2 + hstepA, voffA);
;             PG8_WAIT_V(8); PG8_WAIT_L(0); PG8_BAR; PG8_MMA(0, 0, At, B0); PG8_MMA(0, 1, At, B1); PG8_BAR; PG8_SCHED;
	s_setprio 1
	s_waitcnt lgkmcnt(0)
	v_mfma_f32_16x16x32_bf16 v[62:65], v[142:145], v[180:183], 0
	v_mfma_f32_16x16x32_bf16 v[58:61], v[156:159], v[180:183], 0
	v_mfma_f32_16x16x32_bf16 v[46:49], v[142:145], v[188:191], 0
	v_mfma_f32_16x16x32_bf16 v[42:45], v[156:159], v[188:191], 0
	v_mfma_f32_16x16x32_bf16 v[30:33], v[142:145], v[210:213], 0
	v_mfma_f32_16x16x32_bf16 v[26:29], v[156:159], v[210:213], 0
	v_mfma_f32_16x16x32_bf16 v[14:17], v[142:145], v[218:221], 0
	v_mfma_f32_16x16x32_bf16 v[10:13], v[156:159], v[218:221], 0
	v_mfma_f32_16x16x32_bf16 v[62:65], v[152:155], v[184:187], v[62:65]
	v_mfma_f32_16x16x32_bf16 v[58:61], v[160:163], v[184:187], v[58:61]
	v_mfma_f32_16x16x32_bf16 v[46:49], v[152:155], v[206:209], v[46:49]
	v_mfma_f32_16x16x32_bf16 v[42:45], v[160:163], v[206:209], v[42:45]
	v_mfma_f32_16x16x32_bf16 v[30:33], v[152:155], v[214:217], v[30:33]
	v_mfma_f32_16x16x32_bf16 v[26:29], v[160:163], v[214:217], v[26:29]
	v_mfma_f32_16x16x32_bf16 v[14:17], v[152:155], v[222:225], v[14:17]
	v_mfma_f32_16x16x32_bf16 v[10:13], v[160:163], v[222:225], v[10:13]
	s_setprio 0
	s_setprio 1
	v_mfma_f32_16x16x32_bf16 v[54:57], v[164:167], v[180:183], 0
	v_mfma_f32_16x16x32_bf16 v[50:53], v[172:175], v[180:183], 0
	v_mfma_f32_16x16x32_bf16 v[38:41], v[164:167], v[188:191], 0
	v_mfma_f32_16x16x32_bf16 v[34:37], v[172:175], v[188:191], 0
	v_mfma_f32_16x16x32_bf16 v[22:25], v[164:167], v[210:213], 0
	v_mfma_f32_16x16x32_bf16 v[18:21], v[172:175], v[210:213], 0
	v_mfma_f32_16x16x32_bf16 v[6:9], v[164:167], v[218:221], 0
	v_mfma_f32_16x16x32_bf16 v[2:5], v[172:175], v[218:221], 0
	v_mfma_f32_16x16x32_bf16 v[54:57], v[168:171], v[184:187], v[54:57]
	v_mfma_f32_16x16x32_bf16 v[50:53], v[176:179], v[184:187], v[50:53]
	v_mfma_f32_16x16x32_bf16 v[38:41], v[168:171], v[206:209], v[38:41]
	v_mfma_f32_16x16x32_bf16 v[34:37], v[176:179], v[206:209], v[34:37]
	v_mfma_f32_16x16x32_bf16 v[22:25], v[168:171], v[214:217], v[22:25]
	v_mfma_f32_16x16x32_bf16 v[18:21], v[176:179], v[214:217], v[18:21]
	v_mfma_f32_16x16x32_bf16 v[6:9], v[168:171], v[222:225], v[6:9]
	v_mfma_f32_16x16x32_bf16 v[2:5], v[176:179], v[222:225], v[2:5]
	s_setprio 0
	s_barrier
	s_add_i32 s41, 0, 0x18000
	v_add_u32_e32 v0, s41, v149
	s_add_i32 s42, 0, 0x1c000
	ds_read_b128 v[142:145], v0
	ds_read_b128 v[152:155], v0 offset:1024
	ds_read_b128 v[156:159], v0 offset:2048
	ds_read_b128 v[160:163], v0 offset:3072
	v_add_u32_e32 v0, s42, v149
	ds_read_b128 v[164:167], v0
	ds_read_b128 v[168:171], v0 offset:1024
	ds_read_b128 v[172:175], v0 offset:2048
	ds_read_b128 v[176:179], v0 offset:3072
	s_add_u32 s22, s22, 0x4000
	s_addc_u32 s23, s23, 0
	s_mov_b32 m0, s27
	v_lshl_add_u64 v[226:227], s[22:23], 0, v[136:137]
	ds_read_b128 v[180:183], v151 offset:32768
	ds_read_b128 v[184:187], v151 offset:33792
	ds_read_b128 v[188:191], v151 offset:34816
	ds_read_b128 v[206:209], v151 offset:35840
	ds_read_b128 v[210:213], v151 offset:36864
	ds_read_b128 v[214:217], v151 offset:37888
	ds_read_b128 v[218:221], v151 offset:38912
	ds_read_b128 v[222:225], v151 offset:39936
	global_load_lds_dwordx4 v[226:227], off
	v_lshl_add_u64 v[226:227], s[22:23], 0, v[132:133]
	s_mov_b32 m0, s28
	s_nop 0
	global_load_lds_dwordx4 v[226:227], off
	s_waitcnt vmcnt(8)
	s_waitcnt lgkmcnt(0)
	s_barrier
	s_setprio 1
	s_waitcnt lgkmcnt(0)
	v_mfma_f32_16x16x32_bf16 v[126:129], v[142:145], v[180:183], v[126:129]
	v_mfma_f32_16x16x32_bf16 v[122:125], v[156:159], v[180:183], v[122:125]
	v_mfma_f32_16x16x32_bf16 v[110:113], v[142:145], v[188:191], v[110:113]
	v_mfma_f32_16x16x32_bf16 v[106:109], v[156:159], v[188:191], v[106:109]
	v_mfma_f32_16x16x32_bf16 v[94:97], v[142:145], v[210:213], v[94:97]
	v_mfma_f32_16x16x32_bf16 v[90:93], v[156:159], v[210:213], v[90:93]
	v_mfma_f32_16x16x32_bf16 v[78:81], v[142:145], v[218:221], v[78:81]
	v_mfma_f32_16x16x32_bf16 v[74:77], v[156:159], v[218:221], v[74:77]
	v_mfma_f32_16x16x32_bf16 v[126:129], v[152:155], v[184:187], v[126:129]
	v_mfma_f32_16x16x32_bf16 v[122:125], v[160:163], v[184:187], v[122:125]
	v_mfma_f32_16x16x32_bf16 v[110:113], v[152:155], v[206:209], v[110:113]
	v_mfma_f32_16x16x32_bf16 v[106:109], v[160:163], v[206:209], v[106:109]
	v_mfma_f32_16x16x32_bf16 v[94:97], v[152:155], v[214:217], v[94:97]
	v_mfma_f32_16x16x32_bf16 v[90:93], v[160:163], v[214:217], v[90:93]
	v_mfma_f32_16x16x32_bf16 v[78:81], v[152:155], v[222:225], v[78:81]
	v_mfma_f32_16x16x32_bf16 v[74:77], v[160:163], v[222:225], v[74:77]
	s_setprio 0
	s_setprio 1
	v_mfma_f32_16x16x32_bf16 v[118:121], v[164:167], v[180:183], v[118:121]
	v_mfma_f32_16x16x32_bf16 v[114:117], v[172:175], v[180:183], v[114:117]
	v_mfma_f32_16x16x32_bf16 v[102:105], v[164:167], v[188:191], v[102:105]
	v_mfma_f32_16x16x32_bf16 v[98:101], v[172:175], v[188:191], v[98:101]
	v_mfma_f32_16x16x32_bf16 v[86:89], v[164:167], v[210:213], v[86:89]
	v_mfma_f32_16x16x32_bf16 v[82:85], v[172:175], v[210:213], v[82:85]
	v_mfma_f32_16x16x32_bf16 v[70:73], v[164:167], v[218:221], v[70:73]
	v_mfma_f32_16x16x32_bf16 v[66:69], v[172:175], v[218:221], v[66:69]
	v_mfma_f32_16x16x32_bf16 v[118:121], v[168:171], v[184:187], v[118:121]
	v_mfma_f32_16x16x32_bf16 v[114:117], v[176:179], v[184:187], v[114:117]
	v_mfma_f32_16x16x32_bf16 v[102:105], v[168:171], v[206:209], v[102:105]
	v_mfma_f32_16x16x32_bf16 v[98:101], v[176:179], v[206:209], v[98:101]
	v_mfma_f32_16x16x32_bf16 v[86:89], v[168:171], v[214:217], v[86:89]
	v_mfma_f32_16x16x32_bf16 v[82:85], v[176:179], v[214:217], v[82:85]
	v_mfma_f32_16x16x32_bf16 v[70:73], v[168:171], v[222:225], v[70:73]
	v_mfma_f32_16x16x32_bf16 v[66:69], v[176:179], v[222:225], v[66:69]
	s_setprio 0
	s_barrier
; #define PG8_STAGE(bufoff, gbase, voff) do { _Pragma("unroll") for (int _i = 0; _i < 2; ++_i) \
;         __builtin_amdgcn_global_load_lds((const unsigned*)((const char*)(gbase) + (voff)[_i]), (PG8_LAS unsigned*)(lds + (bufoff) + ldsw + _i * 8192), 16, 0, 0); } while (0)
; #define PG8_LDA(dst, b, h) do { _Pragma("unroll") for (int m = 0; m < 4; ++m) _Pragma("unroll") for (int k = 0; k < 2; ++k) dst[m][k] = *(const PG8_LAS bf16x8*)(lds + PG8_SA(b, h) + aoff + m * 2048 + k * 1024); } while (0)
; #define PG8_LDB(dst, b, h) do { _Pragma("unroll") for (int n = 0; n < 2; ++n) _Pragma("unroll") for (int k = 0; k < 2; ++k) dst[n][k] = *(const PG8_LAS bf16x8*)(lds + PG8_SB(b, h) + boff + n * 2048 + k * 1024); } while (0)
; template <class Epi, class Sched, bool ALIGN_EPI = false, bool SP2 = false>
; __device__ __forceinline__ void gemm_phase(PG8_LAS unsigned char* lds, const Gemm g, const Sched& S, const Epi& E) {
;     ...
;         for (int t = 0; t < nt; t += 2) {
;             const bool last = (t == nt - 2);
;             const char* a1 = cA + (size_t)(t + 1) * kstepA;
;             const char* a2 = last ? nA : cA + (size_t)(t + 2) * kstepA; const char* b2 = last ? nB : cB + (size_t)(t + 2) * kstep;
;             const char* a3 = a2 + kstepA; const char* b3 = b2 + kstep;
;             if (last && has_next) S.a_ready(nxt);
;             if constexpr (SP2) {
;             PG8_LDB(B0, 0, 0); PG8_LDB(B1, 0, 1); PG8_SCHED; PG8_LDA(At, 0, 0); PG8_STAGE(PG8_SA(1, 1), a1 + hstepA, voffA);
;             PG8_WAIT_V(8); PG8_WAIT_L(0); PG8_BAR; PG8_MMA(0, 0, At, B0); PG8_MMA(0, 1, At, B1); PG8_BAR; PG8_SCHED;
;             PG8_LDA(At, 0, 1); PG8_STAGE(PG8_SB(0, 0), b2, voffB); PG8_STAGE(PG8_SB(0, 1), b2 + hstepB, voffB); PG8_STAGE(PG8_SA(0, 0), a2, voffA);
;             PG8_WAIT_V(8); PG8_WAIT_L(0); PG8_BAR; PG8_MMA(1, 0, At, B0); PG8_MMA(1, 1, At, B1); PG8_BAR; PG8_SCHED;
;             PG8_LDB(B0, 1, 0); PG8_LDB(B1, 1, 1); PG8_SCHED; PG8_LDA(At, 1, 0); PG8_STAGE(PG8_SA(0, 1), a2 + hstepA, voffA);
;             PG8_WAIT_V(8); PG8_WAIT_L(0); PG8_BAR; PG8_MMA(0, 0, At, B0); PG8_MMA(0, 1, At, B1); PG8_BAR; PG8_SCHED;
;             PG8_LDA(At, 1, 1); PG8_STAGE(PG8_SB(1, 0), b3, voffB); PG8_STAGE(PG8_SB(1, 1), b3 + hstepB, voffB); PG8_STAGE(PG8_SA(1, 0), a3, voffA);
;             PG8_WAIT_V(8); PG8_WAIT_L(0); PG8_BAR; PG8_MMA(1, 0, At, B0); PG8_MMA(1, 1, At, B1); PG8_BAR; PG8_SCHED;
	s_add_i32 s22, s41, s24
	v_lshl_add_u64 v[146:147], v[146:147], 0, s[78:79]
	s_mov_b32 m0, s22
	ds_read_b128 v[180:183], v151 offset:49152
	ds_read_b128 v[184:187], v151 offset:50176
	ds_read_b128 v[188:191], v151 offset:51200
	ds_read_b128 v[206:209], v151 offset:52224
	ds_read_b128 v[210:213], v151 offset:53248
	ds_read_b128 v[214:217], v151 offset:54272
	ds_read_b128 v[218:221], v151 offset:55296
	ds_read_b128 v[222:225], v151 offset:56320
	global_load_lds_dwordx4 v[146:147], off
	s_add_i32 m0, s22, 0x2000
	s_add_u32 s20, s20, 0x40080
	v_lshl_add_u64 v[146:147], v[192:193], 0, s[78:79]
	s_addc_u32 s21, s21, 0
	s_add_i32 s22, s42, s24
	global_load_lds_dwordx4 v[146:147], off
	v_lshl_add_u64 v[146:147], s[20:21], 0, v[134:135]
	s_mov_b32 m0, s22
	s_nop 0
	global_load_lds_dwordx4 v[146:147], off
	v_lshl_add_u64 v[146:147], s[20:21], 0, v[130:131]
	s_add_i32 m0, s22, 0x2000
	s_nop 0
	global_load_lds_dwordx4 v[146:147], off
	v_lshl_add_u64 v[146:147], s[18:19], 0, v[136:137]
	s_mov_b32 m0, s29
	s_nop 0
	global_load_lds_dwordx4 v[146:147], off
	v_lshl_add_u64 v[146:147], s[18:19], 0, v[132:133]
	s_mov_b32 m0, s30
	s_nop 0
	global_load_lds_dwordx4 v[146:147], off
	s_waitcnt vmcnt(8)
	s_waitcnt lgkmcnt(0)
	s_barrier
	s_setprio 1
	s_waitcnt lgkmcnt(0)
	v_mfma_f32_16x16x32_bf16 v[62:65], v[142:145], v[180:183], v[62:65]
	v_mfma_f32_16x16x32_bf16 v[58:61], v[156:159], v[180:183], v[58:61]
	v_mfma_f32_16x16x32_bf16 v[46:49], v[142:145], v[188:191], v[46:49]
	v_mfma_f32_16x16x32_bf16 v[42:45], v[156:159], v[188:191], v[42:45]
	v_mfma_f32_16x16x32_bf16 v[30:33], v[142:145], v[210:213], v[30:33]
	v_mfma_f32_16x16x32_bf16 v[26:29], v[156:159], v[210:213], v[26:29]
	v_mfma_f32_16x16x32_bf16 v[14:17], v[142:145], v[218:221], v[14:17]
	v_mfma_f32_16x16x32_bf16 v[10:13], v[156:159], v[218:221], v[10:13]
	v_mfma_f32_16x16x32_bf16 v[62:65], v[152:155], v[184:187], v[62:65]
	v_mfma_f32_16x16x32_bf16 v[58:61], v[160:163], v[184:187], v[58:61]
	v_mfma_f32_16x16x32_bf16 v[46:49], v[152:155], v[206:209], v[46:49]
	v_mfma_f32_16x16x32_bf16 v[42:45], v[160:163], v[206:209], v[42:45]
	v_mfma_f32_16x16x32_bf16 v[30:33], v[152:155], v[214:217], v[30:33]
	v_mfma_f32_16x16x32_bf16 v[26:29], v[160:163], v[214:217], v[26:29]
	v_mfma_f32_16x16x32_bf16 v[14:17], v[152:155], v[222:225], v[14:17]
	v_mfma_f32_16x16x32_bf16 v[10:13], v[160:163], v[222:225], v[10:13]
	s_setprio 0
	s_setprio 1
	v_mfma_f32_16x16x32_bf16 v[54:57], v[164:167], v[180:183], v[54:57]
	s_add_i32 s40, s40, 2
	v_mfma_f32_16x16x32_bf16 v[50:53], v[172:175], v[180:183], v[50:53]
	s_add_u32 s38, s38, 0x100
	v_mfma_f32_16x16x32_bf16 v[38:41], v[164:167], v[188:191], v[38:41]
	s_addc_u32 s39, s39, 0
	v_mfma_f32_16x16x32_bf16 v[34:37], v[172:175], v[188:191], v[34:37]
	s_add_u32 s6, s6, 0x400000
	v_mfma_f32_16x16x32_bf16 v[22:25], v[164:167], v[210:213], v[22:25]
	s_addc_u32 s7, s7, 0
	v_mfma_f32_16x16x32_bf16 v[18:21], v[172:175], v[210:213], v[18:21]
	s_add_u32 s18, s6, 0x1fc000
	v_mfma_f32_16x16x32_bf16 v[6:9], v[164:167], v[218:221], v[6:9]
	s_addc_u32 s19, s7, 0
	v_mfma_f32_16x16x32_bf16 v[2:5], v[172:175], v[218:221], v[2:5]
	s_cmp_eq_u32 s40, 12
	v_mfma_f32_16x16x32_bf16 v[54:57], v[168:171], v[184:187], v[54:57]
	s_cselect_b32 s22, s36, s18
	v_mfma_f32_16x16x32_bf16 v[50:53], v[176:179], v[184:187], v[50:53]
	s_cselect_b32 s23, s13, s19
	v_mfma_f32_16x16x32_bf16 v[38:41], v[168:171], v[206:209], v[38:41]
	s_cselect_b32 s20, s37, s38
	v_mfma_f32_16x16x32_bf16 v[34:37], v[176:179], v[206:209], v[34:37]
	s_cselect_b32 s21, s11, s39
	v_mfma_f32_16x16x32_bf16 v[22:25], v[168:171], v[214:217], v[22:25]
	s_add_u32 s18, s22, 0x200000
	v_mfma_f32_16x16x32_bf16 v[18:21], v[176:179], v[214:217], v[18:21]
	s_addc_u32 s19, s23, 0
	v_mfma_f32_16x16x32_bf16 v[6:9], v[168:171], v[222:225], v[6:9]
	s_add_i32 s41, 0, 0x10000
	v_mfma_f32_16x16x32_bf16 v[2:5], v[176:179], v[222:225], v[2:5]
	s_setprio 0
	s_barrier
.LBB0_333:
	v_add_u32_e32 v0, s41, v149
	s_add_i32 s44, 0, 0x14000
	ds_read_b128 v[142:145], v0
	ds_read_b128 v[152:155], v0 offset:1024
	ds_read_b128 v[156:159], v0 offset:2048
	ds_read_b128 v[160:163], v0 offset:3072
	v_add_u32_e32 v0, s44, v149
	ds_read_b128 v[164:167], v0
	ds_read_b128 v[168:171], v0 offset:1024
	ds_read_b128 v[172:175], v0 offset:2048
	ds_read_b128 v[176:179], v0 offset:3072
	v_lshl_add_u64 v[146:147], s[6:7], 0, v[138:139]
	s_add_i32 m0, s25, 0xc000
	ds_read_b128 v[180:183], v151
	ds_read_b128 v[184:187], v151 offset:1024
	ds_read_b128 v[188:191], v151 offset:2048
	ds_read_b128 v[206:209], v151 offset:3072
	ds_read_b128 v[210:213], v151 offset:4096
	ds_read_b128 v[214:217], v151 offset:5120
	ds_read_b128 v[218:221], v151 offset:6144
	ds_read_b128 v[222:225], v151 offset:7168
	global_load_lds_dwordx4 v[146:147], off
	v_lshl_add_u64 v[146:147], s[6:7], 0, v[140:141]
	s_add_i32 m0, s25, 0xe000
	s_nop 0
	global_load_lds_dwordx4 v[146:147], off
	s_waitcnt vmcnt(8)
	s_waitcnt lgkmcnt(0)
	s_barrier
; #define PG8_STAGE(bufoff, gbase, voff) do { _Pragma("unroll") for (int _i = 0; _i < 2; ++_i) \
;         __builtin_amdgcn_global_load_lds((const unsigned*)((const char*)(gbase) + (voff)[_i]), (PG8_LAS unsigned*)(lds + (bufoff) + ldsw + _i * 8192), 16, 0, 0); } while (0)
; #define PG8_LDA(dst, b, h) do { _Pragma("unroll") for (int m = 0; m < 4; ++m) _Pragma("unroll") for (int k = 0; k < 2; ++k) dst[m][k] = *(const PG8_LAS bf16x8*)(lds + PG8_SA(b, h) + aoff + m * 2048 + k * 1024); } while (0)
; #define PG8_MMA(ai, bj, At, Bt) do { __builtin_amdgcn_s_setprio(1); _Pragma("unroll") for (int m = 0; m < 4; ++m) _Pragma("unroll") for (int n = 0; n < 2; ++n) _Pragma("unroll") for (int k = 0; k < 2; ++k) \
;         acc[ai][bj][m][n] = __builtin_amdgcn_mfma_f32_16x16x32_bf16(Bt[n][k], At[m][k], acc[ai][bj][m][n], 0, 0, 0); __builtin_amdgcn_s_setprio(0); } while (0)
; #define PG8_WAIT_V(n) asm volatile("s_waitcnt vmcnt(" #n ")" ::: "memory")
; #define PG8_WAIT_L(n) asm volatile("s_waitcnt lgkmcnt(" #n ")" ::: "memory")
; #define PG8_BAR __builtin_amdgcn_s_barrier()
; #define PG8_SCHED __builtin_amdgcn_sched_barrier(0)
; template <class Epi, class Sched, bool ALIGN_EPI = false, bool SP2 = false>
; __device__ __forceinline__ void gemm_phase(PG8_LAS unsigned char* lds, const Gemm g, const Sched& S, const Epi& E) {
;     ...
;             PG8_WAIT_V(8); PG8_WAIT_L(0); PG8_BAR; PG8_MMA(0, 0, At, B0); PG8_MMA(0, 1, At, B1); PG8_BAR; PG8_SCHED;
;             PG8_LDA(At, 0, 1); PG8_STAGE(PG8_SB(0, 0), b2, voffB); PG8_STAGE(PG8_SB(0, 1), b2 + hstepB, voffB); PG8_STAGE(PG8_SA(0, 0), a2, voffA);
;             PG8_WAIT_V(8); PG8_WAIT_L(0); PG8_BAR; PG8_MMA(1, 0, At, B0); PG8_MMA(1, 1, At, B1); PG8_BAR; PG8_SCHED;
	s_setprio 1
	s_waitcnt lgkmcnt(0)
	v_mfma_f32_16x16x32_bf16 v[126:129], v[142:145], v[180:183], v[126:129]
	v_mfma_f32_16x16x32_bf16 v[122:125], v[156:159], v[180:183], v[122:125]
	v_mfma_f32_16x16x32_bf16 v[110:113], v[142:145], v[188:191], v[110:113]
	v_mfma_f32_16x16x32_bf16 v[106:109], v[156:159], v[188:191], v[106:109]
	v_mfma_f32_16x16x32_bf16 v[94:97], v[142:145], v[210:213], v[94:97]
	v_mfma_f32_16x16x32_bf16 v[90:93], v[156:159], v[210:213], v[90:93]
	v_mfma_f32_16x16x32_bf16 v[78:81], v[142:145], v[218:221], v[78:81]
	v_mfma_f32_16x16x32_bf16 v[74:77], v[156:159], v[218:221], v[74:77]
	v_mfma_f32_16x16x32_bf16 v[126:129], v[152:155], v[184:187], v[126:129]
	v_mfma_f32_16x16x32_bf16 v[122:125], v[160:163], v[184:187], v[122:125]
	v_mfma_f32_16x16x32_bf16 v[110:113], v[152:155], v[206:209], v[110:113]
	v_mfma_f32_16x16x32_bf16 v[106:109], v[160:163], v[206:209], v[106:109]
	v_mfma_f32_16x16x32_bf16 v[94:97], v[152:155], v[214:217], v[94:97]
	v_mfma_f32_16x16x32_bf16 v[90:93], v[160:163], v[214:217], v[90:93]
	v_mfma_f32_16x16x32_bf16 v[78:81], v[152:155], v[222:225], v[78:81]
	v_mfma_f32_16x16x32_bf16 v[74:77], v[160:163], v[222:225], v[74:77]
	s_setprio 0
	s_setprio 1
	v_mfma_f32_16x16x32_bf16 v[118:121], v[164:167], v[180:183], v[118:121]
	v_mfma_f32_16x16x32_bf16 v[114:117], v[172:175], v[180:183], v[114:117]
	v_mfma_f32_16x16x32_bf16 v[102:105], v[164:167], v[188:191], v[102:105]
	v_mfma_f32_16x16x32_bf16 v[98:101], v[172:175], v[188:191], v[98:101]
	v_mfma_f32_16x16x32_bf16 v[86:89], v[164:167], v[210:213], v[86:89]
	v_mfma_f32_16x16x32_bf16 v[82:85], v[172:175], v[210:213], v[82:85]
	v_mfma_f32_16x16x32_bf16 v[70:73], v[164:167], v[218:221], v[70:73]
	v_mfma_f32_16x16x32_bf16 v[66:69], v[172:175], v[218:221], v[66:69]
	v_mfma_f32_16x16x32_bf16 v[118:121], v[168:171], v[184:187], v[118:121]
	v_mfma_f32_16x16x32_bf16 v[114:117], v[176:179], v[184:187], v[114:117]
	v_mfma_f32_16x16x32_bf16 v[102:105], v[168:171], v[206:209], v[102:105]
	v_mfma_f32_16x16x32_bf16 v[98:101], v[176:179], v[206:209], v[98:101]
	v_mfma_f32_16x16x32_bf16 v[86:89], v[168:171], v[214:217], v[86:89]
	v_mfma_f32_16x16x32_bf16 v[82:85], v[176:179], v[214:217], v[82:85]
	v_mfma_f32_16x16x32_bf16 v[70:73], v[168:171], v[222:225], v[70:73]
	v_mfma_f32_16x16x32_bf16 v[66:69], v[176:179], v[222:225], v[66:69]
	s_setprio 0
	s_barrier
	s_add_i32 s41, s41, s24
	v_lshl_add_u64 v[146:147], s[20:21], 0, v[134:135]
	s_mov_b32 m0, s41
	ds_read_b128 v[180:183], v151 offset:16384
	ds_read_b128 v[184:187], v151 offset:17408
	ds_read_b128 v[188:191], v151 offset:18432
	ds_read_b128 v[206:209], v151 offset:19456
	ds_read_b128 v[210:213], v151 offset:20480
	ds_read_b128 v[214:217], v151 offset:21504
	ds_read_b128 v[218:221], v151 offset:22528
	ds_read_b128 v[222:225], v151 offset:23552
	global_load_lds_dwordx4 v[146:147], off
	s_add_i32 m0, s41, 0x2000
	s_add_u32 s42, s20, 0x40000
	v_lshl_add_u64 v[192:193], s[20:21], 0, v[130:131]
	s_addc_u32 s43, s21, 0
	s_add_i32 s41, s44, s24
	global_load_lds_dwordx4 v[192:193], off
	v_lshl_add_u64 v[226:227], s[42:43], 0, v[134:135]
	s_mov_b32 m0, s41
	s_nop 0
	global_load_lds_dwordx4 v[226:227], off
	v_lshl_add_u64 v[226:227], s[42:43], 0, v[130:131]
	s_add_i32 m0, s41, 0x2000
	s_nop 0
	global_load_lds_dwordx4 v[226:227], off
	v_lshl_add_u64 v[226:227], s[22:23], 0, v[136:137]
	s_mov_b32 m0, s25
	s_nop 0
	global_load_lds_dwordx4 v[226:227], off
	v_lshl_add_u64 v[226:227], s[22:23], 0, v[132:133]
	s_mov_b32 m0, s26
	s_nop 0
	global_load_lds_dwordx4 v[226:227], off
	s_waitcnt vmcnt(8)
	s_waitcnt lgkmcnt(0)
	s_barrier
	s_setprio 1
	s_waitcnt lgkmcnt(0)
	v_mfma_f32_16x16x32_bf16 v[62:65], v[142:145], v[180:183], v[62:65]
	v_mfma_f32_16x16x32_bf16 v[58:61], v[156:159], v[180:183], v[58:61]
	v_mfma_f32_16x16x32_bf16 v[46:49], v[142:145], v[188:191], v[46:49]
	v_mfma_f32_16x16x32_bf16 v[42:45], v[156:159], v[188:191], v[42:45]
	v_mfma_f32_16x16x32_bf16 v[30:33], v[142:145], v[210:213], v[30:33]
	v_mfma_f32_16x16x32_bf16 v[26:29], v[156:159], v[210:213], v[26:29]
	v_mfma_f32_16x16x32_bf16 v[14:17], v[142:145], v[218:221], v[14:17]
	v_mfma_f32_16x16x32_bf16 v[10:13], v[156:159], v[218:221], v[10:13]
	v_mfma_f32_16x16x32_bf16 v[62:65], v[152:155], v[184:187], v[62:65]
	v_mfma_f32_16x16x32_bf16 v[58:61], v[160:163], v[184:187], v[58:61]
	v_mfma_f32_16x16x32_bf16 v[46:49], v[152:155], v[206:209], v[46:49]
	v_mfma_f32_16x16x32_bf16 v[42:45], v[160:163], v[206:209], v[42:45]
	v_mfma_f32_16x16x32_bf16 v[30:33], v[152:155], v[214:217], v[30:33]
	v_mfma_f32_16x16x32_bf16 v[26:29], v[160:163], v[214:217], v[26:29]
	v_mfma_f32_16x16x32_bf16 v[14:17], v[152:155], v[222:225], v[14:17]
	v_mfma_f32_16x16x32_bf16 v[10:13], v[160:163], v[222:225], v[10:13]
	s_setprio 0
	s_setprio 1
	v_mfma_f32_16x16x32_bf16 v[54:57], v[164:167], v[180:183], v[54:57]
	v_mfma_f32_16x16x32_bf16 v[50:53], v[172:175], v[180:183], v[50:53]
	v_mfma_f32_16x16x32_bf16 v[38:41], v[164:167], v[188:191], v[38:41]
	v_mfma_f32_16x16x32_bf16 v[34:37], v[172:175], v[188:191], v[34:37]
	v_mfma_f32_16x16x32_bf16 v[22:25], v[164:167], v[210:213], v[22:25]
	v_mfma_f32_16x16x32_bf16 v[18:21], v[172:175], v[210:213], v[18:21]
	v_mfma_f32_16x16x32_bf16 v[6:9], v[164:167], v[218:221], v[6:9]
	v_mfma_f32_16x16x32_bf16 v[2:5], v[172:175], v[218:221], v[2:5]
	v_mfma_f32_16x16x32_bf16 v[54:57], v[168:171], v[184:187], v[54:57]
	v_mfma_f32_16x16x32_bf16 v[50:53], v[176:179], v[184:187], v[50:53]
	v_mfma_f32_16x16x32_bf16 v[38:41], v[168:171], v[206:209], v[38:41]
	v_mfma_f32_16x16x32_bf16 v[34:37], v[176:179], v[206:209], v[34:37]
	v_mfma_f32_16x16x32_bf16 v[22:25], v[168:171], v[214:217], v[22:25]
	v_mfma_f32_16x16x32_bf16 v[18:21], v[176:179], v[214:217], v[18:21]
	v_mfma_f32_16x16x32_bf16 v[6:9], v[168:171], v[222:225], v[6:9]
	v_mfma_f32_16x16x32_bf16 v[2:5], v[176:179], v[222:225], v[2:5]
	s_setprio 0
	s_barrier
; #define PG8_STAGE(bufoff, gbase, voff) do { _Pragma("unroll") for (int _i = 0; _i < 2; ++_i) \
;         __builtin_amdgcn_global_load_lds((const unsigned*)((const char*)(gbase) + (voff)[_i]), (PG8_LAS unsigned*)(lds + (bufoff) + ldsw + _i * 8192), 16, 0, 0); } while (0)
; #define PG8_LDA(dst, b, h) do { _Pragma("unroll") for (int m = 0; m < 4; ++m) _Pragma("unroll") for (int k = 0; k < 2; ++k) dst[m][k] = *(const PG8_LAS bf16x8*)(lds + PG8_SA(b, h) + aoff + m * 2048 + k * 1024); } while (0)
; #define PG8_LDB(dst, b, h) do { _Pragma("unroll") for (int n = 0; n < 2; ++n) _Pragma("unroll") for (int k = 0; k < 2; ++k) dst[n][k] = *(const PG8_LAS bf16x8*)(lds + PG8_SB(b, h) + boff + n * 2048 + k * 1024); } while (0)
; #define PG8_MMA(ai, bj, At, Bt) do { __builtin_amdgcn_s_setprio(1); _Pragma("unroll") for (int m = 0; m < 4; ++m) _Pragma("unroll") for (int n = 0; n < 2; ++n) _Pragma("unroll") for (int k = 0; k < 2; ++k) \
;         acc[ai][bj][m][n] = __builtin_amdgcn_mfma_f32_16x16x32_bf16(Bt[n][k], At[m][k], acc[ai][bj][m][n], 0, 0, 0); __builtin_amdgcn_s_setprio(0); } while (0)
; #define PG8_WAIT_V(n) asm volatile("s_waitcnt vmcnt(" #n ")" ::: "memory")
; #define PG8_WAIT_L(n) asm volatile("s_waitcnt lgkmcnt(" #n ")" ::: "memory")
; #define PG8_BAR __builtin_amdgcn_s_barrier()
; #define PG8_SCHED __builtin_amdgcn_sched_barrier(0)
; template <class Epi, class Sched, bool ALIGN_EPI = false, bool SP2 = false>
; __device__ __forceinline__ void gemm_phase(PG8_LAS unsigned char* lds, const Gemm g, const Sched& S, const Epi& E) {
;     ...
;             PG8_LDB(B0, 1, 0); PG8_LDB(B1, 1, 1); PG8_SCHED; PG8_LDA(At, 1, 0); PG8_STAGE(PG8_SA(0, 1), a2 + hstepA, voffA);
;             PG8_WAIT_V(8); PG8_WAIT_L(0); PG8_BAR; PG8_MMA(0, 0, At, B0); PG8_MMA(0, 1, At, B1); PG8_BAR; PG8_SCHED;
	s_add_i32 s41, 0, 0x18000
	v_add_u32_e32 v0, s41, v149
	s_add_i32 s42, 0, 0x1c000
	ds_read_b128 v[142:145], v0
	ds_read_b128 v[152:155], v0 offset:1024
	ds_read_b128 v[156:159], v0 offset:2048
	ds_read_b128 v[160:163], v0 offset:3072
	v_add_u32_e32 v0, s42, v149
	ds_read_b128 v[164:167], v0
	ds_read_b128 v[168:171], v0 offset:1024
	ds_read_b128 v[172:175], v0 offset:2048
	ds_read_b128 v[176:179], v0 offset:3072
	s_add_u32 s22, s22, 0x4000
	s_addc_u32 s23, s23, 0
	s_mov_b32 m0, s27
	v_lshl_add_u64 v[226:227], s[22:23], 0, v[136:137]
	ds_read_b128 v[180:183], v151 offset:32768
	ds_read_b128 v[184:187], v151 offset:33792
	ds_read_b128 v[188:191], v151 offset:34816
	ds_read_b128 v[206:209], v151 offset:35840
	ds_read_b128 v[210:213], v151 offset:36864
	ds_read_b128 v[214:217], v151 offset:37888
	ds_read_b128 v[218:221], v151 offset:38912
	ds_read_b128 v[222:225], v151 offset:39936
	global_load_lds_dwordx4 v[226:227], off
	v_lshl_add_u64 v[226:227], s[22:23], 0, v[132:133]
	s_mov_b32 m0, s28
	s_nop 0
	global_load_lds_dwordx4 v[226:227], off
	s_waitcnt vmcnt(8)
	s_waitcnt lgkmcnt(0)
	s_barrier
	s_setprio 1
	s_waitcnt lgkmcnt(0)
	v_mfma_f32_16x16x32_bf16 v[126:129], v[142:145], v[180:183], v[126:129]
	v_mfma_f32_16x16x32_bf16 v[122:125], v[156:159], v[180:183], v[122:125]
	v_mfma_f32_16x16x32_bf16 v[110:113], v[142:145], v[188:191], v[110:113]
	v_mfma_f32_16x16x32_bf16 v[106:109], v[156:159], v[188:191], v[106:109]
	v_mfma_f32_16x16x32_bf16 v[94:97], v[142:145], v[210:213], v[94:97]
	v_mfma_f32_16x16x32_bf16 v[90:93], v[156:159], v[210:213], v[90:93]
	v_mfma_f32_16x16x32_bf16 v[78:81], v[142:145], v[218:221], v[78:81]
	v_mfma_f32_16x16x32_bf16 v[74:77], v[156:159], v[218:221], v[74:77]
	v_mfma_f32_16x16x32_bf16 v[126:129], v[152:155], v[184:187], v[126:129]
	v_mfma_f32_16x16x32_bf16 v[122:125], v[160:163], v[184:187], v[122:125]
	v_mfma_f32_16x16x32_bf16 v[110:113], v[152:155], v[206:209], v[110:113]
	v_mfma_f32_16x16x32_bf16 v[106:109], v[160:163], v[206:209], v[106:109]
	v_mfma_f32_16x16x32_bf16 v[94:97], v[152:155], v[214:217], v[94:97]
	v_mfma_f32_16x16x32_bf16 v[90:93], v[160:163], v[214:217], v[90:93]
	v_mfma_f32_16x16x32_bf16 v[78:81], v[152:155], v[222:225], v[78:81]
	v_mfma_f32_16x16x32_bf16 v[74:77], v[160:163], v[222:225], v[74:77]
	s_setprio 0
	s_setprio 1
	v_mfma_f32_16x16x32_bf16 v[118:121], v[164:167], v[180:183], v[118:121]
	v_mfma_f32_16x16x32_bf16 v[114:117], v[172:175], v[180:183], v[114:117]
	v_mfma_f32_16x16x32_bf16 v[102:105], v[164:167], v[188:191], v[102:105]
	v_mfma_f32_16x16x32_bf16 v[98:101], v[172:175], v[188:191], v[98:101]
	v_mfma_f32_16x16x32_bf16 v[86:89], v[164:167], v[210:213], v[86:89]
	v_mfma_f32_16x16x32_bf16 v[82:85], v[172:175], v[210:213], v[82:85]
	v_mfma_f32_16x16x32_bf16 v[70:73], v[164:167], v[218:221], v[70:73]
	v_mfma_f32_16x16x32_bf16 v[66:69], v[172:175], v[218:221], v[66:69]
	v_mfma_f32_16x16x32_bf16 v[118:121], v[168:171], v[184:187], v[118:121]
	v_mfma_f32_16x16x32_bf16 v[114:117], v[176:179], v[184:187], v[114:117]
	v_mfma_f32_16x16x32_bf16 v[102:105], v[168:171], v[206:209], v[102:105]
	v_mfma_f32_16x16x32_bf16 v[98:101], v[176:179], v[206:209], v[98:101]
	v_mfma_f32_16x16x32_bf16 v[86:89], v[168:171], v[214:217], v[86:89]
	v_mfma_f32_16x16x32_bf16 v[82:85], v[176:179], v[214:217], v[82:85]
	v_mfma_f32_16x16x32_bf16 v[70:73], v[168:171], v[222:225], v[70:73]
	v_mfma_f32_16x16x32_bf16 v[66:69], v[176:179], v[222:225], v[66:69]
	s_setprio 0
	s_barrier
; #define PG8_STAGE(bufoff, gbase, voff) do { _Pragma("unroll") for (int _i = 0; _i < 2; ++_i) \
;         __builtin_amdgcn_global_load_lds((const unsigned*)((const char*)(gbase) + (voff)[_i]), (PG8_LAS unsigned*)(lds + (bufoff) + ldsw + _i * 8192), 16, 0, 0); } while (0)
; #define PG8_LDA(dst, b, h) do { _Pragma("unroll") for (int m = 0; m < 4; ++m) _Pragma("unroll") for (int k = 0; k < 2; ++k) dst[m][k] = *(const PG8_LAS bf16x8*)(lds + PG8_SA(b, h) + aoff + m * 2048 + k * 1024); } while (0)
; #define PG8_LDB(dst, b, h) do { _Pragma("unroll") for (int n = 0; n < 2; ++n) _Pragma("unroll") for (int k = 0; k < 2; ++k) dst[n][k] = *(const PG8_LAS bf16x8*)(lds + PG8_SB(b, h) + boff + n * 2048 + k * 1024); } while (0)
; template <class Epi, class Sched, bool ALIGN_EPI = false, bool SP2 = false>
; __device__ __forceinline__ void gemm_phase(PG8_LAS unsigned char* lds, const Gemm g, const Sched& S, const Epi& E) {
;     ...
;         for (int t = 0; t < nt; t += 2) {
;             const bool last = (t == nt - 2);
;             const char* a1 = cA + (size_t)(t + 1) * kstepA;
;             const char* a2 = last ? nA : cA + (size_t)(t + 2) * kstepA; const char* b2 = last ? nB : cB + (size_t)(t + 2) * kstep;
;             const char* a3 = a2 + kstepA; const char* b3 = b2 + kstep;
;             if (last && has_next) S.a_ready(nxt);
;             if constexpr (SP2) {
;             PG8_LDB(B0, 0, 0); PG8_LDB(B1, 0, 1); PG8_SCHED; PG8_LDA(At, 0, 0); PG8_STAGE(PG8_SA(1, 1), a1 + hstepA, voffA);
;             PG8_WAIT_V(8); PG8_WAIT_L(0); PG8_BAR; PG8_MMA(0, 0, At, B0); PG8_MMA(0, 1, At, B1); PG8_BAR; PG8_SCHED;
;             PG8_LDA(At, 0, 1); PG8_STAGE(PG8_SB(0, 0), b2, voffB); PG8_STAGE(PG8_SB(0, 1), b2 + hstepB, voffB); PG8_STAGE(PG8_SA(0, 0), a2, voffA);
;             PG8_WAIT_V(8); PG8_WAIT_L(0); PG8_BAR; PG8_MMA(1, 0, At, B0); PG8_MMA(1, 1, At, B1); PG8_BAR; PG8_SCHED;
;             PG8_LDB(B0, 1, 0); PG8_LDB(B1, 1, 1); PG8_SCHED; PG8_LDA(At, 1, 0); PG8_STAGE(PG8_SA(0, 1), a2 + hstepA, voffA);
;             PG8_WAIT_V(8); PG8_WAIT_L(0); PG8_BAR; PG8_MMA(0, 0, At, B0); PG8_MMA(0, 1, At, B1); PG8_BAR; PG8_SCHED;
;             PG8_LDA(At, 1, 1); PG8_STAGE(PG8_SB(1, 0), b3, voffB); PG8_STAGE(PG8_SB(1, 1), b3 + hstepB, voffB); PG8_STAGE(PG8_SA(1, 0), a3, voffA);
;             PG8_WAIT_V(8); PG8_WAIT_L(0); PG8_BAR; PG8_MMA(1, 0, At, B0); PG8_MMA(1, 1, At, B1); PG8_BAR; PG8_SCHED;
	s_add_i32 s22, s41, s24
	v_lshl_add_u64 v[146:147], v[146:147], 0, s[78:79]
	s_mov_b32 m0, s22
	ds_read_b128 v[180:183], v151 offset:49152
	ds_read_b128 v[184:187], v151 offset:50176
	ds_read_b128 v[188:191], v151 offset:51200
	ds_read_b128 v[206:209], v151 offset:52224
	ds_read_b128 v[210:213], v151 offset:53248
	ds_read_b128 v[214:217], v151 offset:54272
	ds_read_b128 v[218:221], v151 offset:55296
	ds_read_b128 v[222:225], v151 offset:56320
	global_load_lds_dwordx4 v[146:147], off
	s_add_i32 m0, s22, 0x2000
	s_add_u32 s20, s20, 0x40080
	v_lshl_add_u64 v[146:147], v[192:193], 0, s[78:79]
	s_addc_u32 s21, s21, 0
	s_add_i32 s22, s42, s24
	global_load_lds_dwordx4 v[146:147], off
	v_lshl_add_u64 v[146:147], s[20:21], 0, v[134:135]
	s_mov_b32 m0, s22
	s_nop 0
	global_load_lds_dwordx4 v[146:147], off
	v_lshl_add_u64 v[146:147], s[20:21], 0, v[130:131]
	s_add_i32 m0, s22, 0x2000
	s_nop 0
	global_load_lds_dwordx4 v[146:147], off
	v_lshl_add_u64 v[146:147], s[18:19], 0, v[136:137]
	s_mov_b32 m0, s29
	s_nop 0
	global_load_lds_dwordx4 v[146:147], off
	v_lshl_add_u64 v[146:147], s[18:19], 0, v[132:133]
	s_mov_b32 m0, s30
	s_nop 0
	global_load_lds_dwordx4 v[146:147], off
	s_waitcnt vmcnt(8)
	s_waitcnt lgkmcnt(0)
	s_barrier
	s_setprio 1
	s_waitcnt lgkmcnt(0)
	v_mfma_f32_16x16x32_bf16 v[62:65], v[142:145], v[180:183], v[62:65]
	v_mfma_f32_16x16x32_bf16 v[58:61], v[156:159], v[180:183], v[58:61]
	v_mfma_f32_16x16x32_bf16 v[46:49], v[142:145], v[188:191], v[46:49]
	v_mfma_f32_16x16x32_bf16 v[42:45], v[156:159], v[188:191], v[42:45]
	v_mfma_f32_16x16x32_bf16 v[30:33], v[142:145], v[210:213], v[30:33]
	v_mfma_f32_16x16x32_bf16 v[26:29], v[156:159], v[210:213], v[26:29]
	v_mfma_f32_16x16x32_bf16 v[14:17], v[142:145], v[218:221], v[14:17]
	v_mfma_f32_16x16x32_bf16 v[10:13], v[156:159], v[218:221], v[10:13]
	v_mfma_f32_16x16x32_bf16 v[62:65], v[152:155], v[184:187], v[62:65]
	v_mfma_f32_16x16x32_bf16 v[58:61], v[160:163], v[184:187], v[58:61]
	v_mfma_f32_16x16x32_bf16 v[46:49], v[152:155], v[206:209], v[46:49]
	v_mfma_f32_16x16x32_bf16 v[42:45], v[160:163], v[206:209], v[42:45]
	v_mfma_f32_16x16x32_bf16 v[30:33], v[152:155], v[214:217], v[30:33]
	v_mfma_f32_16x16x32_bf16 v[26:29], v[160:163], v[214:217], v[26:29]
	v_mfma_f32_16x16x32_bf16 v[14:17], v[152:155], v[222:225], v[14:17]
	v_mfma_f32_16x16x32_bf16 v[10:13], v[160:163], v[222:225], v[10:13]
	s_add_i32 s40, s40, 2
	s_setprio 0
	s_setprio 1
	v_mfma_f32_16x16x32_bf16 v[54:57], v[164:167], v[180:183], v[54:57]
	s_add_u32 s38, s38, 0x100
	v_mfma_f32_16x16x32_bf16 v[50:53], v[172:175], v[180:183], v[50:53]
	s_addc_u32 s39, s39, 0
	v_mfma_f32_16x16x32_bf16 v[38:41], v[164:167], v[188:191], v[38:41]
	s_add_u32 s6, s6, 0x400000
	v_mfma_f32_16x16x32_bf16 v[34:37], v[172:175], v[188:191], v[34:37]
	s_addc_u32 s7, s7, 0
	v_mfma_f32_16x16x32_bf16 v[22:25], v[164:167], v[210:213], v[22:25]
	s_add_u32 s18, s6, 0x1fc000
	v_mfma_f32_16x16x32_bf16 v[18:21], v[172:175], v[210:213], v[18:21]
	s_addc_u32 s19, s7, 0
	v_mfma_f32_16x16x32_bf16 v[6:9], v[164:167], v[218:221], v[6:9]
	s_cmp_eq_u32 s40, 12
	v_mfma_f32_16x16x32_bf16 v[2:5], v[172:175], v[218:221], v[2:5]
	s_cselect_b32 s22, s36, s18
	v_mfma_f32_16x16x32_bf16 v[54:57], v[168:171], v[184:187], v[54:57]
	s_cselect_b32 s23, s13, s19
	v_mfma_f32_16x16x32_bf16 v[50:53], v[176:179], v[184:187], v[50:53]
	s_cselect_b32 s20, s37, s38
	v_mfma_f32_16x16x32_bf16 v[38:41], v[168:171], v[206:209], v[38:41]
	s_cselect_b32 s21, s11, s39
	v_mfma_f32_16x16x32_bf16 v[34:37], v[176:179], v[206:209], v[34:37]
	s_add_u32 s18, s22, 0x200000
	v_mfma_f32_16x16x32_bf16 v[22:25], v[168:171], v[214:217], v[22:25]
	s_addc_u32 s19, s23, 0
	v_mfma_f32_16x16x32_bf16 v[18:21], v[176:179], v[214:217], v[18:21]
	s_add_i32 s41, 0, 0x10000
	v_mfma_f32_16x16x32_bf16 v[6:9], v[168:171], v[222:225], v[6:9]
	s_cmp_gt_u32 s40, 13
	v_mfma_f32_16x16x32_bf16 v[2:5], v[176:179], v[222:225], v[2:5]
	s_setprio 0
	s_barrier
	s_cbranch_scc0 .LBB0_333
	s_and_b64 vcc, exec, s[8:9]
	s_cbranch_vccz .LBB0_336
	s_barrier
